# v55 + per-chunk workgroup barrier of the scan units replaced by LDS progress flags (scan waves and helper waves hand chunks off without a rendezvous)
# speedup vs baseline: 1.0077x; 1.0077x over previous
.LBB0_702:
	s_cmp_lt_i32 s28, 8
	s_cselect_b64 s[4:5], -1, 0
	s_and_b64 s[0:1], s[4:5], s[0:1]
	v_writelane_b32 v255, s0, 15
	s_andn2_b64 vcc, exec, s[0:1]
	s_nop 0
	v_writelane_b32 v255, s1, 16
	s_cbranch_vccnz .LBB0_1054
	s_cmpk_lt_i32 s2, 0x80
	s_cselect_b64 s[0:1], -1, 0
	s_cmpk_lg_i32 s33, 0x100
	s_cselect_b64 s[4:5], -1, 0
	s_or_b64 s[0:1], s[0:1], s[4:5]
	s_cmp_lg_u32 s31, 2
	s_cselect_b64 s[4:5], -1, 0
	v_mov_b32_e32 v1, v0
	s_and_b64 s[0:1], s[0:1], s[4:5]
	s_andn2_b64 vcc, exec, s[0:1]
	v_readfirstlane_b32 s4, v1
	s_cbranch_vccnz .LBB0_836
	s_lshl_b32 s0, s2, 4
	s_and_b32 s0, s0, 0x70
	s_ashr_i32 s1, s2, 3
	s_add_i32 s5, s0, s1
	s_cmpk_eq_i32 s33, 0x100
	s_cselect_b64 s[0:1], -1, 0
	s_and_b64 s[6:7], s[0:1], exec
	s_cselect_b32 s10, s5, s2
	s_cmpk_gt_i32 s10, 0x7f
	s_cbranch_scc1 .LBB0_836
	s_lshl_b32 s5, s2, 2
	s_bfe_u32 s4, s4, 0x20006
	s_or_b32 s4, s5, s4
	s_add_i32 s6, s4, 0x3000
	s_and_b64 s[4:5], s[0:1], exec
	s_mov_b32 s11, 0x10200
	s_add_u32 s12, s92, 0x4100000
	s_addc_u32 s13, s93, 0
	s_add_u32 s16, s92, 0x8100000
	s_addc_u32 s17, s93, 0
	s_add_u32 s18, s92, 0xc100000
	s_addc_u32 s19, s93, 0
	s_add_u32 s14, s92, 0x26e00000
	s_addc_u32 s38, s93, 0
	s_add_u32 s39, s92, 0x22c00000
	s_addc_u32 s72, s93, 0
	s_and_b64 s[0:1], s[0:1], exec
	s_cselect_b32 s68, 0x80, s33
	s_mov_b32 s21, 0
	s_waitcnt vmcnt(0)
	v_mov_b32_e32 v115, 0
	s_movk_i32 s69, 0x500
	s_add_i32 s70, 0, 0x13000
	s_movk_i32 s71, 0x2600
	v_and_b32_e32 v250, 7, v0
	v_lshlrev_b32_e32 v250, 2, v250
	v_add_u32_e32 v250, 0x1b000, v250
	v_mov_b32_e32 v251, 0
	ds_write_b32 v250, v251
	s_branch .LBB0_707
.LBB0_706:
	s_waitcnt vmcnt(0)
	s_waitcnt lgkmcnt(0)
	s_barrier
	v_and_b32_e32 v250, 7, v0
	v_lshlrev_b32_e32 v250, 2, v250
	v_add_u32_e32 v250, 0x1b000, v250
	v_mov_b32_e32 v251, 0
	ds_write_b32 v250, v251
	s_add_i32 s10, s10, s68
	s_cmpk_lt_i32 s10, 0x80
	s_cbranch_scc0 .LBB0_836

.LBB0_721:
	s_and_b64 s[8:9], s[0:1], exec
	v_readlane_b32 s8, v255, 9
	v_and_b32_e32 v166, 63, v44
	v_readlane_b32 s9, v255, 10
	v_and_b32_e32 v26, 31, v44
	v_lshlrev_b32_e32 v27, 6, v44
	s_cselect_b32 s27, s72, s9
	s_cselect_b32 s26, s39, s8
	s_mov_b64 s[8:9], -1
	s_cmp_lt_i32 s20, 4
	v_lshl_add_u32 v118, v45, 4, 0
	v_lshl_or_b32 v164, s42, 6, v166
	v_and_b32_e32 v119, 0x600, v27
	v_and_b32_e32 v123, 0x100, v27
	v_and_b32_e32 v129, 0xc0, v27
	v_lshlrev_b32_e32 v116, 2, v26
	s_waitcnt lgkmcnt(0)
	s_barrier
	s_cbranch_scc1 .LBB0_831
	v_lshl_or_b32 v167, s42, 2, v165
	s_mul_i32 s8, s42, 0x2100
	v_mov_b32_e32 v121, s7
	v_or_b32_e32 v120, s6, v46
	v_mad_u64_u32 v[124:125], s[6:7], v167, s69, v[118:119]
	s_add_i32 s8, s8, 0
	s_ashr_i32 s23, s22, 31
	v_lshlrev_b32_e32 v26, 2, v44
	v_lshrrev_b32_e32 v125, 5, v164
	s_add_i32 s15, s8, 0x1b000
	v_and_b32_e32 v122, 28, v26
	v_lshlrev_b32_e32 v26, 11, v125
	s_lshl_b64 s[42:43], s[22:23], 2
	v_add3_u32 v27, s70, v26, v119
	s_add_u32 s42, s26, s42
	v_add3_u32 v168, v27, v123, v129
	s_addc_u32 s43, s27, s43
	v_mov_b32_e32 v117, v115
	v_add_u32_e32 v27, 0x100, v164
	v_lshl_add_u64 v[126:127], s[42:43], 0, v[116:117]
	v_lshrrev_b32_e32 v117, 5, v27
	v_lshlrev_b32_e32 v27, 11, v117
	s_ashr_i32 s37, s36, 31
	v_add3_u32 v26, 0, v26, v119
	s_lshl_b64 s[36:37], s[36:37], 2
	v_add3_u32 v173, v26, v123, v129
	v_add3_u32 v26, 0, v27, v119
	s_add_u32 s36, s40, s36
	v_add3_u32 v174, v26, v123, v129
	v_lshlrev_b32_e32 v232, 2, v44
	v_and_b32_e32 v232, 48, v232
	v_xor_b32_e32 v233, 16, v232
	v_xor_b32_e32 v234, 32, v232
	v_xor_b32_e32 v235, 48, v232
	v_add_u32_e32 v224, v173, v232
	v_add_u32_e32 v225, v173, v233
	v_add_u32_e32 v226, v173, v234
	v_add_u32_e32 v227, v173, v235
	v_add_u32_e32 v228, 0x8000, v224
	v_add_u32_e32 v229, 0x8000, v225
	v_add_u32_e32 v230, 0x8000, v226
	v_add_u32_e32 v231, 0x8000, v227
	v_lshlrev_b32_e32 v26, 3, v44
	s_addc_u32 s37, s41, s37
	v_lshrrev_b32_e32 v171, 3, v166
	v_and_b32_e32 v128, 56, v26
	s_lshl_b64 s[40:41], s[22:23], 1
	v_add3_u32 v28, s70, v27, v119
	v_mul_u32_u24_e32 v26, 0x84, v128
	v_lshlrev_b32_e32 v27, 2, v171
	s_add_u32 s40, s16, s40
	v_lshl_add_u32 v176, v122, 2, s15
	v_add3_u32 v182, s15, v26, v27
	s_addc_u32 s41, s17, s41
	s_lshl_b32 s15, s20, 6
	v_or_b32_e32 v26, s15, v166
	s_addk_i32 s15, 0xff00
	v_add3_u32 v169, v28, v123, v129
	v_lshlrev_b32_e32 v28, 7, v167
	v_lshlrev_b32_e32 v114, 1, v122
	v_lshrrev_b32_e32 v183, 5, v26
	v_or_b32_e32 v26, s15, v166
	v_cmp_gt_u32_e64 s[6:7], 8, v45
	s_mov_b32 s45, 0
	v_cmp_eq_u32_e64 s[8:9], 0, v45
	v_add_u32_e32 v170, 64, v167
	v_add_u32_e32 v172, 0x50, v167
	v_add_u32_e32 v175, 0x60, v167
	v_add_u32_e32 v177, 0x70, v167
	v_mul_u32_u24_e32 v178, 0x84, v171
	v_or_b32_e32 v179, 8, v171
	v_or_b32_e32 v180, 16, v171
	v_or_b32_e32 v181, 24, v171
	v_lshl_add_u64 v[130:131], s[40:41], 0, v[114:115]
	v_lshrrev_b32_e32 v184, 5, v26
	v_lshl_or_b32 v185, s20, 2, v165
	s_mov_b32 s23, -4
	v_add_u32_e32 v186, v118, v28
	s_mov_b32 s49, s11
	s_mov_b32 s46, 0
	v_and_b32_e32 v246, 3, v166
	v_lshlrev_b32_e32 v246, 2, v246
	v_add_u32_e32 v246, 0x1b000, v246
	s_lshl_b32 s64, s20, 2
	s_add_i32 s64, s64, 0x1b000
	v_mov_b32_e32 v247, s64
	s_branch .LBB0_726

.LBB0_725:
	s_waitcnt lgkmcnt(0)
	s_add_i32 s64, s46, 4
	v_mov_b32_e32 v248, s64
	ds_write_b32 v247, v248
.Lhflag_4:
	ds_read_b32 v249, v246
	s_waitcnt lgkmcnt(0)
	v_cmp_gt_u32_e32 vcc, s64, v249
	s_nop 0
	s_cbranch_vccz .Lhflag_go_4
	s_sleep 6
	s_branch .Lhflag_4
.Lhflag_go_4:
	s_add_i32 s46, s46, 4
	s_add_i32 s45, s45, 64
	s_cmpk_lt_u32 s23, 0x1fc
	s_mov_b32 s49, s20
	s_cbranch_scc0 .LBB0_830

.LBB0_752:
	s_waitcnt lgkmcnt(0)
	s_add_i32 s64, s46, 1
	v_mov_b32_e32 v248, s64
	ds_write_b32 v247, v248

.Lhflag_go_1:
	s_min_u32 s15, s23, 0x1fa
	s_and_b64 vcc, exec, s[4:5]
	s_mov_b64 s[40:41], -1
	s_cbranch_vccnz .LBB0_754
	v_lshl_add_u32 v10, s15, 4, v167
	v_sub_u32_e32 v106, 0x1faf, v10
	s_mov_b64 s[40:41], 0

.LBB0_778:
	s_waitcnt lgkmcnt(0)
	s_add_i32 s64, s46, 2
	v_mov_b32_e32 v248, s64
	ds_write_b32 v247, v248

.Lhflag_go_2:
	s_min_u32 s15, s23, 0x1f9
	s_and_b64 vcc, exec, s[4:5]
	s_mov_b64 s[52:53], -1
	s_cbranch_vccnz .LBB0_780
	v_lshl_add_u32 v18, s15, 4, v167
	v_sub_u32_e32 v106, 0x1f9f, v18
	s_mov_b64 s[52:53], 0

.LBB0_805:
	s_waitcnt lgkmcnt(0)
	s_add_i32 s64, s46, 3
	v_mov_b32_e32 v248, s64
	ds_write_b32 v247, v248

.Lhflag_go_3:
	s_min_u32 s15, s23, 0x1f8
	s_and_b64 vcc, exec, s[4:5]
	s_mov_b64 s[42:43], -1
	s_cbranch_vccnz .LBB0_807
	v_lshl_add_u32 v90, s15, 4, v167
	v_sub_u32_e32 v106, 0x1f8f, v90
	s_mov_b64 s[42:43], 0

.LBB0_831:
	v_readlane_b32 s28, v255, 5
	s_and_b64 vcc, exec, s[8:9]
	v_readlane_b32 s31, v255, 8
	v_readlane_b32 s29, v255, 6
	v_readlane_b32 s30, v255, 7
	s_cbranch_vccz .LBB0_834
	s_bfe_u32 s4, s44, 0x20006
	s_lshl_b32 s5, s4, 5
	s_add_i32 s5, s5, 0
	s_mul_i32 s6, s4, 0x1e0
	s_lshl_b32 s4, s4, 9
	v_lshl_add_u32 v110, v165, 2, s5
	s_add_i32 s5, s5, s6
	v_lshlrev_b32_e32 v2, 2, v166
	s_add_i32 s4, s4, 0
	v_add_u32_e32 v111, s5, v2
	s_add_i32 s4, s4, 0x13000
	s_waitcnt vmcnt(8)
	v_mov_b32_e32 v24, 0
	v_add_u32_e32 v112, 0xb000, v111
	v_add_u32_e32 v113, s4, v2
	s_mov_b32 s4, -4
	v_mov_b32_e32 v25, v24
	v_mov_b32_e32 v22, v24
	v_mov_b32_e32 v23, v24
	v_mov_b32_e32 v6, v24
	v_mov_b32_e32 v7, v24
	v_mov_b32_e32 v8, v24
	v_mov_b32_e32 v9, v24
	v_and_b32_e32 v246, 3, v166
	v_lshlrev_b32_e32 v246, 2, v246
	v_add_u32_e32 v246, 0x1b010, v246
	s_lshl_b32 s64, s20, 2
	s_add_i32 s64, s64, 0x1b000
	v_mov_b32_e32 v247, s64
	s_lshr_b32 s58, s10, 2
	s_lshl_b32 s58, s58, 8
	s_add_u32 s56, s92, s58
	s_addc_u32 s57, s93, 0
	s_add_u32 s56, s56, 0x37800000
	s_addc_u32 s57, s57, 0
	s_movk_i32 s58, 0x2000
	s_mov_b32 s59, 0
	s_bitcmp1_b32 s10, 1
	s_cbranch_scc0 .Lw_fwd
	s_add_u32 s56, s56, 0x7ffe000
	s_addc_u32 s57, s57, 0
	s_mov_b32 s58, 0xffffe000
	s_mov_b32 s59, -1

.LBB0_833:
	ds_read_b128 v[34:37], v118
	global_load_dwordx4 v[208:211], v118, s[56:57]
	s_add_u32 s56, s56, s58
	s_addc_u32 s57, s57, s59
	ds_read_b128 v[42:45], v118 offset:512
	ds_read_b128 v[54:57], v118 offset:768
	ds_read_b128 v[58:61], v118 offset:1024
	s_waitcnt lgkmcnt(3)
	v_pk_mul_f32 v[64:65], v[22:23], v[36:37]
	v_pk_mul_f32 v[36:37], v[8:9], v[36:37]
	v_pk_fma_f32 v[64:65], v[24:25], v[34:35], v[64:65]
	v_pk_fma_f32 v[34:35], v[6:7], v[34:35], v[36:37]
	v_add_f32_e32 v36, v64, v65
	v_add_f32_e32 v34, v34, v35
	v_add_u32_e32 v121, 0xa000, v110
	v_add_f32_dpp v36, v36, v36 row_ror:8 row_mask:0xf bank_mask:0xf bound_ctrl:1
	v_add_f32_dpp v34, v34, v34 row_ror:8 row_mask:0xf bank_mask:0xf bound_ctrl:1
	ds_read2_b32 v[62:63], v121 offset1:4
	ds_read_b128 v[66:69], v118 offset:1280
	global_load_dwordx4 v[212:215], v118, s[56:57]
	s_add_u32 s56, s56, s58
	s_addc_u32 s57, s57, s59
	ds_read_b128 v[90:93], v118 offset:1792
	ds_read_b128 v[94:97], v118 offset:2048
	ds_read_b128 v[102:105], v118 offset:2304
	ds_read2_b32 v[98:99], v121 offset0:32 offset1:36
	ds_read_b128 v[78:81], v118 offset:2560
	global_load_dwordx4 v[216:219], v118, s[56:57]
	s_add_u32 s56, s56, s58
	s_addc_u32 s57, s57, s59
	ds_read_b128 v[46:49], v118 offset:3072
	ds_read_b128 v[50:53], v118 offset:3328
	ds_read_b128 v[10:13], v118 offset:3584
	ds_read2_b32 v[84:85], v121 offset0:64 offset1:68
	ds_read_b128 v[70:73], v118 offset:3840
	global_load_dwordx4 v[220:223], v118, s[56:57]
	s_add_u32 s56, s56, s58
	s_addc_u32 s57, s57, s59
	ds_read_b128 v[26:29], v118 offset:4352
	ds_read_b128 v[30:33], v118 offset:4608
	ds_read_b128 v[2:5], v118 offset:4864
	ds_read2_b32 v[82:83], v121 offset0:96 offset1:100
	v_add_f32_dpp v36, v36, v36 row_ror:4 row_mask:0xf bank_mask:0xf bound_ctrl:1
	v_add_f32_dpp v34, v34, v34 row_ror:4 row_mask:0xf bank_mask:0xf bound_ctrl:1
	s_waitcnt lgkmcnt(12)
	v_mov_b32_e32 v64, v63
	v_add_f32_dpp v36, v36, v36 row_ror:2 row_mask:0xf bank_mask:0xf bound_ctrl:1
	v_add_f32_dpp v34, v34, v34 row_ror:2 row_mask:0xf bank_mask:0xf bound_ctrl:1
	v_add_u32_e32 v117, 0xa400, v110
	v_add_f32_dpp v36, v36, v36 row_ror:1 row_mask:0xf bank_mask:0xf bound_ctrl:1
	v_pk_mul_f32 v[74:75], v[42:43], v[36:37] op_sel_hi:[1,0]
	v_add_f32_dpp v34, v34, v34 row_ror:1 row_mask:0xf bank_mask:0xf bound_ctrl:1
	v_pk_fma_f32 v[74:75], v[54:55], v[62:63], v[74:75] op_sel_hi:[1,0,1]
	v_add_u32_e32 v120, 0xa800, v110
	s_waitcnt vmcnt(7)
	v_pk_fma_f32 v[106:107], v[24:25], v[192:193], v[74:75]
	v_pk_mul_f32 v[24:25], v[44:45], v[36:37] op_sel_hi:[1,0]
	v_add_u32_e32 v114, 0xac00, v110
	v_pk_fma_f32 v[24:25], v[56:57], v[62:63], v[24:25] op_sel_hi:[1,0,1]
	s_add_i32 s4, s4, 4
	v_pk_fma_f32 v[36:37], v[22:23], v[194:195], v[24:25]
	v_pk_mul_f32 v[22:23], v[42:43], v[34:35] op_sel_hi:[1,0]
	s_cmpk_gt_u32 s4, 0x1fb
	v_pk_fma_f32 v[22:23], v[54:55], v[64:65], v[22:23] op_sel_hi:[1,0,1]
	s_nop 0
	v_pk_fma_f32 v[42:43], v[6:7], v[192:193], v[22:23]
	v_pk_mul_f32 v[6:7], v[44:45], v[34:35] op_sel_hi:[1,0]
	v_pk_mul_f32 v[44:45], v[68:69], v[36:37]
	v_pk_fma_f32 v[6:7], v[56:57], v[64:65], v[6:7] op_sel_hi:[1,0,1]
	v_pk_fma_f32 v[44:45], v[66:67], v[106:107], v[44:45]
	v_pk_fma_f32 v[34:35], v[8:9], v[194:195], v[6:7]
	v_add_f32_e32 v44, v44, v45
	v_pk_mul_f32 v[54:55], v[68:69], v[34:35]
	v_pk_mul_f32 v[6:7], v[60:61], v[36:37]
	v_pk_fma_f32 v[54:55], v[66:67], v[42:43], v[54:55]
	v_add_f32_dpp v44, v44, v44 row_ror:8 row_mask:0xf bank_mask:0xf bound_ctrl:1
	v_add_f32_e32 v45, v54, v55
	v_pk_mul_f32 v[8:9], v[60:61], v[34:35]
	v_add_f32_dpp v44, v44, v44 row_ror:4 row_mask:0xf bank_mask:0xf bound_ctrl:1
	v_add_f32_dpp v45, v45, v45 row_ror:8 row_mask:0xf bank_mask:0xf bound_ctrl:1
	v_pk_fma_f32 v[6:7], v[58:59], v[106:107], v[6:7]
	v_add_f32_dpp v44, v44, v44 row_ror:2 row_mask:0xf bank_mask:0xf bound_ctrl:1
	v_add_f32_dpp v45, v45, v45 row_ror:4 row_mask:0xf bank_mask:0xf bound_ctrl:1
	v_pk_fma_f32 v[8:9], v[58:59], v[42:43], v[8:9]
	v_add_f32_dpp v44, v44, v44 row_ror:1 row_mask:0xf bank_mask:0xf bound_ctrl:1
	v_add_f32_dpp v45, v45, v45 row_ror:2 row_mask:0xf bank_mask:0xf bound_ctrl:1
	v_pk_mul_f32 v[58:59], v[90:91], v[44:45] op_sel_hi:[1,0]
	s_waitcnt lgkmcnt(10)
	v_mov_b32_e32 v56, v99
	v_add_f32_dpp v54, v45, v45 row_ror:1 row_mask:0xf bank_mask:0xf bound_ctrl:1
	v_pk_mul_f32 v[44:45], v[92:93], v[44:45] op_sel_hi:[1,0]
	v_pk_fma_f32 v[58:59], v[94:95], v[98:99], v[58:59] op_sel_hi:[1,0,1]
	v_pk_fma_f32 v[44:45], v[96:97], v[98:99], v[44:45] op_sel_hi:[1,0,1]
	s_waitcnt vmcnt(6)
	v_pk_fma_f32 v[106:107], v[196:197], v[106:107], v[58:59]
	v_pk_fma_f32 v[108:109], v[198:199], v[36:37], v[44:45]
	v_pk_mul_f32 v[36:37], v[90:91], v[54:55] op_sel_hi:[1,0]
	s_waitcnt lgkmcnt(9)
	v_pk_mul_f32 v[90:91], v[80:81], v[108:109]
	v_pk_fma_f32 v[36:37], v[94:95], v[56:57], v[36:37] op_sel_hi:[1,0,1]
	v_pk_fma_f32 v[90:91], v[78:79], v[106:107], v[90:91]
	v_pk_fma_f32 v[86:87], v[196:197], v[42:43], v[36:37]
	v_pk_mul_f32 v[36:37], v[92:93], v[54:55] op_sel_hi:[1,0]
	v_add_f32_e32 v6, v6, v7
	v_pk_fma_f32 v[36:37], v[96:97], v[56:57], v[36:37] op_sel_hi:[1,0,1]
	v_add_f32_e32 v7, v8, v9
	v_pk_fma_f32 v[88:89], v[198:199], v[34:35], v[36:37]
	v_pk_mul_f32 v[34:35], v[104:105], v[108:109]
	v_pk_mul_f32 v[80:81], v[80:81], v[88:89]
	v_pk_mul_f32 v[36:37], v[104:105], v[88:89]
	v_pk_fma_f32 v[78:79], v[78:79], v[86:87], v[80:81]
	v_add_f32_e32 v80, v90, v91
	v_add_f32_e32 v78, v78, v79
	s_waitcnt lgkmcnt(5)
	v_mov_b32_e32 v90, v85
	v_add_f32_dpp v80, v80, v80 row_ror:8 row_mask:0xf bank_mask:0xf bound_ctrl:1
	v_add_f32_dpp v78, v78, v78 row_ror:8 row_mask:0xf bank_mask:0xf bound_ctrl:1
	v_pk_fma_f32 v[36:37], v[102:103], v[86:87], v[36:37]
	v_add_f32_dpp v80, v80, v80 row_ror:4 row_mask:0xf bank_mask:0xf bound_ctrl:1
	v_add_f32_dpp v78, v78, v78 row_ror:4 row_mask:0xf bank_mask:0xf bound_ctrl:1
	v_pk_fma_f32 v[34:35], v[102:103], v[106:107], v[34:35]
	v_add_f32_dpp v80, v80, v80 row_ror:2 row_mask:0xf bank_mask:0xf bound_ctrl:1
	v_add_f32_dpp v78, v78, v78 row_ror:2 row_mask:0xf bank_mask:0xf bound_ctrl:1
	ds_write2st64_b32 v111, v6, v7 offset0:176 offset1:177
	v_add_f32_dpp v80, v80, v80 row_ror:1 row_mask:0xf bank_mask:0xf bound_ctrl:1
	v_add_f32_dpp v78, v78, v78 row_ror:1 row_mask:0xf bank_mask:0xf bound_ctrl:1
	v_pk_mul_f32 v[92:93], v[46:47], v[80:81] op_sel_hi:[1,0]
	v_pk_mul_f32 v[46:47], v[46:47], v[78:79] op_sel_hi:[1,0]
	v_pk_fma_f32 v[92:93], v[50:51], v[84:85], v[92:93] op_sel_hi:[1,0,1]
	v_pk_mul_f32 v[80:81], v[48:49], v[80:81] op_sel_hi:[1,0]
	v_pk_fma_f32 v[46:47], v[50:51], v[90:91], v[46:47] op_sel_hi:[1,0,1]
	s_waitcnt vmcnt(5)
	v_pk_fma_f32 v[94:95], v[200:201], v[106:107], v[92:93]
	v_pk_fma_f32 v[80:81], v[52:53], v[84:85], v[80:81] op_sel_hi:[1,0,1]
	v_pk_fma_f32 v[84:85], v[200:201], v[86:87], v[46:47]
	v_pk_mul_f32 v[18:19], v[48:49], v[78:79] op_sel_hi:[1,0]
	v_pk_fma_f32 v[80:81], v[202:203], v[108:109], v[80:81]
	v_pk_fma_f32 v[18:19], v[52:53], v[90:91], v[18:19] op_sel_hi:[1,0,1]
	s_waitcnt lgkmcnt(5)
	v_pk_mul_f32 v[86:87], v[72:73], v[80:81]
	v_pk_fma_f32 v[78:79], v[202:203], v[88:89], v[18:19]
	v_pk_fma_f32 v[86:87], v[70:71], v[94:95], v[86:87]
	v_pk_mul_f32 v[72:73], v[72:73], v[78:79]
	v_pk_mul_f32 v[18:19], v[12:13], v[80:81]
	v_pk_fma_f32 v[70:71], v[70:71], v[84:85], v[72:73]
	v_add_f32_e32 v72, v86, v87
	v_add_f32_e32 v70, v70, v71
	s_waitcnt lgkmcnt(1)
	v_mov_b32_e32 v86, v83
	v_add_f32_dpp v72, v72, v72 row_ror:8 row_mask:0xf bank_mask:0xf bound_ctrl:1
	v_add_f32_dpp v70, v70, v70 row_ror:8 row_mask:0xf bank_mask:0xf bound_ctrl:1
	v_pk_mul_f32 v[12:13], v[12:13], v[78:79]
	v_add_f32_dpp v72, v72, v72 row_ror:4 row_mask:0xf bank_mask:0xf bound_ctrl:1
	v_add_f32_dpp v70, v70, v70 row_ror:4 row_mask:0xf bank_mask:0xf bound_ctrl:1
	v_add_f32_e32 v34, v34, v35
	v_add_f32_dpp v72, v72, v72 row_ror:2 row_mask:0xf bank_mask:0xf bound_ctrl:1
	v_add_f32_dpp v70, v70, v70 row_ror:2 row_mask:0xf bank_mask:0xf bound_ctrl:1
	v_add_f32_e32 v35, v36, v37
	v_add_f32_dpp v72, v72, v72 row_ror:1 row_mask:0xf bank_mask:0xf bound_ctrl:1
	v_add_f32_dpp v70, v70, v70 row_ror:1 row_mask:0xf bank_mask:0xf bound_ctrl:1
	v_pk_mul_f32 v[88:89], v[26:27], v[72:73] op_sel_hi:[1,0]
	v_pk_mul_f32 v[26:27], v[26:27], v[70:71] op_sel_hi:[1,0]
	v_pk_fma_f32 v[88:89], v[30:31], v[82:83], v[88:89] op_sel_hi:[1,0,1]
	v_pk_fma_f32 v[26:27], v[30:31], v[86:87], v[26:27] op_sel_hi:[1,0,1]
	s_waitcnt vmcnt(4)
	v_pk_fma_f32 v[106:107], v[204:205], v[94:95], v[88:89]
	v_pk_mul_f32 v[72:73], v[28:29], v[72:73] op_sel_hi:[1,0]
	v_pk_fma_f32 v[26:27], v[204:205], v[84:85], v[26:27]
	v_pk_mul_f32 v[14:15], v[28:29], v[70:71] op_sel_hi:[1,0]
	v_pk_fma_f32 v[72:73], v[32:33], v[82:83], v[72:73] op_sel_hi:[1,0,1]
	v_pk_fma_f32 v[14:15], v[32:33], v[86:87], v[14:15] op_sel_hi:[1,0,1]
	v_pk_fma_f32 v[72:73], v[206:207], v[80:81], v[72:73]
	v_pk_fma_f32 v[28:29], v[206:207], v[78:79], v[14:15]
	v_pk_fma_f32 v[18:19], v[10:11], v[94:95], v[18:19]
	v_pk_fma_f32 v[10:11], v[10:11], v[84:85], v[12:13]
	v_pk_mul_f32 v[14:15], v[4:5], v[72:73]
	v_pk_mul_f32 v[4:5], v[4:5], v[28:29]
	ds_read_b128 v[74:77], v118 offset:5120
	global_load_dwordx4 v[192:195], v118, s[56:57]
	s_add_u32 s56, s56, s58
	s_addc_u32 s57, s57, s59
	ds_read_b128 v[38:41], v118 offset:5632
	ds_read_b128 v[62:65], v118 offset:5888
	ds_read_b128 v[6:9], v118 offset:6144
	ds_read2_b32 v[100:101], v121 offset0:128 offset1:132
	ds_write2st64_b32 v111, v34, v35 offset0:184 offset1:185
	v_add_f32_e32 v12, v18, v19
	v_add_f32_e32 v10, v10, v11
	v_pk_fma_f32 v[14:15], v[2:3], v[106:107], v[14:15]
	v_pk_fma_f32 v[2:3], v[2:3], v[26:27], v[4:5]
	ds_read_b128 v[66:69], v118 offset:6400
	global_load_dwordx4 v[196:199], v118, s[56:57]
	s_add_u32 s56, s56, s58
	s_addc_u32 s57, s57, s59
	ds_read_b128 v[54:57], v118 offset:6912
	ds_read_b128 v[58:61], v118 offset:7168
	ds_read_b128 v[34:37], v118 offset:7424
	ds_read2_b32 v[98:99], v121 offset0:160 offset1:164
	ds_write2st64_b32 v111, v12, v10 offset0:192 offset1:193
	v_add_f32_e32 v4, v14, v15
	v_add_f32_e32 v2, v2, v3
	ds_read_b128 v[90:93], v118 offset:7680
	global_load_dwordx4 v[200:203], v118, s[56:57]
	s_add_u32 s56, s56, s58
	s_addc_u32 s57, s57, s59
	ds_read_b128 v[46:49], v118 offset:8192
	ds_read_b128 v[50:53], v118 offset:8448
	ds_read_b128 v[10:13], v118 offset:8704
	ds_read2_b32 v[102:103], v121 offset0:192 offset1:196
	ds_write2st64_b32 v111, v4, v2 offset0:200 offset1:201
	s_waitcnt lgkmcnt(12)
	v_pk_mul_f32 v[2:3], v[76:77], v[72:73]
	v_pk_mul_f32 v[4:5], v[76:77], v[28:29]
	v_pk_fma_f32 v[2:3], v[74:75], v[106:107], v[2:3]
	v_pk_fma_f32 v[4:5], v[74:75], v[26:27], v[4:5]
	v_add_f32_e32 v2, v2, v3
	v_add_f32_e32 v3, v4, v5
	v_mov_b32_e32 v70, v101
	v_add_f32_dpp v2, v2, v2 row_ror:8 row_mask:0xf bank_mask:0xf bound_ctrl:1
	v_add_f32_dpp v3, v3, v3 row_ror:8 row_mask:0xf bank_mask:0xf bound_ctrl:1
	ds_read_b128 v[94:97], v118 offset:8960
	global_load_dwordx4 v[204:207], v118, s[56:57]
	s_add_u32 s56, s56, s58
	s_addc_u32 s57, s57, s59
	ds_read_b128 v[82:85], v118 offset:9472
	ds_read_b128 v[86:89], v118 offset:9728
	ds_read_b128 v[14:17], v118 offset:9984
	ds_read2_b32 v[104:105], v121 offset0:224 offset1:228
	v_add_f32_dpp v2, v2, v2 row_ror:4 row_mask:0xf bank_mask:0xf bound_ctrl:1
	v_add_f32_dpp v3, v3, v3 row_ror:4 row_mask:0xf bank_mask:0xf bound_ctrl:1
	s_nop 0
	v_add_f32_dpp v2, v2, v2 row_ror:2 row_mask:0xf bank_mask:0xf bound_ctrl:1
	v_add_f32_dpp v3, v3, v3 row_ror:2 row_mask:0xf bank_mask:0xf bound_ctrl:1
	s_nop 0
	v_add_f32_dpp v2, v2, v2 row_ror:1 row_mask:0xf bank_mask:0xf bound_ctrl:1
	v_add_f32_dpp v4, v3, v3 row_ror:1 row_mask:0xf bank_mask:0xf bound_ctrl:1
	v_pk_mul_f32 v[74:75], v[38:39], v[2:3] op_sel_hi:[1,0]
	v_pk_mul_f32 v[2:3], v[40:41], v[2:3] op_sel_hi:[1,0]
	v_pk_fma_f32 v[74:75], v[62:63], v[100:101], v[74:75] op_sel_hi:[1,0,1]
	v_pk_fma_f32 v[2:3], v[64:65], v[100:101], v[2:3] op_sel_hi:[1,0,1]
	s_waitcnt vmcnt(7)
	v_pk_fma_f32 v[74:75], v[208:209], v[106:107], v[74:75]
	v_pk_fma_f32 v[72:73], v[210:211], v[72:73], v[2:3]
	v_pk_mul_f32 v[2:3], v[38:39], v[4:5] op_sel_hi:[1,0]
	s_nop 0
	v_pk_fma_f32 v[2:3], v[62:63], v[70:71], v[2:3] op_sel_hi:[1,0,1]
	s_nop 0
	v_pk_fma_f32 v[62:63], v[208:209], v[26:27], v[2:3]
	v_pk_mul_f32 v[2:3], v[40:41], v[4:5] op_sel_hi:[1,0]
	s_nop 0
	v_pk_fma_f32 v[2:3], v[64:65], v[70:71], v[2:3] op_sel_hi:[1,0,1]
	s_waitcnt lgkmcnt(12)
	v_pk_mul_f32 v[70:71], v[68:69], v[72:73]
	v_pk_fma_f32 v[64:65], v[210:211], v[28:29], v[2:3]
	v_pk_fma_f32 v[70:71], v[66:67], v[74:75], v[70:71]
	v_pk_mul_f32 v[68:69], v[68:69], v[64:65]
	v_pk_mul_f32 v[2:3], v[8:9], v[72:73]
	v_pk_fma_f32 v[66:67], v[66:67], v[62:63], v[68:69]
	v_add_f32_e32 v68, v70, v71
	v_add_f32_e32 v66, v66, v67
	v_mov_b32_e32 v70, v99
	v_add_f32_dpp v68, v68, v68 row_ror:8 row_mask:0xf bank_mask:0xf bound_ctrl:1
	v_add_f32_dpp v66, v66, v66 row_ror:8 row_mask:0xf bank_mask:0xf bound_ctrl:1
	v_pk_mul_f32 v[4:5], v[8:9], v[64:65]
	v_add_f32_dpp v68, v68, v68 row_ror:4 row_mask:0xf bank_mask:0xf bound_ctrl:1
	v_add_f32_dpp v66, v66, v66 row_ror:4 row_mask:0xf bank_mask:0xf bound_ctrl:1
	v_pk_fma_f32 v[2:3], v[6:7], v[74:75], v[2:3]
	v_add_f32_dpp v68, v68, v68 row_ror:2 row_mask:0xf bank_mask:0xf bound_ctrl:1
	v_add_f32_dpp v66, v66, v66 row_ror:2 row_mask:0xf bank_mask:0xf bound_ctrl:1
	v_pk_fma_f32 v[4:5], v[6:7], v[62:63], v[4:5]
	v_add_f32_dpp v68, v68, v68 row_ror:1 row_mask:0xf bank_mask:0xf bound_ctrl:1
	v_add_f32_dpp v66, v66, v66 row_ror:1 row_mask:0xf bank_mask:0xf bound_ctrl:1
	v_pk_mul_f32 v[76:77], v[54:55], v[68:69] op_sel_hi:[1,0]
	v_pk_mul_f32 v[54:55], v[54:55], v[66:67] op_sel_hi:[1,0]
	v_pk_fma_f32 v[76:77], v[58:59], v[98:99], v[76:77] op_sel_hi:[1,0,1]
	v_pk_fma_f32 v[54:55], v[58:59], v[70:71], v[54:55] op_sel_hi:[1,0,1]
	s_waitcnt vmcnt(6)
	v_pk_fma_f32 v[106:107], v[212:213], v[74:75], v[76:77]
	v_pk_mul_f32 v[68:69], v[56:57], v[68:69] op_sel_hi:[1,0]
	v_pk_fma_f32 v[42:43], v[212:213], v[62:63], v[54:55]
	v_pk_mul_f32 v[54:55], v[56:57], v[66:67] op_sel_hi:[1,0]
	v_pk_fma_f32 v[68:69], v[60:61], v[98:99], v[68:69] op_sel_hi:[1,0,1]
	v_pk_fma_f32 v[54:55], v[60:61], v[70:71], v[54:55] op_sel_hi:[1,0,1]
	v_pk_fma_f32 v[108:109], v[214:215], v[72:73], v[68:69]
	v_pk_fma_f32 v[44:45], v[214:215], v[64:65], v[54:55]
	v_pk_mul_f32 v[54:55], v[36:37], v[108:109]
	v_pk_mul_f32 v[36:37], v[36:37], v[44:45]
	v_add_f32_e32 v2, v2, v3
	v_add_f32_e32 v3, v4, v5
	v_pk_fma_f32 v[54:55], v[34:35], v[106:107], v[54:55]
	v_pk_fma_f32 v[34:35], v[34:35], v[42:43], v[36:37]
	ds_write2st64_b32 v111, v2, v3 offset0:208 offset1:209
	v_add_f32_e32 v36, v54, v55
	v_add_f32_e32 v34, v34, v35
	ds_read_b128 v[38:41], v118 offset:10240
	global_load_dwordx4 v[208:211], v118, s[56:57]
	s_add_u32 s56, s56, s58
	s_addc_u32 s57, s57, s59
	ds_read_b128 v[22:25], v118 offset:10752
	ds_read_b128 v[26:29], v118 offset:11008
	ds_read_b128 v[2:5], v118 offset:11264
	ds_write2st64_b32 v111, v36, v34 offset0:216 offset1:217
	s_waitcnt lgkmcnt(12)
	v_pk_mul_f32 v[34:35], v[92:93], v[108:109]
	v_pk_mul_f32 v[36:37], v[92:93], v[44:45]
	v_pk_fma_f32 v[34:35], v[90:91], v[106:107], v[34:35]
	v_pk_fma_f32 v[36:37], v[90:91], v[42:43], v[36:37]
	v_add_f32_e32 v34, v34, v35
	v_add_f32_e32 v35, v36, v37
	v_mov_b32_e32 v54, v103
	v_add_f32_dpp v34, v34, v34 row_ror:8 row_mask:0xf bank_mask:0xf bound_ctrl:1
	v_add_f32_dpp v35, v35, v35 row_ror:8 row_mask:0xf bank_mask:0xf bound_ctrl:1
	ds_read2_b32 v[100:101], v117 offset1:4
	v_add_f32_dpp v34, v34, v34 row_ror:4 row_mask:0xf bank_mask:0xf bound_ctrl:1
	v_add_f32_dpp v35, v35, v35 row_ror:4 row_mask:0xf bank_mask:0xf bound_ctrl:1
	ds_read_b128 v[78:81], v118 offset:11520
	global_load_dwordx4 v[212:215], v118, s[56:57]
	s_add_u32 s56, s56, s58
	s_addc_u32 s57, s57, s59
	ds_read_b128 v[70:73], v118 offset:12032
	ds_read_b128 v[74:77], v118 offset:12288
	ds_read_b128 v[62:65], v118 offset:12544
	ds_read2_b32 v[98:99], v117 offset0:32 offset1:36
	v_add_f32_dpp v34, v34, v34 row_ror:2 row_mask:0xf bank_mask:0xf bound_ctrl:1
	v_add_f32_dpp v35, v35, v35 row_ror:2 row_mask:0xf bank_mask:0xf bound_ctrl:1
	s_nop 0
	v_add_f32_dpp v34, v34, v34 row_ror:1 row_mask:0xf bank_mask:0xf bound_ctrl:1
	v_add_f32_dpp v36, v35, v35 row_ror:1 row_mask:0xf bank_mask:0xf bound_ctrl:1
	v_pk_mul_f32 v[56:57], v[46:47], v[34:35] op_sel_hi:[1,0]
	v_pk_mul_f32 v[34:35], v[48:49], v[34:35] op_sel_hi:[1,0]
	v_pk_mul_f32 v[46:47], v[46:47], v[36:37] op_sel_hi:[1,0]
	v_pk_mul_f32 v[36:37], v[48:49], v[36:37] op_sel_hi:[1,0]
	v_pk_fma_f32 v[34:35], v[52:53], v[102:103], v[34:35] op_sel_hi:[1,0,1]
	v_pk_fma_f32 v[36:37], v[52:53], v[54:55], v[36:37] op_sel_hi:[1,0,1]
	v_pk_fma_f32 v[56:57], v[50:51], v[102:103], v[56:57] op_sel_hi:[1,0,1]
	s_waitcnt vmcnt(7)
	v_pk_fma_f32 v[34:35], v[218:219], v[108:109], v[34:35]
	v_pk_fma_f32 v[46:47], v[50:51], v[54:55], v[46:47] op_sel_hi:[1,0,1]
	v_pk_fma_f32 v[20:21], v[218:219], v[44:45], v[36:37]
	v_pk_fma_f32 v[92:93], v[216:217], v[106:107], v[56:57]
	v_pk_fma_f32 v[18:19], v[216:217], v[42:43], v[46:47]
	v_pk_mul_f32 v[36:37], v[12:13], v[34:35]
	v_pk_mul_f32 v[12:13], v[12:13], v[20:21]
	v_pk_fma_f32 v[36:37], v[10:11], v[92:93], v[36:37]
	v_pk_fma_f32 v[10:11], v[10:11], v[18:19], v[12:13]
	v_add_f32_e32 v12, v36, v37
	v_add_f32_e32 v10, v10, v11
	ds_write2st64_b32 v111, v12, v10 offset0:224 offset1:225
	s_waitcnt lgkmcnt(12)
	v_pk_mul_f32 v[10:11], v[96:97], v[34:35]
	v_pk_mul_f32 v[12:13], v[96:97], v[20:21]
	v_pk_fma_f32 v[10:11], v[94:95], v[92:93], v[10:11]
	v_pk_fma_f32 v[12:13], v[94:95], v[18:19], v[12:13]
	v_add_f32_e32 v10, v10, v11
	v_add_f32_e32 v11, v12, v13
	v_mov_b32_e32 v36, v105
	v_add_f32_dpp v10, v10, v10 row_ror:8 row_mask:0xf bank_mask:0xf bound_ctrl:1
	v_add_f32_dpp v11, v11, v11 row_ror:8 row_mask:0xf bank_mask:0xf bound_ctrl:1
	s_waitcnt lgkmcnt(6)
	v_mov_b32_e32 v102, v101
	v_add_f32_dpp v10, v10, v10 row_ror:4 row_mask:0xf bank_mask:0xf bound_ctrl:1
	v_add_f32_dpp v11, v11, v11 row_ror:4 row_mask:0xf bank_mask:0xf bound_ctrl:1
	ds_read_b128 v[58:61], v118 offset:12800
	global_load_dwordx4 v[216:219], v118, s[56:57]
	s_add_u32 s56, s56, s58
	s_addc_u32 s57, s57, s59
	ds_read_b128 v[50:53], v118 offset:13312
	ds_read_b128 v[54:57], v118 offset:13568
	ds_read_b128 v[42:45], v118 offset:13824
	ds_read2_b32 v[90:91], v117 offset0:64 offset1:68
	v_add_f32_dpp v10, v10, v10 row_ror:2 row_mask:0xf bank_mask:0xf bound_ctrl:1
	v_add_f32_dpp v11, v11, v11 row_ror:2 row_mask:0xf bank_mask:0xf bound_ctrl:1
	s_nop 0
	v_add_f32_dpp v10, v10, v10 row_ror:1 row_mask:0xf bank_mask:0xf bound_ctrl:1
	v_add_f32_dpp v12, v11, v11 row_ror:1 row_mask:0xf bank_mask:0xf bound_ctrl:1
	v_pk_mul_f32 v[94:95], v[82:83], v[10:11] op_sel_hi:[1,0]
	v_pk_mul_f32 v[10:11], v[84:85], v[10:11] op_sel_hi:[1,0]
	v_pk_fma_f32 v[94:95], v[86:87], v[104:105], v[94:95] op_sel_hi:[1,0,1]
	v_pk_fma_f32 v[10:11], v[88:89], v[104:105], v[10:11] op_sel_hi:[1,0,1]
	s_waitcnt vmcnt(7)
	v_pk_fma_f32 v[92:93], v[220:221], v[92:93], v[94:95]
	v_pk_fma_f32 v[94:95], v[222:223], v[34:35], v[10:11]
	v_pk_mul_f32 v[10:11], v[82:83], v[12:13] op_sel_hi:[1,0]
	s_nop 0
	v_pk_fma_f32 v[10:11], v[86:87], v[36:37], v[10:11] op_sel_hi:[1,0,1]
	v_pk_mul_f32 v[86:87], v[40:41], v[94:95]
	v_pk_fma_f32 v[96:97], v[220:221], v[18:19], v[10:11]
	v_pk_mul_f32 v[10:11], v[84:85], v[12:13] op_sel_hi:[1,0]
	v_pk_fma_f32 v[86:87], v[38:39], v[92:93], v[86:87]
	v_pk_fma_f32 v[10:11], v[88:89], v[36:37], v[10:11] op_sel_hi:[1,0,1]
	s_nop 0
	v_pk_fma_f32 v[84:85], v[222:223], v[20:21], v[10:11]
	v_pk_mul_f32 v[10:11], v[16:17], v[94:95]
	v_pk_mul_f32 v[40:41], v[40:41], v[84:85]
	v_pk_fma_f32 v[10:11], v[14:15], v[92:93], v[10:11]
	v_pk_fma_f32 v[38:39], v[38:39], v[96:97], v[40:41]
	v_add_f32_e32 v40, v86, v87
	v_add_f32_e32 v38, v38, v39
	v_pk_mul_f32 v[12:13], v[16:17], v[84:85]
	v_add_f32_dpp v40, v40, v40 row_ror:8 row_mask:0xf bank_mask:0xf bound_ctrl:1
	v_add_f32_dpp v38, v38, v38 row_ror:8 row_mask:0xf bank_mask:0xf bound_ctrl:1
	v_pk_fma_f32 v[12:13], v[14:15], v[96:97], v[12:13]
	v_add_f32_dpp v40, v40, v40 row_ror:4 row_mask:0xf bank_mask:0xf bound_ctrl:1
	v_add_f32_dpp v38, v38, v38 row_ror:4 row_mask:0xf bank_mask:0xf bound_ctrl:1
	v_add_f32_e32 v10, v10, v11
	v_add_f32_dpp v40, v40, v40 row_ror:2 row_mask:0xf bank_mask:0xf bound_ctrl:1
	v_add_f32_dpp v38, v38, v38 row_ror:2 row_mask:0xf bank_mask:0xf bound_ctrl:1
	v_add_f32_e32 v11, v12, v13
	v_add_f32_dpp v40, v40, v40 row_ror:1 row_mask:0xf bank_mask:0xf bound_ctrl:1
	v_add_f32_dpp v38, v38, v38 row_ror:1 row_mask:0xf bank_mask:0xf bound_ctrl:1
	v_pk_mul_f32 v[86:87], v[22:23], v[40:41] op_sel_hi:[1,0]
	v_pk_mul_f32 v[22:23], v[22:23], v[38:39] op_sel_hi:[1,0]
	v_pk_fma_f32 v[86:87], v[26:27], v[100:101], v[86:87] op_sel_hi:[1,0,1]
	v_pk_fma_f32 v[22:23], v[26:27], v[102:103], v[22:23] op_sel_hi:[1,0,1]
	s_waitcnt vmcnt(6)
	v_pk_fma_f32 v[86:87], v[192:193], v[92:93], v[86:87]
	v_pk_mul_f32 v[40:41], v[24:25], v[40:41] op_sel_hi:[1,0]
	v_pk_fma_f32 v[92:93], v[192:193], v[96:97], v[22:23]
	v_pk_mul_f32 v[6:7], v[24:25], v[38:39] op_sel_hi:[1,0]
	v_pk_fma_f32 v[40:41], v[28:29], v[100:101], v[40:41] op_sel_hi:[1,0,1]
	v_pk_fma_f32 v[6:7], v[28:29], v[102:103], v[6:7] op_sel_hi:[1,0,1]
	v_pk_fma_f32 v[88:89], v[194:195], v[94:95], v[40:41]
	v_pk_fma_f32 v[94:95], v[194:195], v[84:85], v[6:7]
	s_waitcnt lgkmcnt(10)
	v_pk_mul_f32 v[96:97], v[80:81], v[88:89]
	v_pk_mul_f32 v[80:81], v[80:81], v[94:95]
	v_pk_fma_f32 v[96:97], v[78:79], v[86:87], v[96:97]
	v_pk_fma_f32 v[78:79], v[78:79], v[92:93], v[80:81]
	v_add_f32_e32 v80, v96, v97
	v_add_f32_e32 v78, v78, v79
	s_waitcnt lgkmcnt(6)
	v_mov_b32_e32 v100, v99
	v_add_f32_dpp v80, v80, v80 row_ror:8 row_mask:0xf bank_mask:0xf bound_ctrl:1
	v_add_f32_dpp v78, v78, v78 row_ror:8 row_mask:0xf bank_mask:0xf bound_ctrl:1
	v_pk_mul_f32 v[6:7], v[4:5], v[88:89]
	v_add_f32_dpp v80, v80, v80 row_ror:4 row_mask:0xf bank_mask:0xf bound_ctrl:1
	v_add_f32_dpp v78, v78, v78 row_ror:4 row_mask:0xf bank_mask:0xf bound_ctrl:1
	v_pk_mul_f32 v[4:5], v[4:5], v[94:95]
	v_add_f32_dpp v80, v80, v80 row_ror:2 row_mask:0xf bank_mask:0xf bound_ctrl:1
	v_add_f32_dpp v78, v78, v78 row_ror:2 row_mask:0xf bank_mask:0xf bound_ctrl:1
	v_pk_fma_f32 v[6:7], v[2:3], v[86:87], v[6:7]
	v_add_f32_dpp v80, v80, v80 row_ror:1 row_mask:0xf bank_mask:0xf bound_ctrl:1
	v_add_f32_dpp v78, v78, v78 row_ror:1 row_mask:0xf bank_mask:0xf bound_ctrl:1
	v_pk_mul_f32 v[96:97], v[70:71], v[80:81] op_sel_hi:[1,0]
	v_pk_mul_f32 v[70:71], v[70:71], v[78:79] op_sel_hi:[1,0]
	v_pk_fma_f32 v[96:97], v[74:75], v[98:99], v[96:97] op_sel_hi:[1,0,1]
	v_pk_mul_f32 v[80:81], v[72:73], v[80:81] op_sel_hi:[1,0]
	v_pk_fma_f32 v[70:71], v[74:75], v[100:101], v[70:71] op_sel_hi:[1,0,1]
	s_waitcnt vmcnt(5)
	v_pk_fma_f32 v[96:97], v[196:197], v[86:87], v[96:97]
	v_pk_fma_f32 v[80:81], v[76:77], v[98:99], v[80:81] op_sel_hi:[1,0,1]
	v_pk_fma_f32 v[98:99], v[196:197], v[92:93], v[70:71]
	v_pk_mul_f32 v[66:67], v[72:73], v[78:79] op_sel_hi:[1,0]
	v_pk_fma_f32 v[88:89], v[198:199], v[88:89], v[80:81]
	v_pk_fma_f32 v[66:67], v[76:77], v[100:101], v[66:67] op_sel_hi:[1,0,1]
	v_pk_fma_f32 v[2:3], v[2:3], v[92:93], v[4:5]
	v_pk_fma_f32 v[100:101], v[198:199], v[94:95], v[66:67]
	s_waitcnt lgkmcnt(4)
	v_pk_mul_f32 v[92:93], v[60:61], v[88:89]
	v_pk_mul_f32 v[60:61], v[60:61], v[100:101]
	v_pk_fma_f32 v[92:93], v[58:59], v[96:97], v[92:93]
	v_pk_fma_f32 v[58:59], v[58:59], v[98:99], v[60:61]
	v_add_f32_e32 v60, v92, v93
	v_add_f32_e32 v58, v58, v59
	s_waitcnt lgkmcnt(0)
	v_mov_b32_e32 v102, v91
	v_add_f32_dpp v60, v60, v60 row_ror:8 row_mask:0xf bank_mask:0xf bound_ctrl:1
	v_add_f32_dpp v58, v58, v58 row_ror:8 row_mask:0xf bank_mask:0xf bound_ctrl:1
	ds_write2st64_b32 v111, v10, v11 offset0:232 offset1:233
	v_add_f32_dpp v60, v60, v60 row_ror:4 row_mask:0xf bank_mask:0xf bound_ctrl:1
	v_add_f32_dpp v58, v58, v58 row_ror:4 row_mask:0xf bank_mask:0xf bound_ctrl:1
	v_pk_mul_f32 v[66:67], v[64:65], v[88:89]
	v_add_f32_dpp v60, v60, v60 row_ror:2 row_mask:0xf bank_mask:0xf bound_ctrl:1
	v_add_f32_dpp v58, v58, v58 row_ror:2 row_mask:0xf bank_mask:0xf bound_ctrl:1
	ds_read_b128 v[10:13], v118 offset:14080
	global_load_dwordx4 v[220:223], v118, s[56:57]
	s_add_u32 s56, s56, s58
	s_addc_u32 s57, s57, s59
	ds_read_b128 v[18:21], v118 offset:14592
	ds_read_b128 v[34:37], v118 offset:14848
	ds_read_b128 v[30:33], v118 offset:15104
	ds_read2_b32 v[82:83], v117 offset0:96 offset1:100
	v_add_f32_dpp v60, v60, v60 row_ror:1 row_mask:0xf bank_mask:0xf bound_ctrl:1
	v_add_f32_dpp v58, v58, v58 row_ror:1 row_mask:0xf bank_mask:0xf bound_ctrl:1
	v_pk_mul_f32 v[92:93], v[50:51], v[60:61] op_sel_hi:[1,0]
	v_pk_mul_f32 v[50:51], v[50:51], v[58:59] op_sel_hi:[1,0]
	v_pk_fma_f32 v[92:93], v[54:55], v[90:91], v[92:93] op_sel_hi:[1,0,1]
	v_pk_fma_f32 v[50:51], v[54:55], v[102:103], v[50:51] op_sel_hi:[1,0,1]
	s_waitcnt vmcnt(5)
	v_pk_fma_f32 v[92:93], v[200:201], v[96:97], v[92:93]
	v_pk_mul_f32 v[60:61], v[52:53], v[60:61] op_sel_hi:[1,0]
	v_pk_fma_f32 v[94:95], v[200:201], v[98:99], v[50:51]
	v_pk_mul_f32 v[46:47], v[52:53], v[58:59] op_sel_hi:[1,0]
	v_pk_fma_f32 v[60:61], v[56:57], v[90:91], v[60:61] op_sel_hi:[1,0,1]
	v_pk_fma_f32 v[46:47], v[56:57], v[102:103], v[46:47] op_sel_hi:[1,0,1]
	v_pk_fma_f32 v[66:67], v[62:63], v[96:97], v[66:67]
	v_pk_mul_f32 v[64:65], v[64:65], v[100:101]
	v_pk_fma_f32 v[90:91], v[202:203], v[88:89], v[60:61]
	v_pk_fma_f32 v[96:97], v[202:203], v[100:101], v[46:47]
	v_pk_fma_f32 v[62:63], v[62:63], v[98:99], v[64:65]
	s_waitcnt lgkmcnt(4)
	v_pk_mul_f32 v[98:99], v[12:13], v[90:91]
	v_pk_mul_f32 v[12:13], v[12:13], v[96:97]
	v_pk_fma_f32 v[98:99], v[10:11], v[92:93], v[98:99]
	v_pk_fma_f32 v[10:11], v[10:11], v[94:95], v[12:13]
	v_add_f32_e32 v12, v98, v99
	v_add_f32_e32 v10, v10, v11
	s_waitcnt lgkmcnt(0)
	v_mov_b32_e32 v100, v83
	v_add_f32_dpp v12, v12, v12 row_ror:8 row_mask:0xf bank_mask:0xf bound_ctrl:1
	v_add_f32_dpp v10, v10, v10 row_ror:8 row_mask:0xf bank_mask:0xf bound_ctrl:1
	v_add_f32_e32 v4, v6, v7
	v_add_f32_dpp v12, v12, v12 row_ror:4 row_mask:0xf bank_mask:0xf bound_ctrl:1
	v_add_f32_dpp v10, v10, v10 row_ror:4 row_mask:0xf bank_mask:0xf bound_ctrl:1
	v_add_f32_e32 v2, v2, v3
	v_add_f32_dpp v12, v12, v12 row_ror:2 row_mask:0xf bank_mask:0xf bound_ctrl:1
	v_add_f32_dpp v10, v10, v10 row_ror:2 row_mask:0xf bank_mask:0xf bound_ctrl:1
	ds_write2st64_b32 v111, v4, v2 offset0:240 offset1:241
	v_add_f32_dpp v12, v12, v12 row_ror:1 row_mask:0xf bank_mask:0xf bound_ctrl:1
	v_add_f32_dpp v98, v10, v10 row_ror:1 row_mask:0xf bank_mask:0xf bound_ctrl:1
	v_pk_mul_f32 v[10:11], v[18:19], v[12:13] op_sel_hi:[1,0]
	v_pk_mul_f32 v[18:19], v[18:19], v[98:99] op_sel_hi:[1,0]
	v_pk_fma_f32 v[10:11], v[34:35], v[82:83], v[10:11] op_sel_hi:[1,0,1]
	v_pk_mul_f32 v[12:13], v[20:21], v[12:13] op_sel_hi:[1,0]
	v_pk_fma_f32 v[18:19], v[34:35], v[100:101], v[18:19] op_sel_hi:[1,0,1]
	s_waitcnt vmcnt(4)
	v_pk_fma_f32 v[10:11], v[204:205], v[92:93], v[10:11]
	v_pk_fma_f32 v[12:13], v[36:37], v[82:83], v[12:13] op_sel_hi:[1,0,1]
	v_pk_fma_f32 v[14:15], v[204:205], v[94:95], v[18:19]
	v_pk_mul_f32 v[18:19], v[20:21], v[98:99] op_sel_hi:[1,0]
	v_pk_fma_f32 v[12:13], v[206:207], v[90:91], v[12:13]
	v_pk_fma_f32 v[18:19], v[36:37], v[100:101], v[18:19] op_sel_hi:[1,0,1]
	ds_read_b128 v[6:9], v118 offset:15360
	global_load_dwordx4 v[192:195], v118, s[56:57]
	s_add_u32 s56, s56, s58
	s_addc_u32 s57, s57, s59
	ds_read_b128 v[22:25], v118 offset:15872
	ds_read_b128 v[26:29], v118 offset:16128
	ds_read_b128 v[38:41], v118 offset:16384
	ds_read2_b32 v[84:85], v117 offset0:128 offset1:132
	v_pk_fma_f32 v[16:17], v[206:207], v[96:97], v[18:19]
	s_waitcnt lgkmcnt(4)
	v_pk_mul_f32 v[98:99], v[8:9], v[12:13]
	v_pk_mul_f32 v[8:9], v[8:9], v[16:17]
	v_pk_fma_f32 v[98:99], v[6:7], v[10:11], v[98:99]
	v_pk_fma_f32 v[6:7], v[6:7], v[14:15], v[8:9]
	v_add_f32_e32 v8, v98, v99
	v_add_f32_e32 v6, v6, v7
	v_pk_mul_f32 v[18:19], v[32:33], v[12:13]
	v_add_f32_dpp v8, v8, v8 row_ror:8 row_mask:0xf bank_mask:0xf bound_ctrl:1
	v_add_f32_dpp v6, v6, v6 row_ror:8 row_mask:0xf bank_mask:0xf bound_ctrl:1
	s_waitcnt lgkmcnt(0)
	v_mov_b32_e32 v98, v85
	v_add_f32_dpp v8, v8, v8 row_ror:4 row_mask:0xf bank_mask:0xf bound_ctrl:1
	v_add_f32_dpp v6, v6, v6 row_ror:4 row_mask:0xf bank_mask:0xf bound_ctrl:1
	v_pk_mul_f32 v[46:47], v[44:45], v[90:91]
	v_add_f32_dpp v8, v8, v8 row_ror:2 row_mask:0xf bank_mask:0xf bound_ctrl:1
	v_add_f32_dpp v6, v6, v6 row_ror:2 row_mask:0xf bank_mask:0xf bound_ctrl:1
	v_pk_mul_f32 v[44:45], v[44:45], v[96:97]
	v_add_f32_dpp v8, v8, v8 row_ror:1 row_mask:0xf bank_mask:0xf bound_ctrl:1
	v_pk_mul_f32 v[100:101], v[22:23], v[8:9] op_sel_hi:[1,0]
	v_pk_mul_f32 v[8:9], v[24:25], v[8:9] op_sel_hi:[1,0]
	v_add_f32_dpp v6, v6, v6 row_ror:1 row_mask:0xf bank_mask:0xf bound_ctrl:1
	v_pk_fma_f32 v[8:9], v[28:29], v[84:85], v[8:9] op_sel_hi:[1,0,1]
	v_add_f32_e32 v64, v66, v67
	s_waitcnt vmcnt(4)
	v_pk_fma_f32 v[8:9], v[210:211], v[12:13], v[8:9]
	v_pk_mul_f32 v[12:13], v[22:23], v[6:7] op_sel_hi:[1,0]
	v_pk_mul_f32 v[6:7], v[24:25], v[6:7] op_sel_hi:[1,0]
	v_add_f32_e32 v62, v62, v63
	v_pk_fma_f32 v[6:7], v[28:29], v[98:99], v[6:7] op_sel_hi:[1,0,1]
	v_pk_fma_f32 v[46:47], v[42:43], v[92:93], v[46:47]
	v_pk_fma_f32 v[42:43], v[42:43], v[94:95], v[44:45]
	v_pk_mul_f32 v[20:21], v[32:33], v[16:17]
	v_pk_fma_f32 v[100:101], v[26:27], v[84:85], v[100:101] op_sel_hi:[1,0,1]
	v_pk_fma_f32 v[12:13], v[26:27], v[98:99], v[12:13] op_sel_hi:[1,0,1]
	v_pk_fma_f32 v[4:5], v[210:211], v[16:17], v[6:7]
	ds_write2st64_b32 v111, v64, v62 offset0:248 offset1:249
	v_add_f32_e32 v44, v46, v47
	v_add_f32_e32 v42, v42, v43
	v_pk_fma_f32 v[18:19], v[30:31], v[10:11], v[18:19]
	v_pk_fma_f32 v[20:21], v[30:31], v[14:15], v[20:21]
	v_pk_fma_f32 v[10:11], v[208:209], v[10:11], v[100:101]
	v_pk_fma_f32 v[2:3], v[208:209], v[14:15], v[12:13]
	v_pk_mul_f32 v[6:7], v[40:41], v[8:9]
	v_pk_mul_f32 v[12:13], v[40:41], v[4:5]
	ds_read_b128 v[62:65], v118 offset:16640
	global_load_dwordx4 v[196:199], v118, s[56:57]
	s_add_u32 s56, s56, s58
	s_addc_u32 s57, s57, s59
	ds_read_b128 v[70:73], v118 offset:17152
	ds_read_b128 v[74:77], v118 offset:17408
	ds_read_b128 v[78:81], v118 offset:17664
	ds_read2_b32 v[86:87], v117 offset0:160 offset1:164
	ds_write2st64_b32 v112, v44, v42 offset0:80 offset1:81
	v_add_f32_e32 v18, v18, v19
	v_add_f32_e32 v19, v20, v21
	v_pk_fma_f32 v[6:7], v[38:39], v[10:11], v[6:7]
	v_pk_fma_f32 v[12:13], v[38:39], v[2:3], v[12:13]
	ds_read_b128 v[46:49], v118 offset:17920
	global_load_dwordx4 v[200:203], v118, s[56:57]
	s_add_u32 s56, s56, s58
	s_addc_u32 s57, s57, s59
	ds_read_b128 v[50:53], v118 offset:18432
	ds_read_b128 v[54:57], v118 offset:18688
	ds_read_b128 v[58:61], v118 offset:18944
	ds_read2_b32 v[88:89], v117 offset0:192 offset1:196
	ds_write2st64_b32 v112, v18, v19 offset0:88 offset1:89
	v_add_f32_e32 v6, v6, v7
	v_add_f32_e32 v7, v12, v13
	ds_read_b128 v[18:21], v118 offset:19200
	global_load_dwordx4 v[204:207], v118, s[56:57]
	s_add_u32 s56, s56, s58
	s_addc_u32 s57, s57, s59
	ds_read_b128 v[34:37], v118 offset:19712
	ds_read_b128 v[90:93], v118 offset:19968
	ds_read_b128 v[94:97], v118 offset:20224
	ds_read2_b32 v[82:83], v117 offset0:224 offset1:228
	ds_write2st64_b32 v112, v6, v7 offset0:96 offset1:97
	s_waitcnt lgkmcnt(12)
	v_pk_mul_f32 v[6:7], v[64:65], v[8:9]
	v_pk_mul_f32 v[12:13], v[64:65], v[4:5]
	v_pk_fma_f32 v[6:7], v[62:63], v[10:11], v[6:7]
	v_pk_fma_f32 v[12:13], v[62:63], v[2:3], v[12:13]
	v_add_f32_e32 v6, v6, v7
	v_add_f32_e32 v7, v12, v13
	v_mov_b32_e32 v14, v87
	v_add_f32_dpp v6, v6, v6 row_ror:8 row_mask:0xf bank_mask:0xf bound_ctrl:1
	v_add_f32_dpp v7, v7, v7 row_ror:8 row_mask:0xf bank_mask:0xf bound_ctrl:1
	s_nop 0
	v_add_f32_dpp v6, v6, v6 row_ror:4 row_mask:0xf bank_mask:0xf bound_ctrl:1
	v_add_f32_dpp v7, v7, v7 row_ror:4 row_mask:0xf bank_mask:0xf bound_ctrl:1
	s_nop 0
	v_add_f32_dpp v6, v6, v6 row_ror:2 row_mask:0xf bank_mask:0xf bound_ctrl:1
	v_add_f32_dpp v7, v7, v7 row_ror:2 row_mask:0xf bank_mask:0xf bound_ctrl:1
	s_nop 0
	v_add_f32_dpp v6, v6, v6 row_ror:1 row_mask:0xf bank_mask:0xf bound_ctrl:1
	v_add_f32_dpp v12, v7, v7 row_ror:1 row_mask:0xf bank_mask:0xf bound_ctrl:1
	v_pk_mul_f32 v[16:17], v[70:71], v[6:7] op_sel_hi:[1,0]
	v_pk_mul_f32 v[6:7], v[72:73], v[6:7] op_sel_hi:[1,0]
	v_pk_fma_f32 v[16:17], v[74:75], v[86:87], v[16:17] op_sel_hi:[1,0,1]
	v_pk_fma_f32 v[6:7], v[76:77], v[86:87], v[6:7] op_sel_hi:[1,0,1]
	s_waitcnt vmcnt(6)
	v_pk_fma_f32 v[10:11], v[212:213], v[10:11], v[16:17]
	v_pk_fma_f32 v[6:7], v[214:215], v[8:9], v[6:7]
	v_pk_mul_f32 v[8:9], v[70:71], v[12:13] op_sel_hi:[1,0]
	s_nop 0
	v_pk_fma_f32 v[8:9], v[74:75], v[14:15], v[8:9] op_sel_hi:[1,0,1]
	s_nop 0
	v_pk_fma_f32 v[2:3], v[212:213], v[2:3], v[8:9]
	v_pk_mul_f32 v[8:9], v[72:73], v[12:13] op_sel_hi:[1,0]
	s_nop 0
	v_pk_fma_f32 v[8:9], v[76:77], v[14:15], v[8:9] op_sel_hi:[1,0,1]
	s_waitcnt lgkmcnt(7)
	v_mov_b32_e32 v14, v89
	v_pk_fma_f32 v[4:5], v[214:215], v[4:5], v[8:9]
	v_pk_mul_f32 v[8:9], v[80:81], v[6:7]
	v_pk_mul_f32 v[12:13], v[80:81], v[4:5]
	v_pk_fma_f32 v[8:9], v[78:79], v[10:11], v[8:9]
	v_pk_fma_f32 v[12:13], v[78:79], v[2:3], v[12:13]
	v_add_f32_e32 v8, v8, v9
	v_add_f32_e32 v9, v12, v13
	ds_write2st64_b32 v112, v8, v9 offset0:104 offset1:105
	ds_read_b32 v249, v246
	v_pk_mul_f32 v[8:9], v[48:49], v[6:7]
	v_pk_mul_f32 v[12:13], v[48:49], v[4:5]
	v_pk_fma_f32 v[8:9], v[46:47], v[10:11], v[8:9]
	v_pk_fma_f32 v[12:13], v[46:47], v[2:3], v[12:13]
	v_add_f32_e32 v8, v8, v9
	v_add_f32_e32 v9, v12, v13
	s_nop 0
	v_add_f32_dpp v8, v8, v8 row_ror:8 row_mask:0xf bank_mask:0xf bound_ctrl:1
	v_add_f32_dpp v9, v9, v9 row_ror:8 row_mask:0xf bank_mask:0xf bound_ctrl:1
	s_nop 0
	v_add_f32_dpp v8, v8, v8 row_ror:4 row_mask:0xf bank_mask:0xf bound_ctrl:1
	v_add_f32_dpp v9, v9, v9 row_ror:4 row_mask:0xf bank_mask:0xf bound_ctrl:1
	s_nop 0
	v_add_f32_dpp v8, v8, v8 row_ror:2 row_mask:0xf bank_mask:0xf bound_ctrl:1
	v_add_f32_dpp v9, v9, v9 row_ror:2 row_mask:0xf bank_mask:0xf bound_ctrl:1
	s_nop 0
	v_add_f32_dpp v8, v8, v8 row_ror:1 row_mask:0xf bank_mask:0xf bound_ctrl:1
	v_add_f32_dpp v12, v9, v9 row_ror:1 row_mask:0xf bank_mask:0xf bound_ctrl:1
	v_pk_mul_f32 v[16:17], v[50:51], v[8:9] op_sel_hi:[1,0]
	v_pk_mul_f32 v[8:9], v[52:53], v[8:9] op_sel_hi:[1,0]
	v_pk_fma_f32 v[16:17], v[54:55], v[88:89], v[16:17] op_sel_hi:[1,0,1]
	v_pk_fma_f32 v[8:9], v[56:57], v[88:89], v[8:9] op_sel_hi:[1,0,1]
	s_waitcnt vmcnt(5)
	v_pk_fma_f32 v[10:11], v[216:217], v[10:11], v[16:17]
	v_pk_fma_f32 v[6:7], v[218:219], v[6:7], v[8:9]
	v_pk_mul_f32 v[8:9], v[50:51], v[12:13] op_sel_hi:[1,0]
	s_nop 0
	v_pk_fma_f32 v[8:9], v[54:55], v[14:15], v[8:9] op_sel_hi:[1,0,1]
	s_nop 0
	v_pk_fma_f32 v[2:3], v[216:217], v[2:3], v[8:9]
	v_pk_mul_f32 v[8:9], v[52:53], v[12:13] op_sel_hi:[1,0]
	s_nop 0
	v_pk_fma_f32 v[8:9], v[56:57], v[14:15], v[8:9] op_sel_hi:[1,0,1]
	s_waitcnt lgkmcnt(2)
	v_mov_b32_e32 v14, v83
	v_pk_fma_f32 v[4:5], v[218:219], v[4:5], v[8:9]
	v_pk_mul_f32 v[8:9], v[60:61], v[6:7]
	v_pk_mul_f32 v[12:13], v[60:61], v[4:5]
	v_pk_fma_f32 v[8:9], v[58:59], v[10:11], v[8:9]
	v_pk_fma_f32 v[12:13], v[58:59], v[2:3], v[12:13]
	v_add_f32_e32 v8, v8, v9
	v_add_f32_e32 v9, v12, v13
	ds_write2st64_b32 v112, v8, v9 offset0:112 offset1:113
	v_pk_mul_f32 v[8:9], v[20:21], v[6:7]
	v_pk_mul_f32 v[12:13], v[20:21], v[4:5]
	v_pk_fma_f32 v[8:9], v[18:19], v[10:11], v[8:9]
	v_pk_fma_f32 v[12:13], v[18:19], v[2:3], v[12:13]
	v_add_f32_e32 v8, v8, v9
	v_add_f32_e32 v9, v12, v13
	s_nop 0
	v_add_f32_dpp v8, v8, v8 row_ror:8 row_mask:0xf bank_mask:0xf bound_ctrl:1
	v_add_f32_dpp v9, v9, v9 row_ror:8 row_mask:0xf bank_mask:0xf bound_ctrl:1
	s_nop 0
	v_add_f32_dpp v8, v8, v8 row_ror:4 row_mask:0xf bank_mask:0xf bound_ctrl:1
	v_add_f32_dpp v9, v9, v9 row_ror:4 row_mask:0xf bank_mask:0xf bound_ctrl:1
	s_nop 0
	v_add_f32_dpp v8, v8, v8 row_ror:2 row_mask:0xf bank_mask:0xf bound_ctrl:1
	v_add_f32_dpp v9, v9, v9 row_ror:2 row_mask:0xf bank_mask:0xf bound_ctrl:1
	s_nop 0
	v_add_f32_dpp v8, v8, v8 row_ror:1 row_mask:0xf bank_mask:0xf bound_ctrl:1
	v_add_f32_dpp v12, v9, v9 row_ror:1 row_mask:0xf bank_mask:0xf bound_ctrl:1
	v_pk_mul_f32 v[16:17], v[34:35], v[8:9] op_sel_hi:[1,0]
	v_pk_mul_f32 v[8:9], v[36:37], v[8:9] op_sel_hi:[1,0]
	v_pk_fma_f32 v[16:17], v[90:91], v[82:83], v[16:17] op_sel_hi:[1,0,1]
	v_pk_fma_f32 v[8:9], v[92:93], v[82:83], v[8:9] op_sel_hi:[1,0,1]
	s_waitcnt vmcnt(4)
	v_pk_fma_f32 v[22:23], v[220:221], v[10:11], v[16:17]
	v_pk_fma_f32 v[24:25], v[222:223], v[6:7], v[8:9]
	v_pk_mul_f32 v[6:7], v[34:35], v[12:13] op_sel_hi:[1,0]
	s_nop 0
	v_pk_fma_f32 v[6:7], v[90:91], v[14:15], v[6:7] op_sel_hi:[1,0,1]
	s_nop 0
	v_pk_fma_f32 v[26:27], v[220:221], v[2:3], v[6:7]
	v_pk_mul_f32 v[2:3], v[36:37], v[12:13] op_sel_hi:[1,0]
	s_nop 0
	v_pk_fma_f32 v[2:3], v[92:93], v[14:15], v[2:3] op_sel_hi:[1,0,1]
	s_nop 0
	v_pk_fma_f32 v[28:29], v[222:223], v[4:5], v[2:3]
	v_pk_mul_f32 v[2:3], v[96:97], v[24:25]
	v_pk_mul_f32 v[4:5], v[96:97], v[28:29]
	v_pk_fma_f32 v[2:3], v[94:95], v[22:23], v[2:3]
	v_pk_fma_f32 v[4:5], v[94:95], v[26:27], v[4:5]
	v_add_f32_e32 v2, v2, v3
	v_add_f32_e32 v3, v4, v5
	ds_write2st64_b32 v112, v2, v3 offset0:120 offset1:121
	s_add_i32 s64, s4, 1
	v_mov_b32_e32 v248, s64
	ds_write_b32 v247, v248
	s_waitcnt lgkmcnt(3)
	v_cmp_gt_u32_e32 vcc, s64, v249
	s_nop 0
	s_cbranch_vccnz .Lsflag_slow_1
.Lsflag_go_1:
	ds_read_b128 v[18:21], v118 offset:20480
	global_load_dwordx4 v[208:211], v118, s[56:57]
	s_add_u32 s56, s56, s58
	s_addc_u32 s57, s57, s59
	ds_read_b128 v[10:13], v118 offset:20992
	ds_read_b128 v[14:17], v118 offset:21248
	ds_read_b128 v[2:5], v118 offset:21504
	s_waitcnt lgkmcnt(3)
	v_pk_mul_f32 v[66:67], v[20:21], v[24:25]
	v_pk_mul_f32 v[20:21], v[20:21], v[28:29]
	v_pk_fma_f32 v[66:67], v[18:19], v[22:23], v[66:67]
	v_pk_fma_f32 v[18:19], v[18:19], v[26:27], v[20:21]
	v_add_f32_e32 v20, v66, v67
	v_add_f32_e32 v18, v18, v19
	ds_read2_b32 v[62:63], v120 offset1:4
	ds_read_b128 v[30:33], v118 offset:21760
	global_load_dwordx4 v[212:215], v118, s[56:57]
	s_add_u32 s56, s56, s58
	s_addc_u32 s57, s57, s59
	ds_read_b128 v[38:41], v118 offset:22272
	ds_read_b128 v[42:45], v118 offset:22528
	ds_read_b128 v[46:49], v118 offset:22784
	ds_read2_b32 v[64:65], v120 offset0:32 offset1:36
	ds_read_b128 v[50:53], v118 offset:23040
	global_load_dwordx4 v[216:219], v118, s[56:57]
	s_add_u32 s56, s56, s58
	s_addc_u32 s57, s57, s59
	ds_read_b128 v[58:61], v118 offset:23552
	ds_read_b128 v[82:85], v118 offset:23808
	ds_read_b128 v[88:91], v118 offset:24064
	ds_read2_b32 v[108:109], v120 offset0:64 offset1:68
	ds_read_b128 v[92:95], v118 offset:24320
	global_load_dwordx4 v[220:223], v118, s[56:57]
	s_add_u32 s56, s56, s58
	s_addc_u32 s57, s57, s59
	ds_read_b128 v[100:103], v118 offset:24832
	ds_read_b128 v[104:107], v118 offset:25088
	ds_read_b128 v[124:127], v118 offset:25344
	ds_read2_b32 v[130:131], v120 offset0:96 offset1:100
	v_add_f32_dpp v20, v20, v20 row_ror:8 row_mask:0xf bank_mask:0xf bound_ctrl:1
	v_add_f32_dpp v18, v18, v18 row_ror:8 row_mask:0xf bank_mask:0xf bound_ctrl:1
	s_waitcnt lgkmcnt(12)
	v_mov_b32_e32 v66, v63
	v_add_f32_dpp v20, v20, v20 row_ror:4 row_mask:0xf bank_mask:0xf bound_ctrl:1
	v_add_f32_dpp v18, v18, v18 row_ror:4 row_mask:0xf bank_mask:0xf bound_ctrl:1
	s_nop 0
	v_add_f32_dpp v20, v20, v20 row_ror:2 row_mask:0xf bank_mask:0xf bound_ctrl:1
	v_add_f32_dpp v18, v18, v18 row_ror:2 row_mask:0xf bank_mask:0xf bound_ctrl:1
	s_nop 0
	v_add_f32_dpp v20, v20, v20 row_ror:1 row_mask:0xf bank_mask:0xf bound_ctrl:1
	v_add_f32_dpp v18, v18, v18 row_ror:1 row_mask:0xf bank_mask:0xf bound_ctrl:1
	v_pk_mul_f32 v[68:69], v[10:11], v[20:21] op_sel_hi:[1,0]
	v_pk_mul_f32 v[10:11], v[10:11], v[18:19] op_sel_hi:[1,0]
	v_pk_fma_f32 v[68:69], v[14:15], v[62:63], v[68:69] op_sel_hi:[1,0,1]
	v_pk_mul_f32 v[20:21], v[12:13], v[20:21] op_sel_hi:[1,0]
	v_pk_fma_f32 v[10:11], v[14:15], v[66:67], v[10:11] op_sel_hi:[1,0,1]
	s_waitcnt vmcnt(7)
	v_pk_fma_f32 v[22:23], v[192:193], v[22:23], v[68:69]
	v_pk_fma_f32 v[20:21], v[16:17], v[62:63], v[20:21] op_sel_hi:[1,0,1]
	v_pk_fma_f32 v[26:27], v[192:193], v[26:27], v[10:11]
	v_pk_mul_f32 v[6:7], v[12:13], v[18:19] op_sel_hi:[1,0]
	v_pk_fma_f32 v[24:25], v[194:195], v[24:25], v[20:21]
	v_pk_fma_f32 v[6:7], v[16:17], v[66:67], v[6:7] op_sel_hi:[1,0,1]
	v_pk_mul_f32 v[62:63], v[32:33], v[24:25]
	v_pk_fma_f32 v[28:29], v[194:195], v[28:29], v[6:7]
	v_pk_fma_f32 v[62:63], v[30:31], v[22:23], v[62:63]
	v_pk_mul_f32 v[32:33], v[32:33], v[28:29]
	v_pk_mul_f32 v[6:7], v[4:5], v[24:25]
	v_pk_fma_f32 v[30:31], v[30:31], v[26:27], v[32:33]
	v_add_f32_e32 v32, v62, v63
	v_add_f32_e32 v30, v30, v31
	s_waitcnt lgkmcnt(10)
	v_mov_b32_e32 v62, v65
	v_add_f32_dpp v32, v32, v32 row_ror:8 row_mask:0xf bank_mask:0xf bound_ctrl:1
	v_add_f32_dpp v30, v30, v30 row_ror:8 row_mask:0xf bank_mask:0xf bound_ctrl:1
	v_pk_mul_f32 v[4:5], v[4:5], v[28:29]
	v_add_f32_dpp v32, v32, v32 row_ror:4 row_mask:0xf bank_mask:0xf bound_ctrl:1
	v_add_f32_dpp v30, v30, v30 row_ror:4 row_mask:0xf bank_mask:0xf bound_ctrl:1
	v_pk_fma_f32 v[6:7], v[2:3], v[22:23], v[6:7]
	v_add_f32_dpp v32, v32, v32 row_ror:2 row_mask:0xf bank_mask:0xf bound_ctrl:1
	v_add_f32_dpp v30, v30, v30 row_ror:2 row_mask:0xf bank_mask:0xf bound_ctrl:1
	v_pk_fma_f32 v[2:3], v[2:3], v[26:27], v[4:5]
	v_add_f32_dpp v32, v32, v32 row_ror:1 row_mask:0xf bank_mask:0xf bound_ctrl:1
	v_pk_mul_f32 v[66:67], v[38:39], v[32:33] op_sel_hi:[1,0]
	v_pk_mul_f32 v[32:33], v[40:41], v[32:33] op_sel_hi:[1,0]
	v_add_f32_dpp v30, v30, v30 row_ror:1 row_mask:0xf bank_mask:0xf bound_ctrl:1
	v_pk_fma_f32 v[32:33], v[44:45], v[64:65], v[32:33] op_sel_hi:[1,0,1]
	v_pk_fma_f32 v[66:67], v[42:43], v[64:65], v[66:67] op_sel_hi:[1,0,1]
	s_waitcnt vmcnt(6)
	v_pk_fma_f32 v[24:25], v[198:199], v[24:25], v[32:33]
	v_pk_mul_f32 v[32:33], v[38:39], v[30:31] op_sel_hi:[1,0]
	v_pk_mul_f32 v[30:31], v[40:41], v[30:31] op_sel_hi:[1,0]
	v_pk_fma_f32 v[32:33], v[42:43], v[62:63], v[32:33] op_sel_hi:[1,0,1]
	v_pk_fma_f32 v[30:31], v[44:45], v[62:63], v[30:31] op_sel_hi:[1,0,1]
	v_pk_fma_f32 v[22:23], v[196:197], v[22:23], v[66:67]
	v_pk_fma_f32 v[28:29], v[198:199], v[28:29], v[30:31]
	v_pk_fma_f32 v[26:27], v[196:197], v[26:27], v[32:33]
	v_pk_mul_f32 v[30:31], v[48:49], v[24:25]
	v_pk_mul_f32 v[32:33], v[48:49], v[28:29]
	v_add_f32_e32 v4, v6, v7
	v_add_f32_e32 v2, v2, v3
	v_pk_fma_f32 v[30:31], v[46:47], v[22:23], v[30:31]
	v_pk_fma_f32 v[32:33], v[46:47], v[26:27], v[32:33]
	ds_write2st64_b32 v113, v4, v2 offset1:1
	v_add_f32_e32 v30, v30, v31
	v_add_f32_e32 v31, v32, v33
	ds_read_b128 v[2:5], v118 offset:25600
	global_load_dwordx4 v[192:195], v118, s[56:57]
	s_add_u32 s56, s56, s58
	s_addc_u32 s57, s57, s59
	ds_read_b128 v[10:13], v118 offset:26112
	ds_read_b128 v[14:17], v118 offset:26368
	ds_read_b128 v[18:21], v118 offset:26624
	ds_read2_b32 v[132:133], v120 offset0:128 offset1:132
	ds_write2st64_b32 v113, v30, v31 offset0:8 offset1:9
	s_waitcnt lgkmcnt(12)
	v_pk_mul_f32 v[30:31], v[52:53], v[24:25]
	v_pk_mul_f32 v[32:33], v[52:53], v[28:29]
	v_pk_fma_f32 v[30:31], v[50:51], v[22:23], v[30:31]
	v_pk_fma_f32 v[32:33], v[50:51], v[26:27], v[32:33]
	v_add_f32_e32 v30, v30, v31
	v_add_f32_e32 v31, v32, v33
	v_mov_b32_e32 v34, v109
	v_add_f32_dpp v30, v30, v30 row_ror:8 row_mask:0xf bank_mask:0xf bound_ctrl:1
	v_add_f32_dpp v31, v31, v31 row_ror:8 row_mask:0xf bank_mask:0xf bound_ctrl:1
	ds_read_b128 v[78:81], v118 offset:26880
	global_load_dwordx4 v[196:199], v118, s[56:57]
	s_add_u32 s56, s56, s58
	s_addc_u32 s57, s57, s59
	ds_read_b128 v[70:73], v118 offset:27392
	ds_read_b128 v[74:77], v118 offset:27648
	ds_read_b128 v[62:65], v118 offset:27904
	ds_read2_b32 v[86:87], v120 offset0:160 offset1:164
	v_add_f32_dpp v30, v30, v30 row_ror:4 row_mask:0xf bank_mask:0xf bound_ctrl:1
	v_add_f32_dpp v31, v31, v31 row_ror:4 row_mask:0xf bank_mask:0xf bound_ctrl:1
	s_nop 0
	v_add_f32_dpp v30, v30, v30 row_ror:2 row_mask:0xf bank_mask:0xf bound_ctrl:1
	v_add_f32_dpp v31, v31, v31 row_ror:2 row_mask:0xf bank_mask:0xf bound_ctrl:1
	s_nop 0
	v_add_f32_dpp v30, v30, v30 row_ror:1 row_mask:0xf bank_mask:0xf bound_ctrl:1
	v_add_f32_dpp v32, v31, v31 row_ror:1 row_mask:0xf bank_mask:0xf bound_ctrl:1
	v_pk_mul_f32 v[36:37], v[58:59], v[30:31] op_sel_hi:[1,0]
	v_pk_mul_f32 v[30:31], v[60:61], v[30:31] op_sel_hi:[1,0]
	v_pk_fma_f32 v[36:37], v[82:83], v[108:109], v[36:37] op_sel_hi:[1,0,1]
	v_pk_fma_f32 v[30:31], v[84:85], v[108:109], v[30:31] op_sel_hi:[1,0,1]
	s_waitcnt vmcnt(7)
	v_pk_fma_f32 v[22:23], v[200:201], v[22:23], v[36:37]
	v_pk_fma_f32 v[24:25], v[202:203], v[24:25], v[30:31]
	v_pk_mul_f32 v[30:31], v[58:59], v[32:33] op_sel_hi:[1,0]
	s_nop 0
	v_pk_fma_f32 v[30:31], v[82:83], v[34:35], v[30:31] op_sel_hi:[1,0,1]
	s_nop 0
	v_pk_fma_f32 v[26:27], v[200:201], v[26:27], v[30:31]
	v_pk_mul_f32 v[30:31], v[60:61], v[32:33] op_sel_hi:[1,0]
	s_nop 0
	v_pk_fma_f32 v[30:31], v[84:85], v[34:35], v[30:31] op_sel_hi:[1,0,1]
	s_waitcnt lgkmcnt(12)
	v_mov_b32_e32 v34, v131
	v_pk_fma_f32 v[28:29], v[202:203], v[28:29], v[30:31]
	v_pk_mul_f32 v[30:31], v[90:91], v[24:25]
	v_pk_mul_f32 v[32:33], v[90:91], v[28:29]
	v_pk_fma_f32 v[30:31], v[88:89], v[22:23], v[30:31]
	v_pk_fma_f32 v[32:33], v[88:89], v[26:27], v[32:33]
	v_add_f32_e32 v30, v30, v31
	v_add_f32_e32 v31, v32, v33
	ds_write2st64_b32 v113, v30, v31 offset0:16 offset1:17
	v_pk_mul_f32 v[30:31], v[94:95], v[24:25]
	v_pk_mul_f32 v[32:33], v[94:95], v[28:29]
	v_pk_fma_f32 v[30:31], v[92:93], v[22:23], v[30:31]
	v_pk_fma_f32 v[32:33], v[92:93], v[26:27], v[32:33]
	v_add_f32_e32 v30, v30, v31
	v_add_f32_e32 v31, v32, v33
	ds_read_b128 v[58:61], v118 offset:28160
	global_load_dwordx4 v[200:203], v118, s[56:57]
	s_add_u32 s56, s56, s58
	s_addc_u32 s57, s57, s59
	ds_read_b128 v[50:53], v118 offset:28672
	ds_read_b128 v[54:57], v118 offset:28928
	ds_read_b128 v[42:45], v118 offset:29184
	ds_read2_b32 v[84:85], v120 offset0:192 offset1:196
	v_add_f32_dpp v30, v30, v30 row_ror:8 row_mask:0xf bank_mask:0xf bound_ctrl:1
	v_add_f32_dpp v31, v31, v31 row_ror:8 row_mask:0xf bank_mask:0xf bound_ctrl:1
	s_nop 0
	v_add_f32_dpp v30, v30, v30 row_ror:4 row_mask:0xf bank_mask:0xf bound_ctrl:1
	v_add_f32_dpp v31, v31, v31 row_ror:4 row_mask:0xf bank_mask:0xf bound_ctrl:1
	s_nop 0
	v_add_f32_dpp v30, v30, v30 row_ror:2 row_mask:0xf bank_mask:0xf bound_ctrl:1
	v_add_f32_dpp v31, v31, v31 row_ror:2 row_mask:0xf bank_mask:0xf bound_ctrl:1
	s_nop 0
	v_add_f32_dpp v30, v30, v30 row_ror:1 row_mask:0xf bank_mask:0xf bound_ctrl:1
	v_pk_mul_f32 v[36:37], v[100:101], v[30:31] op_sel_hi:[1,0]
	v_add_f32_dpp v32, v31, v31 row_ror:1 row_mask:0xf bank_mask:0xf bound_ctrl:1
	v_pk_fma_f32 v[36:37], v[104:105], v[130:131], v[36:37] op_sel_hi:[1,0,1]
	s_nop 0
	s_waitcnt vmcnt(7)
	v_pk_fma_f32 v[88:89], v[204:205], v[22:23], v[36:37]
	v_pk_mul_f32 v[22:23], v[102:103], v[30:31] op_sel_hi:[1,0]
	s_nop 0
	v_pk_fma_f32 v[22:23], v[106:107], v[130:131], v[22:23] op_sel_hi:[1,0,1]
	s_nop 0
	v_pk_fma_f32 v[90:91], v[206:207], v[24:25], v[22:23]
	v_pk_mul_f32 v[22:23], v[100:101], v[32:33] op_sel_hi:[1,0]
	s_nop 0
	v_pk_fma_f32 v[22:23], v[104:105], v[34:35], v[22:23] op_sel_hi:[1,0,1]
	s_nop 0
	v_pk_fma_f32 v[92:93], v[204:205], v[26:27], v[22:23]
	v_pk_mul_f32 v[22:23], v[102:103], v[32:33] op_sel_hi:[1,0]
	s_waitcnt lgkmcnt(12)
	v_pk_mul_f32 v[96:97], v[4:5], v[90:91]
	v_pk_fma_f32 v[22:23], v[106:107], v[34:35], v[22:23] op_sel_hi:[1,0,1]
	v_pk_fma_f32 v[96:97], v[2:3], v[88:89], v[96:97]
	v_pk_fma_f32 v[94:95], v[206:207], v[28:29], v[22:23]
	v_pk_mul_f32 v[22:23], v[126:127], v[90:91]
	v_pk_mul_f32 v[4:5], v[4:5], v[94:95]
	v_pk_mul_f32 v[24:25], v[126:127], v[94:95]
	v_pk_fma_f32 v[2:3], v[2:3], v[92:93], v[4:5]
	v_add_f32_e32 v4, v96, v97
	v_add_f32_e32 v2, v2, v3
	v_mov_b32_e32 v96, v133
	v_add_f32_dpp v4, v4, v4 row_ror:8 row_mask:0xf bank_mask:0xf bound_ctrl:1
	v_add_f32_dpp v2, v2, v2 row_ror:8 row_mask:0xf bank_mask:0xf bound_ctrl:1
	v_pk_fma_f32 v[22:23], v[124:125], v[88:89], v[22:23]
	v_add_f32_dpp v4, v4, v4 row_ror:4 row_mask:0xf bank_mask:0xf bound_ctrl:1
	v_add_f32_dpp v2, v2, v2 row_ror:4 row_mask:0xf bank_mask:0xf bound_ctrl:1
	v_pk_fma_f32 v[24:25], v[124:125], v[92:93], v[24:25]
	v_add_f32_dpp v4, v4, v4 row_ror:2 row_mask:0xf bank_mask:0xf bound_ctrl:1
	v_add_f32_dpp v2, v2, v2 row_ror:2 row_mask:0xf bank_mask:0xf bound_ctrl:1
	v_add_f32_e32 v22, v22, v23
	v_add_f32_dpp v4, v4, v4 row_ror:1 row_mask:0xf bank_mask:0xf bound_ctrl:1
	v_pk_mul_f32 v[98:99], v[10:11], v[4:5] op_sel_hi:[1,0]
	v_pk_mul_f32 v[4:5], v[12:13], v[4:5] op_sel_hi:[1,0]
	v_add_f32_dpp v2, v2, v2 row_ror:1 row_mask:0xf bank_mask:0xf bound_ctrl:1
	v_pk_fma_f32 v[4:5], v[16:17], v[132:133], v[4:5] op_sel_hi:[1,0,1]
	v_pk_fma_f32 v[98:99], v[14:15], v[132:133], v[98:99] op_sel_hi:[1,0,1]
	s_waitcnt vmcnt(6)
	v_pk_fma_f32 v[90:91], v[210:211], v[90:91], v[4:5]
	v_pk_mul_f32 v[4:5], v[10:11], v[2:3] op_sel_hi:[1,0]
	v_pk_mul_f32 v[2:3], v[12:13], v[2:3] op_sel_hi:[1,0]
	v_pk_fma_f32 v[4:5], v[14:15], v[96:97], v[4:5] op_sel_hi:[1,0,1]
	v_pk_fma_f32 v[2:3], v[16:17], v[96:97], v[2:3] op_sel_hi:[1,0,1]
	v_pk_fma_f32 v[88:89], v[208:209], v[88:89], v[98:99]
	v_pk_fma_f32 v[94:95], v[210:211], v[94:95], v[2:3]
	v_pk_fma_f32 v[92:93], v[208:209], v[92:93], v[4:5]
	s_waitcnt lgkmcnt(10)
	v_pk_mul_f32 v[96:97], v[80:81], v[90:91]
	v_pk_mul_f32 v[80:81], v[80:81], v[94:95]
	v_pk_fma_f32 v[96:97], v[78:79], v[88:89], v[96:97]
	v_pk_fma_f32 v[78:79], v[78:79], v[92:93], v[80:81]
	v_add_f32_e32 v80, v96, v97
	v_add_f32_e32 v78, v78, v79
	s_waitcnt lgkmcnt(6)
	v_mov_b32_e32 v96, v87
	v_add_f32_dpp v80, v80, v80 row_ror:8 row_mask:0xf bank_mask:0xf bound_ctrl:1
	v_add_f32_dpp v78, v78, v78 row_ror:8 row_mask:0xf bank_mask:0xf bound_ctrl:1
	v_pk_mul_f32 v[2:3], v[20:21], v[90:91]
	v_add_f32_dpp v80, v80, v80 row_ror:4 row_mask:0xf bank_mask:0xf bound_ctrl:1
	v_add_f32_dpp v78, v78, v78 row_ror:4 row_mask:0xf bank_mask:0xf bound_ctrl:1
	v_pk_mul_f32 v[4:5], v[20:21], v[94:95]
	v_add_f32_dpp v80, v80, v80 row_ror:2 row_mask:0xf bank_mask:0xf bound_ctrl:1
	v_add_f32_dpp v78, v78, v78 row_ror:2 row_mask:0xf bank_mask:0xf bound_ctrl:1
	v_add_f32_e32 v23, v24, v25
	v_add_f32_dpp v80, v80, v80 row_ror:1 row_mask:0xf bank_mask:0xf bound_ctrl:1
	v_add_f32_dpp v78, v78, v78 row_ror:1 row_mask:0xf bank_mask:0xf bound_ctrl:1
	v_pk_mul_f32 v[98:99], v[70:71], v[80:81] op_sel_hi:[1,0]
	v_pk_mul_f32 v[70:71], v[70:71], v[78:79] op_sel_hi:[1,0]
	v_pk_fma_f32 v[98:99], v[74:75], v[86:87], v[98:99] op_sel_hi:[1,0,1]
	v_pk_fma_f32 v[70:71], v[74:75], v[96:97], v[70:71] op_sel_hi:[1,0,1]
	s_waitcnt vmcnt(5)
	v_pk_fma_f32 v[104:105], v[212:213], v[88:89], v[98:99]
	v_pk_mul_f32 v[80:81], v[72:73], v[80:81] op_sel_hi:[1,0]
	v_pk_fma_f32 v[66:67], v[212:213], v[92:93], v[70:71]
	v_pk_mul_f32 v[70:71], v[72:73], v[78:79] op_sel_hi:[1,0]
	v_pk_fma_f32 v[80:81], v[76:77], v[86:87], v[80:81] op_sel_hi:[1,0,1]
	v_pk_fma_f32 v[70:71], v[76:77], v[96:97], v[70:71] op_sel_hi:[1,0,1]
	v_pk_fma_f32 v[106:107], v[214:215], v[90:91], v[80:81]
	v_pk_fma_f32 v[68:69], v[214:215], v[94:95], v[70:71]
	v_pk_fma_f32 v[2:3], v[18:19], v[88:89], v[2:3]
	v_pk_fma_f32 v[4:5], v[18:19], v[92:93], v[4:5]
	v_pk_mul_f32 v[70:71], v[64:65], v[106:107]
	v_pk_mul_f32 v[64:65], v[64:65], v[68:69]
	ds_write2st64_b32 v113, v22, v23 offset0:24 offset1:25
	v_add_f32_e32 v2, v2, v3
	v_add_f32_e32 v3, v4, v5
	v_pk_fma_f32 v[70:71], v[62:63], v[104:105], v[70:71]
	v_pk_fma_f32 v[62:63], v[62:63], v[66:67], v[64:65]
	ds_read_b128 v[38:41], v118 offset:29440
	global_load_dwordx4 v[204:207], v118, s[56:57]
	s_add_u32 s56, s56, s58
	s_addc_u32 s57, s57, s59
	ds_read_b128 v[30:33], v118 offset:29952
	ds_read_b128 v[34:37], v118 offset:30208
	ds_read_b128 v[22:25], v118 offset:30464
	ds_read2_b32 v[82:83], v120 offset0:224 offset1:228
	ds_write2st64_b32 v113, v2, v3 offset0:32 offset1:33
	v_add_f32_e32 v64, v70, v71
	v_add_f32_e32 v62, v62, v63
	ds_read_b128 v[18:21], v118 offset:30720
	global_load_dwordx4 v[208:211], v118, s[56:57]
	s_add_u32 s56, s56, s58
	s_addc_u32 s57, s57, s59
	ds_read_b128 v[10:13], v118 offset:31232
	ds_read_b128 v[14:17], v118 offset:31488
	ds_read_b128 v[2:5], v118 offset:31744
	ds_write2st64_b32 v113, v64, v62 offset0:40 offset1:41
	s_waitcnt lgkmcnt(12)
	v_pk_mul_f32 v[62:63], v[60:61], v[106:107]
	v_pk_mul_f32 v[60:61], v[60:61], v[68:69]
	v_pk_fma_f32 v[62:63], v[58:59], v[104:105], v[62:63]
	v_pk_fma_f32 v[58:59], v[58:59], v[66:67], v[60:61]
	v_add_f32_e32 v60, v62, v63
	v_add_f32_e32 v58, v58, v59
	v_mov_b32_e32 v62, v85
	v_add_f32_dpp v60, v60, v60 row_ror:8 row_mask:0xf bank_mask:0xf bound_ctrl:1
	v_add_f32_dpp v58, v58, v58 row_ror:8 row_mask:0xf bank_mask:0xf bound_ctrl:1
	ds_read2_b32 v[102:103], v114 offset1:4
	v_add_f32_dpp v60, v60, v60 row_ror:4 row_mask:0xf bank_mask:0xf bound_ctrl:1
	v_add_f32_dpp v58, v58, v58 row_ror:4 row_mask:0xf bank_mask:0xf bound_ctrl:1
	ds_read_b128 v[98:101], v118 offset:32000
	global_load_dwordx4 v[212:215], v118, s[56:57]
	s_add_u32 s56, s56, s58
	s_addc_u32 s57, s57, s59
	ds_read_b128 v[90:93], v118 offset:32512
	ds_read_b128 v[94:97], v118 offset:32768
	ds_read_b128 v[78:81], v118 offset:33024
	ds_read2_b32 v[108:109], v114 offset0:32 offset1:36
	v_add_f32_dpp v60, v60, v60 row_ror:2 row_mask:0xf bank_mask:0xf bound_ctrl:1
	v_add_f32_dpp v58, v58, v58 row_ror:2 row_mask:0xf bank_mask:0xf bound_ctrl:1
	s_nop 0
	v_add_f32_dpp v60, v60, v60 row_ror:1 row_mask:0xf bank_mask:0xf bound_ctrl:1
	v_add_f32_dpp v58, v58, v58 row_ror:1 row_mask:0xf bank_mask:0xf bound_ctrl:1
	v_pk_mul_f32 v[64:65], v[50:51], v[60:61] op_sel_hi:[1,0]
	v_pk_mul_f32 v[50:51], v[50:51], v[58:59] op_sel_hi:[1,0]
	v_pk_fma_f32 v[64:65], v[54:55], v[84:85], v[64:65] op_sel_hi:[1,0,1]
	v_pk_fma_f32 v[50:51], v[54:55], v[62:63], v[50:51] op_sel_hi:[1,0,1]
	s_waitcnt vmcnt(7)
	v_pk_fma_f32 v[104:105], v[216:217], v[104:105], v[64:65]
	v_pk_mul_f32 v[60:61], v[52:53], v[60:61] op_sel_hi:[1,0]
	v_pk_fma_f32 v[54:55], v[216:217], v[66:67], v[50:51]
	v_pk_mul_f32 v[46:47], v[52:53], v[58:59] op_sel_hi:[1,0]
	v_pk_fma_f32 v[60:61], v[56:57], v[84:85], v[60:61] op_sel_hi:[1,0,1]
	v_pk_fma_f32 v[46:47], v[56:57], v[62:63], v[46:47] op_sel_hi:[1,0,1]
	v_pk_fma_f32 v[60:61], v[218:219], v[106:107], v[60:61]
	v_pk_fma_f32 v[56:57], v[218:219], v[68:69], v[46:47]
	s_waitcnt lgkmcnt(12)
	v_pk_mul_f32 v[50:51], v[40:41], v[60:61]
	v_pk_mul_f32 v[40:41], v[40:41], v[56:57]
	v_pk_fma_f32 v[50:51], v[38:39], v[104:105], v[50:51]
	v_pk_fma_f32 v[38:39], v[38:39], v[54:55], v[40:41]
	v_add_f32_e32 v40, v50, v51
	v_add_f32_e32 v38, v38, v39
	v_mov_b32_e32 v58, v83
	v_add_f32_dpp v40, v40, v40 row_ror:8 row_mask:0xf bank_mask:0xf bound_ctrl:1
	v_add_f32_dpp v38, v38, v38 row_ror:8 row_mask:0xf bank_mask:0xf bound_ctrl:1
	v_pk_mul_f32 v[46:47], v[44:45], v[60:61]
	v_add_f32_dpp v40, v40, v40 row_ror:4 row_mask:0xf bank_mask:0xf bound_ctrl:1
	v_add_f32_dpp v38, v38, v38 row_ror:4 row_mask:0xf bank_mask:0xf bound_ctrl:1
	v_pk_mul_f32 v[44:45], v[44:45], v[56:57]
	v_add_f32_dpp v40, v40, v40 row_ror:2 row_mask:0xf bank_mask:0xf bound_ctrl:1
	v_add_f32_dpp v38, v38, v38 row_ror:2 row_mask:0xf bank_mask:0xf bound_ctrl:1
	v_pk_fma_f32 v[46:47], v[42:43], v[104:105], v[46:47]
	v_add_f32_dpp v40, v40, v40 row_ror:1 row_mask:0xf bank_mask:0xf bound_ctrl:1
	v_add_f32_dpp v38, v38, v38 row_ror:1 row_mask:0xf bank_mask:0xf bound_ctrl:1
	v_pk_mul_f32 v[50:51], v[30:31], v[40:41] op_sel_hi:[1,0]
	v_pk_mul_f32 v[30:31], v[30:31], v[38:39] op_sel_hi:[1,0]
	v_pk_fma_f32 v[50:51], v[34:35], v[82:83], v[50:51] op_sel_hi:[1,0,1]
	v_pk_fma_f32 v[30:31], v[34:35], v[58:59], v[30:31] op_sel_hi:[1,0,1]
	s_waitcnt vmcnt(6)
	v_pk_fma_f32 v[50:51], v[220:221], v[104:105], v[50:51]
	v_pk_mul_f32 v[40:41], v[32:33], v[40:41] op_sel_hi:[1,0]
	v_pk_fma_f32 v[26:27], v[220:221], v[54:55], v[30:31]
	v_pk_mul_f32 v[30:31], v[32:33], v[38:39] op_sel_hi:[1,0]
	v_pk_fma_f32 v[40:41], v[36:37], v[82:83], v[40:41] op_sel_hi:[1,0,1]
	v_pk_fma_f32 v[30:31], v[36:37], v[58:59], v[30:31] op_sel_hi:[1,0,1]
	v_pk_fma_f32 v[52:53], v[222:223], v[60:61], v[40:41]
	v_pk_fma_f32 v[28:29], v[222:223], v[56:57], v[30:31]
	v_pk_fma_f32 v[42:43], v[42:43], v[54:55], v[44:45]
	v_pk_mul_f32 v[30:31], v[24:25], v[52:53]
	v_pk_mul_f32 v[24:25], v[24:25], v[28:29]
	v_add_f32_e32 v44, v46, v47
	v_add_f32_e32 v42, v42, v43
	v_pk_fma_f32 v[30:31], v[22:23], v[50:51], v[30:31]
	v_pk_fma_f32 v[22:23], v[22:23], v[26:27], v[24:25]
	ds_write2st64_b32 v113, v44, v42 offset0:48 offset1:49
	v_add_f32_e32 v24, v30, v31
	v_add_f32_e32 v22, v22, v23
	ds_read_b128 v[46:49], v118 offset:33280
	global_load_dwordx4 v[216:219], v118, s[56:57]
	s_add_u32 s56, s56, s58
	s_addc_u32 s57, s57, s59
	ds_read_b128 v[62:65], v118 offset:33792
	ds_read_b128 v[74:77], v118 offset:34048
	ds_read_b128 v[70:73], v118 offset:34304
	ds_read2_b32 v[106:107], v114 offset0:64 offset1:68
	ds_write2st64_b32 v113, v24, v22 offset0:56 offset1:57
	s_waitcnt lgkmcnt(12)
	v_pk_mul_f32 v[22:23], v[20:21], v[52:53]
	v_pk_mul_f32 v[20:21], v[20:21], v[28:29]
	v_pk_fma_f32 v[22:23], v[18:19], v[50:51], v[22:23]
	v_pk_fma_f32 v[18:19], v[18:19], v[26:27], v[20:21]
	v_add_f32_e32 v20, v22, v23
	v_add_f32_e32 v18, v18, v19
	v_mov_b32_e32 v22, v103
	v_add_f32_dpp v20, v20, v20 row_ror:8 row_mask:0xf bank_mask:0xf bound_ctrl:1
	v_add_f32_dpp v18, v18, v18 row_ror:8 row_mask:0xf bank_mask:0xf bound_ctrl:1
	ds_read_b128 v[34:37], v118 offset:34560
	global_load_dwordx4 v[220:223], v118, s[56:57]
	s_add_u32 s56, s56, s58
	s_addc_u32 s57, s57, s59
	ds_read_b128 v[58:61], v118 offset:35072
	ds_read_b128 v[66:69], v118 offset:35328
	ds_read_b128 v[82:85], v118 offset:35584
	ds_read2_b32 v[104:105], v114 offset0:96 offset1:100
	v_add_f32_dpp v20, v20, v20 row_ror:4 row_mask:0xf bank_mask:0xf bound_ctrl:1
	v_add_f32_dpp v18, v18, v18 row_ror:4 row_mask:0xf bank_mask:0xf bound_ctrl:1
	s_nop 0
	v_add_f32_dpp v20, v20, v20 row_ror:2 row_mask:0xf bank_mask:0xf bound_ctrl:1
	v_add_f32_dpp v18, v18, v18 row_ror:2 row_mask:0xf bank_mask:0xf bound_ctrl:1
	s_nop 0
	v_add_f32_dpp v20, v20, v20 row_ror:1 row_mask:0xf bank_mask:0xf bound_ctrl:1
	v_add_f32_dpp v18, v18, v18 row_ror:1 row_mask:0xf bank_mask:0xf bound_ctrl:1
	v_pk_mul_f32 v[24:25], v[10:11], v[20:21] op_sel_hi:[1,0]
	v_pk_mul_f32 v[10:11], v[10:11], v[18:19] op_sel_hi:[1,0]
	v_pk_fma_f32 v[24:25], v[14:15], v[102:103], v[24:25] op_sel_hi:[1,0,1]
	v_pk_fma_f32 v[10:11], v[14:15], v[22:23], v[10:11] op_sel_hi:[1,0,1]
	s_waitcnt vmcnt(7)
	v_pk_fma_f32 v[54:55], v[192:193], v[50:51], v[24:25]
	v_pk_mul_f32 v[20:21], v[12:13], v[20:21] op_sel_hi:[1,0]
	v_pk_fma_f32 v[6:7], v[192:193], v[26:27], v[10:11]
	v_pk_mul_f32 v[10:11], v[12:13], v[18:19] op_sel_hi:[1,0]
	v_pk_fma_f32 v[20:21], v[16:17], v[102:103], v[20:21] op_sel_hi:[1,0,1]
	v_pk_fma_f32 v[10:11], v[16:17], v[22:23], v[10:11] op_sel_hi:[1,0,1]
	v_pk_fma_f32 v[56:57], v[194:195], v[52:53], v[20:21]
	v_pk_fma_f32 v[8:9], v[194:195], v[28:29], v[10:11]
	v_pk_mul_f32 v[10:11], v[4:5], v[56:57]
	v_pk_mul_f32 v[4:5], v[4:5], v[8:9]
	v_pk_fma_f32 v[10:11], v[2:3], v[54:55], v[10:11]
	v_pk_fma_f32 v[2:3], v[2:3], v[6:7], v[4:5]
	v_add_f32_e32 v4, v10, v11
	v_add_f32_e32 v2, v2, v3
	ds_write2st64_b32 v113, v4, v2 offset0:64 offset1:65
	s_waitcnt lgkmcnt(12)
	v_pk_mul_f32 v[2:3], v[100:101], v[56:57]
	v_pk_mul_f32 v[4:5], v[100:101], v[8:9]
	v_pk_fma_f32 v[2:3], v[98:99], v[54:55], v[2:3]
	v_pk_fma_f32 v[4:5], v[98:99], v[6:7], v[4:5]
	v_add_f32_e32 v2, v2, v3
	v_mov_b32_e32 v14, v109
	ds_read_b128 v[50:53], v118 offset:35840
	global_load_dwordx4 v[192:195], v118, s[56:57]
	s_add_u32 s56, s56, s58
	s_addc_u32 s57, s57, s59
	ds_read_b128 v[22:25], v118 offset:36352
	ds_read_b128 v[26:29], v118 offset:36608
	ds_read_b128 v[30:33], v118 offset:36864
	ds_read2_b32 v[102:103], v114 offset0:128 offset1:132
	v_add_f32_dpp v2, v2, v2 row_ror:8 row_mask:0xf bank_mask:0xf bound_ctrl:1
	s_nop 1
	v_add_f32_dpp v2, v2, v2 row_ror:4 row_mask:0xf bank_mask:0xf bound_ctrl:1
	s_nop 1
	v_add_f32_dpp v2, v2, v2 row_ror:2 row_mask:0xf bank_mask:0xf bound_ctrl:1
	s_nop 1
	v_add_f32_dpp v10, v2, v2 row_ror:1 row_mask:0xf bank_mask:0xf bound_ctrl:1
	v_add_f32_e32 v2, v4, v5
	v_pk_mul_f32 v[4:5], v[92:93], v[10:11] op_sel_hi:[1,0]
	s_nop 0
	v_add_f32_dpp v2, v2, v2 row_ror:8 row_mask:0xf bank_mask:0xf bound_ctrl:1
	v_pk_fma_f32 v[4:5], v[96:97], v[108:109], v[4:5] op_sel_hi:[1,0,1]
	s_nop 0
	v_add_f32_dpp v2, v2, v2 row_ror:4 row_mask:0xf bank_mask:0xf bound_ctrl:1
	s_waitcnt vmcnt(7)
	v_pk_fma_f32 v[4:5], v[198:199], v[56:57], v[4:5]
	s_nop 0
	v_add_f32_dpp v2, v2, v2 row_ror:2 row_mask:0xf bank_mask:0xf bound_ctrl:1
	s_nop 1
	v_add_f32_dpp v12, v2, v2 row_ror:1 row_mask:0xf bank_mask:0xf bound_ctrl:1
	v_pk_mul_f32 v[2:3], v[90:91], v[10:11] op_sel_hi:[1,0]
	v_pk_mul_f32 v[10:11], v[90:91], v[12:13] op_sel_hi:[1,0]
	v_pk_fma_f32 v[2:3], v[94:95], v[108:109], v[2:3] op_sel_hi:[1,0,1]
	v_pk_fma_f32 v[10:11], v[94:95], v[14:15], v[10:11] op_sel_hi:[1,0,1]
	v_pk_fma_f32 v[2:3], v[196:197], v[54:55], v[2:3]
	v_pk_fma_f32 v[6:7], v[196:197], v[6:7], v[10:11]
	v_pk_mul_f32 v[10:11], v[92:93], v[12:13] op_sel_hi:[1,0]
	s_nop 0
	v_pk_fma_f32 v[10:11], v[96:97], v[14:15], v[10:11] op_sel_hi:[1,0,1]
	s_waitcnt lgkmcnt(12)
	v_mov_b32_e32 v14, v107
	v_pk_fma_f32 v[8:9], v[198:199], v[8:9], v[10:11]
	v_pk_mul_f32 v[10:11], v[80:81], v[4:5]
	v_pk_mul_f32 v[12:13], v[80:81], v[8:9]
	v_pk_fma_f32 v[10:11], v[78:79], v[2:3], v[10:11]
	v_pk_fma_f32 v[12:13], v[78:79], v[6:7], v[12:13]
	v_add_f32_e32 v10, v10, v11
	v_add_f32_e32 v11, v12, v13
	ds_write2st64_b32 v113, v10, v11 offset0:72 offset1:73
	v_pk_mul_f32 v[10:11], v[48:49], v[4:5]
	v_pk_mul_f32 v[12:13], v[48:49], v[8:9]
	v_pk_fma_f32 v[10:11], v[46:47], v[2:3], v[10:11]
	v_pk_fma_f32 v[12:13], v[46:47], v[6:7], v[12:13]
	v_add_f32_e32 v10, v10, v11
	v_add_f32_e32 v11, v12, v13
	ds_read_b128 v[94:97], v118 offset:37120
	global_load_dwordx4 v[196:199], v118, s[56:57]
	s_add_u32 s56, s56, s58
	s_addc_u32 s57, s57, s59
	ds_read_b128 v[78:81], v118 offset:37632
	ds_read_b128 v[86:89], v118 offset:37888
	ds_read_b128 v[90:93], v118 offset:38144
	ds_read2_b32 v[98:99], v114 offset0:160 offset1:164
	v_add_f32_dpp v10, v10, v10 row_ror:8 row_mask:0xf bank_mask:0xf bound_ctrl:1
	v_add_f32_dpp v11, v11, v11 row_ror:8 row_mask:0xf bank_mask:0xf bound_ctrl:1
	s_nop 0
	v_add_f32_dpp v10, v10, v10 row_ror:4 row_mask:0xf bank_mask:0xf bound_ctrl:1
	v_add_f32_dpp v11, v11, v11 row_ror:4 row_mask:0xf bank_mask:0xf bound_ctrl:1
	s_nop 0
	v_add_f32_dpp v10, v10, v10 row_ror:2 row_mask:0xf bank_mask:0xf bound_ctrl:1
	v_add_f32_dpp v11, v11, v11 row_ror:2 row_mask:0xf bank_mask:0xf bound_ctrl:1
	s_nop 0
	v_add_f32_dpp v10, v10, v10 row_ror:1 row_mask:0xf bank_mask:0xf bound_ctrl:1
	v_add_f32_dpp v12, v11, v11 row_ror:1 row_mask:0xf bank_mask:0xf bound_ctrl:1
	v_pk_mul_f32 v[16:17], v[62:63], v[10:11] op_sel_hi:[1,0]
	v_pk_mul_f32 v[10:11], v[64:65], v[10:11] op_sel_hi:[1,0]
	v_pk_fma_f32 v[16:17], v[74:75], v[106:107], v[16:17] op_sel_hi:[1,0,1]
	v_pk_fma_f32 v[10:11], v[76:77], v[106:107], v[10:11] op_sel_hi:[1,0,1]
	s_waitcnt vmcnt(7)
	v_pk_fma_f32 v[2:3], v[200:201], v[2:3], v[16:17]
	v_pk_fma_f32 v[4:5], v[202:203], v[4:5], v[10:11]
	v_pk_mul_f32 v[10:11], v[62:63], v[12:13] op_sel_hi:[1,0]
	s_nop 0
	v_pk_fma_f32 v[10:11], v[74:75], v[14:15], v[10:11] op_sel_hi:[1,0,1]
	s_nop 0
	v_pk_fma_f32 v[6:7], v[200:201], v[6:7], v[10:11]
	v_pk_mul_f32 v[10:11], v[64:65], v[12:13] op_sel_hi:[1,0]
	s_nop 0
	v_pk_fma_f32 v[10:11], v[76:77], v[14:15], v[10:11] op_sel_hi:[1,0,1]
	s_waitcnt lgkmcnt(12)
	v_mov_b32_e32 v14, v105
	v_pk_fma_f32 v[8:9], v[202:203], v[8:9], v[10:11]
	v_pk_mul_f32 v[10:11], v[72:73], v[4:5]
	v_pk_mul_f32 v[12:13], v[72:73], v[8:9]
	v_pk_fma_f32 v[10:11], v[70:71], v[2:3], v[10:11]
	v_pk_fma_f32 v[12:13], v[70:71], v[6:7], v[12:13]
	v_add_f32_e32 v10, v10, v11
	v_add_f32_e32 v11, v12, v13
	ds_write2st64_b32 v113, v10, v11 offset0:80 offset1:81
	v_pk_mul_f32 v[10:11], v[36:37], v[4:5]
	v_pk_mul_f32 v[12:13], v[36:37], v[8:9]
	v_pk_fma_f32 v[10:11], v[34:35], v[2:3], v[10:11]
	v_pk_fma_f32 v[12:13], v[34:35], v[6:7], v[12:13]
	v_add_f32_e32 v10, v10, v11
	v_add_f32_e32 v11, v12, v13
	ds_read_b128 v[74:77], v118 offset:38400
	global_load_dwordx4 v[200:203], v118, s[56:57]
	s_add_u32 s56, s56, s58
	s_addc_u32 s57, s57, s59
	ds_read_b128 v[46:49], v118 offset:38912
	ds_read_b128 v[62:65], v118 offset:39168
	ds_read_b128 v[70:73], v118 offset:39424
	ds_read2_b32 v[100:101], v114 offset0:192 offset1:196
	v_add_f32_dpp v10, v10, v10 row_ror:8 row_mask:0xf bank_mask:0xf bound_ctrl:1
	v_add_f32_dpp v11, v11, v11 row_ror:8 row_mask:0xf bank_mask:0xf bound_ctrl:1
	s_nop 0
	v_add_f32_dpp v10, v10, v10 row_ror:4 row_mask:0xf bank_mask:0xf bound_ctrl:1
	v_add_f32_dpp v11, v11, v11 row_ror:4 row_mask:0xf bank_mask:0xf bound_ctrl:1
	s_nop 0
	v_add_f32_dpp v10, v10, v10 row_ror:2 row_mask:0xf bank_mask:0xf bound_ctrl:1
	v_add_f32_dpp v11, v11, v11 row_ror:2 row_mask:0xf bank_mask:0xf bound_ctrl:1
	s_nop 0
	v_add_f32_dpp v10, v10, v10 row_ror:1 row_mask:0xf bank_mask:0xf bound_ctrl:1
	v_pk_mul_f32 v[16:17], v[58:59], v[10:11] op_sel_hi:[1,0]
	v_add_f32_dpp v12, v11, v11 row_ror:1 row_mask:0xf bank_mask:0xf bound_ctrl:1
	v_pk_fma_f32 v[16:17], v[66:67], v[104:105], v[16:17] op_sel_hi:[1,0,1]
	s_nop 0
	s_waitcnt vmcnt(7)
	v_pk_fma_f32 v[106:107], v[204:205], v[2:3], v[16:17]
	v_pk_mul_f32 v[2:3], v[60:61], v[10:11] op_sel_hi:[1,0]
	s_nop 0
	v_pk_fma_f32 v[2:3], v[68:69], v[104:105], v[2:3] op_sel_hi:[1,0,1]
	s_nop 0
	v_pk_fma_f32 v[104:105], v[206:207], v[4:5], v[2:3]
	v_pk_mul_f32 v[2:3], v[58:59], v[12:13] op_sel_hi:[1,0]
	s_nop 0
	v_pk_fma_f32 v[2:3], v[66:67], v[14:15], v[2:3] op_sel_hi:[1,0,1]
	s_nop 0
	v_pk_fma_f32 v[58:59], v[204:205], v[6:7], v[2:3]
	v_pk_mul_f32 v[2:3], v[60:61], v[12:13] op_sel_hi:[1,0]
	s_waitcnt lgkmcnt(12)
	v_pk_mul_f32 v[60:61], v[52:53], v[104:105]
	v_pk_fma_f32 v[2:3], v[68:69], v[14:15], v[2:3] op_sel_hi:[1,0,1]
	v_pk_fma_f32 v[60:61], v[50:51], v[106:107], v[60:61]
	v_pk_fma_f32 v[40:41], v[206:207], v[8:9], v[2:3]
	v_pk_mul_f32 v[2:3], v[84:85], v[104:105]
	v_pk_mul_f32 v[52:53], v[52:53], v[40:41]
	v_pk_mul_f32 v[4:5], v[84:85], v[40:41]
	v_pk_fma_f32 v[50:51], v[50:51], v[58:59], v[52:53]
	v_add_f32_e32 v52, v60, v61
	v_add_f32_e32 v50, v50, v51
	v_mov_b32_e32 v60, v103
	v_add_f32_dpp v52, v52, v52 row_ror:8 row_mask:0xf bank_mask:0xf bound_ctrl:1
	v_add_f32_dpp v50, v50, v50 row_ror:8 row_mask:0xf bank_mask:0xf bound_ctrl:1
	v_pk_fma_f32 v[2:3], v[82:83], v[106:107], v[2:3]
	v_add_f32_dpp v52, v52, v52 row_ror:4 row_mask:0xf bank_mask:0xf bound_ctrl:1
	v_add_f32_dpp v50, v50, v50 row_ror:4 row_mask:0xf bank_mask:0xf bound_ctrl:1
	v_pk_fma_f32 v[4:5], v[82:83], v[58:59], v[4:5]
	v_add_f32_dpp v52, v52, v52 row_ror:2 row_mask:0xf bank_mask:0xf bound_ctrl:1
	v_add_f32_dpp v50, v50, v50 row_ror:2 row_mask:0xf bank_mask:0xf bound_ctrl:1
	v_add_f32_e32 v2, v2, v3
	v_add_f32_dpp v52, v52, v52 row_ror:1 row_mask:0xf bank_mask:0xf bound_ctrl:1
	v_add_f32_dpp v50, v50, v50 row_ror:1 row_mask:0xf bank_mask:0xf bound_ctrl:1
	v_pk_mul_f32 v[66:67], v[22:23], v[52:53] op_sel_hi:[1,0]
	v_pk_mul_f32 v[22:23], v[22:23], v[50:51] op_sel_hi:[1,0]
	v_pk_fma_f32 v[66:67], v[26:27], v[102:103], v[66:67] op_sel_hi:[1,0,1]
	v_pk_fma_f32 v[22:23], v[26:27], v[60:61], v[22:23] op_sel_hi:[1,0,1]
	s_waitcnt vmcnt(6)
	v_pk_fma_f32 v[66:67], v[208:209], v[106:107], v[66:67]
	v_pk_mul_f32 v[52:53], v[24:25], v[52:53] op_sel_hi:[1,0]
	v_pk_fma_f32 v[18:19], v[208:209], v[58:59], v[22:23]
	v_pk_mul_f32 v[22:23], v[24:25], v[50:51] op_sel_hi:[1,0]
	v_pk_fma_f32 v[52:53], v[28:29], v[102:103], v[52:53] op_sel_hi:[1,0,1]
	v_pk_fma_f32 v[22:23], v[28:29], v[60:61], v[22:23] op_sel_hi:[1,0,1]
	v_pk_fma_f32 v[52:53], v[210:211], v[104:105], v[52:53]
	v_pk_fma_f32 v[20:21], v[210:211], v[40:41], v[22:23]
	v_pk_mul_f32 v[22:23], v[32:33], v[52:53]
	v_pk_mul_f32 v[24:25], v[32:33], v[20:21]
	v_add_f32_e32 v3, v4, v5
	v_pk_fma_f32 v[22:23], v[30:31], v[66:67], v[22:23]
	v_pk_fma_f32 v[24:25], v[30:31], v[18:19], v[24:25]
	ds_write2st64_b32 v113, v2, v3 offset0:88 offset1:89
	v_add_f32_e32 v22, v22, v23
	v_add_f32_e32 v23, v24, v25
	ds_read_b128 v[34:37], v118 offset:39680
	global_load_dwordx4 v[204:207], v118, s[56:57]
	s_add_u32 s56, s56, s58
	s_addc_u32 s57, s57, s59
	ds_read_b128 v[6:9], v118 offset:40192
	ds_read_b128 v[10:13], v118 offset:40448
	ds_read_b128 v[14:17], v118 offset:40704
	ds_read2_b32 v[38:39], v114 offset0:224 offset1:228
	ds_write2st64_b32 v113, v22, v23 offset0:96 offset1:97
	s_waitcnt lgkmcnt(12)
	v_pk_mul_f32 v[22:23], v[96:97], v[52:53]
	v_pk_mul_f32 v[24:25], v[96:97], v[20:21]
	v_pk_fma_f32 v[22:23], v[94:95], v[66:67], v[22:23]
	v_pk_fma_f32 v[24:25], v[94:95], v[18:19], v[24:25]
	v_add_f32_e32 v22, v22, v23
	v_add_f32_e32 v23, v24, v25
	v_mov_b32_e32 v26, v99
	v_add_f32_dpp v22, v22, v22 row_ror:8 row_mask:0xf bank_mask:0xf bound_ctrl:1
	v_add_f32_dpp v23, v23, v23 row_ror:8 row_mask:0xf bank_mask:0xf bound_ctrl:1
	s_waitcnt lgkmcnt(7)
	v_mov_b32_e32 v32, v101
	v_add_f32_dpp v22, v22, v22 row_ror:4 row_mask:0xf bank_mask:0xf bound_ctrl:1
	v_add_f32_dpp v23, v23, v23 row_ror:4 row_mask:0xf bank_mask:0xf bound_ctrl:1
	s_nop 0
	v_add_f32_dpp v22, v22, v22 row_ror:2 row_mask:0xf bank_mask:0xf bound_ctrl:1
	v_add_f32_dpp v23, v23, v23 row_ror:2 row_mask:0xf bank_mask:0xf bound_ctrl:1
	s_nop 0
	v_add_f32_dpp v22, v22, v22 row_ror:1 row_mask:0xf bank_mask:0xf bound_ctrl:1
	v_add_f32_dpp v24, v23, v23 row_ror:1 row_mask:0xf bank_mask:0xf bound_ctrl:1
	v_pk_mul_f32 v[28:29], v[78:79], v[22:23] op_sel_hi:[1,0]
	v_pk_mul_f32 v[22:23], v[80:81], v[22:23] op_sel_hi:[1,0]
	v_pk_mul_f32 v[30:31], v[78:79], v[24:25] op_sel_hi:[1,0]
	v_pk_mul_f32 v[24:25], v[80:81], v[24:25] op_sel_hi:[1,0]
	v_pk_fma_f32 v[22:23], v[88:89], v[98:99], v[22:23] op_sel_hi:[1,0,1]
	v_pk_fma_f32 v[24:25], v[88:89], v[26:27], v[24:25] op_sel_hi:[1,0,1]
	v_pk_fma_f32 v[28:29], v[86:87], v[98:99], v[28:29] op_sel_hi:[1,0,1]
	s_waitcnt vmcnt(6)
	v_pk_fma_f32 v[22:23], v[214:215], v[52:53], v[22:23]
	v_pk_fma_f32 v[30:31], v[86:87], v[26:27], v[30:31] op_sel_hi:[1,0,1]
	v_pk_fma_f32 v[26:27], v[214:215], v[20:21], v[24:25]
	v_pk_fma_f32 v[28:29], v[212:213], v[66:67], v[28:29]
	v_pk_fma_f32 v[18:19], v[212:213], v[18:19], v[30:31]
	v_pk_mul_f32 v[20:21], v[92:93], v[22:23]
	v_pk_mul_f32 v[24:25], v[92:93], v[26:27]
	v_pk_fma_f32 v[20:21], v[90:91], v[28:29], v[20:21]
	v_pk_fma_f32 v[24:25], v[90:91], v[18:19], v[24:25]
	v_add_f32_e32 v20, v20, v21
	v_add_f32_e32 v21, v24, v25
	ds_write2st64_b32 v113, v20, v21 offset0:104 offset1:105
	ds_read_b32 v249, v246
	v_pk_mul_f32 v[20:21], v[76:77], v[22:23]
	v_pk_mul_f32 v[24:25], v[76:77], v[26:27]
	v_pk_fma_f32 v[20:21], v[74:75], v[28:29], v[20:21]
	v_pk_fma_f32 v[24:25], v[74:75], v[18:19], v[24:25]
	v_add_f32_e32 v20, v20, v21
	v_add_f32_e32 v21, v24, v25
	s_nop 0
	v_add_f32_dpp v20, v20, v20 row_ror:8 row_mask:0xf bank_mask:0xf bound_ctrl:1
	v_add_f32_dpp v21, v21, v21 row_ror:8 row_mask:0xf bank_mask:0xf bound_ctrl:1
	s_nop 0
	v_add_f32_dpp v20, v20, v20 row_ror:4 row_mask:0xf bank_mask:0xf bound_ctrl:1
	v_add_f32_dpp v21, v21, v21 row_ror:4 row_mask:0xf bank_mask:0xf bound_ctrl:1
	s_nop 0
	v_add_f32_dpp v20, v20, v20 row_ror:2 row_mask:0xf bank_mask:0xf bound_ctrl:1
	v_add_f32_dpp v21, v21, v21 row_ror:2 row_mask:0xf bank_mask:0xf bound_ctrl:1
	s_nop 0
	v_add_f32_dpp v20, v20, v20 row_ror:1 row_mask:0xf bank_mask:0xf bound_ctrl:1
	v_add_f32_dpp v30, v21, v21 row_ror:1 row_mask:0xf bank_mask:0xf bound_ctrl:1
	v_pk_mul_f32 v[24:25], v[46:47], v[20:21] op_sel_hi:[1,0]
	v_pk_mul_f32 v[20:21], v[48:49], v[20:21] op_sel_hi:[1,0]
	v_pk_fma_f32 v[24:25], v[62:63], v[100:101], v[24:25] op_sel_hi:[1,0,1]
	v_pk_fma_f32 v[20:21], v[64:65], v[100:101], v[20:21] op_sel_hi:[1,0,1]
	s_waitcnt vmcnt(5)
	v_pk_fma_f32 v[24:25], v[216:217], v[28:29], v[24:25]
	v_pk_fma_f32 v[22:23], v[218:219], v[22:23], v[20:21]
	v_pk_mul_f32 v[20:21], v[46:47], v[30:31] op_sel_hi:[1,0]
	s_nop 0
	v_pk_fma_f32 v[20:21], v[62:63], v[32:33], v[20:21] op_sel_hi:[1,0,1]
	s_nop 0
	v_pk_fma_f32 v[20:21], v[216:217], v[18:19], v[20:21]
	v_pk_mul_f32 v[18:19], v[48:49], v[30:31] op_sel_hi:[1,0]
	s_nop 0
	v_pk_fma_f32 v[18:19], v[64:65], v[32:33], v[18:19] op_sel_hi:[1,0,1]
	s_nop 0
	v_pk_fma_f32 v[18:19], v[218:219], v[26:27], v[18:19]
	v_pk_mul_f32 v[26:27], v[72:73], v[22:23]
	v_pk_mul_f32 v[28:29], v[72:73], v[18:19]
	v_pk_fma_f32 v[26:27], v[70:71], v[24:25], v[26:27]
	v_pk_fma_f32 v[28:29], v[70:71], v[20:21], v[28:29]
	v_add_f32_e32 v26, v26, v27
	v_add_f32_e32 v27, v28, v29
	ds_write2st64_b32 v113, v26, v27 offset0:112 offset1:113
	s_waitcnt lgkmcnt(7)
	v_pk_mul_f32 v[26:27], v[36:37], v[22:23]
	v_pk_mul_f32 v[28:29], v[36:37], v[18:19]
	v_pk_fma_f32 v[26:27], v[34:35], v[24:25], v[26:27]
	v_pk_fma_f32 v[30:31], v[34:35], v[20:21], v[28:29]
	v_add_f32_e32 v26, v26, v27
	s_nop 1
	v_add_f32_dpp v26, v26, v26 row_ror:8 row_mask:0xf bank_mask:0xf bound_ctrl:1
	s_nop 1
	v_add_f32_dpp v26, v26, v26 row_ror:4 row_mask:0xf bank_mask:0xf bound_ctrl:1
	s_nop 1
	v_add_f32_dpp v26, v26, v26 row_ror:2 row_mask:0xf bank_mask:0xf bound_ctrl:1
	s_nop 1
	v_add_f32_dpp v28, v26, v26 row_ror:1 row_mask:0xf bank_mask:0xf bound_ctrl:1
	v_add_f32_e32 v26, v30, v31
	s_waitcnt lgkmcnt(3)
	v_mov_b32_e32 v30, v39
	v_pk_mul_f32 v[32:33], v[6:7], v[28:29] op_sel_hi:[1,0]
	v_add_f32_dpp v26, v26, v26 row_ror:8 row_mask:0xf bank_mask:0xf bound_ctrl:1
	v_pk_fma_f32 v[32:33], v[10:11], v[38:39], v[32:33] op_sel_hi:[1,0,1]
	s_nop 0
	v_add_f32_dpp v26, v26, v26 row_ror:4 row_mask:0xf bank_mask:0xf bound_ctrl:1
	s_waitcnt vmcnt(4)
	v_pk_fma_f32 v[84:85], v[220:221], v[24:25], v[32:33]
	v_pk_mul_f32 v[24:25], v[8:9], v[28:29] op_sel_hi:[1,0]
	v_add_f32_dpp v26, v26, v26 row_ror:2 row_mask:0xf bank_mask:0xf bound_ctrl:1
	v_pk_fma_f32 v[24:25], v[12:13], v[38:39], v[24:25] op_sel_hi:[1,0,1]
	s_nop 0
	v_add_f32_dpp v26, v26, v26 row_ror:1 row_mask:0xf bank_mask:0xf bound_ctrl:1
	v_pk_mul_f32 v[6:7], v[6:7], v[26:27] op_sel_hi:[1,0]
	v_pk_fma_f32 v[86:87], v[222:223], v[22:23], v[24:25]
	v_pk_fma_f32 v[6:7], v[10:11], v[30:31], v[6:7] op_sel_hi:[1,0,1]
	s_nop 0
	v_pk_fma_f32 v[88:89], v[220:221], v[20:21], v[6:7]
	v_pk_mul_f32 v[2:3], v[8:9], v[26:27] op_sel_hi:[1,0]
	s_nop 0
	v_pk_fma_f32 v[2:3], v[12:13], v[30:31], v[2:3] op_sel_hi:[1,0,1]
	s_nop 0
	v_pk_fma_f32 v[92:93], v[222:223], v[18:19], v[2:3]
	v_pk_mul_f32 v[2:3], v[16:17], v[86:87]
	v_pk_mul_f32 v[4:5], v[16:17], v[92:93]
	v_pk_fma_f32 v[2:3], v[14:15], v[84:85], v[2:3]
	v_pk_fma_f32 v[4:5], v[14:15], v[88:89], v[4:5]
	v_add_f32_e32 v2, v2, v3
	v_add_f32_e32 v3, v4, v5
	ds_write2st64_b32 v113, v2, v3 offset0:120 offset1:121
	s_add_i32 s64, s4, 2
	v_mov_b32_e32 v248, s64
	ds_write_b32 v247, v248
	s_waitcnt lgkmcnt(3)
	v_cmp_gt_u32_e32 vcc, s64, v249
	s_nop 0
	s_cbranch_vccnz .Lsflag_slow_2
.Lsflag_go_2:
	ds_read_b128 v[2:5], v118
	global_load_dwordx4 v[208:211], v118, s[56:57]
	s_add_u32 s56, s56, s58
	s_addc_u32 s57, s57, s59
	ds_read_b128 v[22:25], v118 offset:512
	ds_read_b128 v[26:29], v118 offset:768
	ds_read_b128 v[38:41], v118 offset:1024
	ds_read2_b32 v[94:95], v121 offset1:4
	ds_read_b128 v[42:45], v118 offset:1280
	global_load_dwordx4 v[212:215], v118, s[56:57]
	s_add_u32 s56, s56, s58
	s_addc_u32 s57, s57, s59
	ds_read_b128 v[62:65], v118 offset:1792
	ds_read_b128 v[70:73], v118 offset:2048
	ds_read_b128 v[74:77], v118 offset:2304
	ds_read2_b32 v[96:97], v121 offset0:32 offset1:36
	ds_read_b128 v[78:81], v118 offset:2560
	global_load_dwordx4 v[216:219], v118, s[56:57]
	s_add_u32 s56, s56, s58
	s_addc_u32 s57, s57, s59
	ds_read_b128 v[58:61], v118 offset:3072
	ds_read_b128 v[66:69], v118 offset:3328
	ds_read_b128 v[10:13], v118 offset:3584
	ds_read2_b32 v[82:83], v121 offset0:64 offset1:68
	ds_read_b128 v[50:53], v118 offset:3840
	global_load_dwordx4 v[220:223], v118, s[56:57]
	s_add_u32 s56, s56, s58
	s_addc_u32 s57, s57, s59
	ds_read_b128 v[30:33], v118 offset:4352
	ds_read_b128 v[34:37], v118 offset:4608
	ds_read_b128 v[6:9], v118 offset:4864
	ds_read2_b32 v[90:91], v121 offset0:96 offset1:100
	s_waitcnt lgkmcnt(12)
	v_pk_mul_f32 v[98:99], v[4:5], v[86:87]
	v_pk_mul_f32 v[4:5], v[4:5], v[92:93]
	v_pk_fma_f32 v[98:99], v[2:3], v[84:85], v[98:99]
	v_pk_fma_f32 v[2:3], v[2:3], v[88:89], v[4:5]
	v_add_f32_e32 v4, v98, v99
	v_add_f32_e32 v2, v2, v3
	v_mov_b32_e32 v98, v95
	v_add_f32_dpp v4, v4, v4 row_ror:8 row_mask:0xf bank_mask:0xf bound_ctrl:1
	v_add_f32_dpp v2, v2, v2 row_ror:8 row_mask:0xf bank_mask:0xf bound_ctrl:1
	s_nop 0
	v_add_f32_dpp v4, v4, v4 row_ror:4 row_mask:0xf bank_mask:0xf bound_ctrl:1
	v_add_f32_dpp v2, v2, v2 row_ror:4 row_mask:0xf bank_mask:0xf bound_ctrl:1
	s_nop 0
	v_add_f32_dpp v4, v4, v4 row_ror:2 row_mask:0xf bank_mask:0xf bound_ctrl:1
	v_add_f32_dpp v2, v2, v2 row_ror:2 row_mask:0xf bank_mask:0xf bound_ctrl:1
	s_nop 0
	v_add_f32_dpp v4, v4, v4 row_ror:1 row_mask:0xf bank_mask:0xf bound_ctrl:1
	v_pk_mul_f32 v[100:101], v[22:23], v[4:5] op_sel_hi:[1,0]
	v_pk_mul_f32 v[4:5], v[24:25], v[4:5] op_sel_hi:[1,0]
	v_add_f32_dpp v2, v2, v2 row_ror:1 row_mask:0xf bank_mask:0xf bound_ctrl:1
	v_pk_fma_f32 v[4:5], v[28:29], v[94:95], v[4:5] op_sel_hi:[1,0,1]
	v_pk_fma_f32 v[100:101], v[26:27], v[94:95], v[100:101] op_sel_hi:[1,0,1]
	s_waitcnt vmcnt(7)
	v_pk_fma_f32 v[86:87], v[194:195], v[86:87], v[4:5]
	v_pk_mul_f32 v[4:5], v[22:23], v[2:3] op_sel_hi:[1,0]
	v_pk_mul_f32 v[2:3], v[24:25], v[2:3] op_sel_hi:[1,0]
	v_pk_fma_f32 v[84:85], v[192:193], v[84:85], v[100:101]
	v_pk_fma_f32 v[2:3], v[28:29], v[98:99], v[2:3] op_sel_hi:[1,0,1]
	v_pk_fma_f32 v[4:5], v[26:27], v[98:99], v[4:5] op_sel_hi:[1,0,1]
	v_pk_fma_f32 v[92:93], v[194:195], v[92:93], v[2:3]
	v_pk_mul_f32 v[98:99], v[44:45], v[86:87]
	v_pk_fma_f32 v[88:89], v[192:193], v[88:89], v[4:5]
	v_pk_fma_f32 v[98:99], v[42:43], v[84:85], v[98:99]
	v_pk_mul_f32 v[44:45], v[44:45], v[92:93]
	v_pk_mul_f32 v[2:3], v[40:41], v[86:87]
	v_pk_fma_f32 v[42:43], v[42:43], v[88:89], v[44:45]
	v_add_f32_e32 v44, v98, v99
	v_add_f32_e32 v42, v42, v43
	s_waitcnt lgkmcnt(10)
	v_mov_b32_e32 v98, v97
	v_add_f32_dpp v44, v44, v44 row_ror:8 row_mask:0xf bank_mask:0xf bound_ctrl:1
	v_add_f32_dpp v42, v42, v42 row_ror:8 row_mask:0xf bank_mask:0xf bound_ctrl:1
	v_pk_mul_f32 v[4:5], v[40:41], v[92:93]
	v_add_f32_dpp v44, v44, v44 row_ror:4 row_mask:0xf bank_mask:0xf bound_ctrl:1
	v_add_f32_dpp v42, v42, v42 row_ror:4 row_mask:0xf bank_mask:0xf bound_ctrl:1
	v_pk_fma_f32 v[2:3], v[38:39], v[84:85], v[2:3]
	v_add_f32_dpp v44, v44, v44 row_ror:2 row_mask:0xf bank_mask:0xf bound_ctrl:1
	v_add_f32_dpp v42, v42, v42 row_ror:2 row_mask:0xf bank_mask:0xf bound_ctrl:1
	v_pk_fma_f32 v[4:5], v[38:39], v[88:89], v[4:5]
	v_add_f32_dpp v44, v44, v44 row_ror:1 row_mask:0xf bank_mask:0xf bound_ctrl:1
	v_pk_mul_f32 v[100:101], v[62:63], v[44:45] op_sel_hi:[1,0]
	v_pk_mul_f32 v[44:45], v[64:65], v[44:45] op_sel_hi:[1,0]
	v_add_f32_dpp v42, v42, v42 row_ror:1 row_mask:0xf bank_mask:0xf bound_ctrl:1
	v_pk_fma_f32 v[44:45], v[72:73], v[96:97], v[44:45] op_sel_hi:[1,0,1]
	v_pk_fma_f32 v[100:101], v[70:71], v[96:97], v[100:101] op_sel_hi:[1,0,1]
	s_waitcnt vmcnt(6)
	v_pk_fma_f32 v[86:87], v[198:199], v[86:87], v[44:45]
	v_pk_mul_f32 v[44:45], v[62:63], v[42:43] op_sel_hi:[1,0]
	v_pk_mul_f32 v[42:43], v[64:65], v[42:43] op_sel_hi:[1,0]
	v_pk_fma_f32 v[44:45], v[70:71], v[98:99], v[44:45] op_sel_hi:[1,0,1]
	v_pk_fma_f32 v[42:43], v[72:73], v[98:99], v[42:43] op_sel_hi:[1,0,1]
	v_pk_fma_f32 v[84:85], v[196:197], v[84:85], v[100:101]
	v_pk_fma_f32 v[92:93], v[198:199], v[92:93], v[42:43]
	v_pk_fma_f32 v[88:89], v[196:197], v[88:89], v[44:45]
	s_waitcnt lgkmcnt(9)
	v_pk_mul_f32 v[98:99], v[80:81], v[86:87]
	v_pk_mul_f32 v[80:81], v[80:81], v[92:93]
	v_pk_fma_f32 v[98:99], v[78:79], v[84:85], v[98:99]
	v_pk_fma_f32 v[78:79], v[78:79], v[88:89], v[80:81]
	v_add_f32_e32 v80, v98, v99
	v_add_f32_e32 v78, v78, v79
	s_waitcnt lgkmcnt(5)
	v_mov_b32_e32 v98, v83
	v_add_f32_dpp v80, v80, v80 row_ror:8 row_mask:0xf bank_mask:0xf bound_ctrl:1
	v_add_f32_dpp v78, v78, v78 row_ror:8 row_mask:0xf bank_mask:0xf bound_ctrl:1
	v_pk_mul_f32 v[44:45], v[76:77], v[92:93]
	v_add_f32_dpp v80, v80, v80 row_ror:4 row_mask:0xf bank_mask:0xf bound_ctrl:1
	v_add_f32_dpp v78, v78, v78 row_ror:4 row_mask:0xf bank_mask:0xf bound_ctrl:1
	v_add_f32_e32 v2, v2, v3
	v_add_f32_dpp v80, v80, v80 row_ror:2 row_mask:0xf bank_mask:0xf bound_ctrl:1
	v_add_f32_dpp v78, v78, v78 row_ror:2 row_mask:0xf bank_mask:0xf bound_ctrl:1
	v_add_f32_e32 v3, v4, v5
	v_add_f32_dpp v80, v80, v80 row_ror:1 row_mask:0xf bank_mask:0xf bound_ctrl:1
	v_add_f32_dpp v78, v78, v78 row_ror:1 row_mask:0xf bank_mask:0xf bound_ctrl:1
	v_pk_mul_f32 v[100:101], v[58:59], v[80:81] op_sel_hi:[1,0]
	v_pk_mul_f32 v[58:59], v[58:59], v[78:79] op_sel_hi:[1,0]
	v_pk_fma_f32 v[100:101], v[66:67], v[82:83], v[100:101] op_sel_hi:[1,0,1]
	v_pk_fma_f32 v[58:59], v[66:67], v[98:99], v[58:59] op_sel_hi:[1,0,1]
	s_waitcnt vmcnt(5)
	v_pk_fma_f32 v[100:101], v[200:201], v[84:85], v[100:101]
	v_pk_mul_f32 v[80:81], v[60:61], v[80:81] op_sel_hi:[1,0]
	v_pk_fma_f32 v[66:67], v[200:201], v[88:89], v[58:59]
	v_pk_mul_f32 v[46:47], v[60:61], v[78:79] op_sel_hi:[1,0]
	v_pk_fma_f32 v[80:81], v[68:69], v[82:83], v[80:81] op_sel_hi:[1,0,1]
	v_pk_fma_f32 v[46:47], v[68:69], v[98:99], v[46:47] op_sel_hi:[1,0,1]
	v_pk_fma_f32 v[80:81], v[202:203], v[86:87], v[80:81]
	v_pk_fma_f32 v[68:69], v[202:203], v[92:93], v[46:47]
	s_waitcnt lgkmcnt(4)
	v_pk_mul_f32 v[78:79], v[52:53], v[80:81]
	v_pk_mul_f32 v[52:53], v[52:53], v[68:69]
	v_pk_fma_f32 v[78:79], v[50:51], v[100:101], v[78:79]
	v_pk_fma_f32 v[50:51], v[50:51], v[66:67], v[52:53]
	v_add_f32_e32 v52, v78, v79
	v_add_f32_e32 v50, v50, v51
	s_waitcnt lgkmcnt(0)
	v_mov_b32_e32 v78, v91
	v_add_f32_dpp v52, v52, v52 row_ror:8 row_mask:0xf bank_mask:0xf bound_ctrl:1
	v_add_f32_dpp v50, v50, v50 row_ror:8 row_mask:0xf bank_mask:0xf bound_ctrl:1
	v_pk_mul_f32 v[46:47], v[12:13], v[80:81]
	v_add_f32_dpp v52, v52, v52 row_ror:4 row_mask:0xf bank_mask:0xf bound_ctrl:1
	v_add_f32_dpp v50, v50, v50 row_ror:4 row_mask:0xf bank_mask:0xf bound_ctrl:1
	v_pk_fma_f32 v[46:47], v[10:11], v[100:101], v[46:47]
	v_add_f32_dpp v52, v52, v52 row_ror:2 row_mask:0xf bank_mask:0xf bound_ctrl:1
	v_add_f32_dpp v50, v50, v50 row_ror:2 row_mask:0xf bank_mask:0xf bound_ctrl:1
	ds_write2st64_b32 v111, v2, v3 offset0:176 offset1:177
	v_add_f32_dpp v52, v52, v52 row_ror:1 row_mask:0xf bank_mask:0xf bound_ctrl:1
	v_add_f32_dpp v50, v50, v50 row_ror:1 row_mask:0xf bank_mask:0xf bound_ctrl:1
	v_pk_mul_f32 v[92:93], v[30:31], v[52:53] op_sel_hi:[1,0]
	v_pk_mul_f32 v[30:31], v[30:31], v[50:51] op_sel_hi:[1,0]
	v_pk_fma_f32 v[92:93], v[34:35], v[90:91], v[92:93] op_sel_hi:[1,0,1]
	v_pk_fma_f32 v[30:31], v[34:35], v[78:79], v[30:31] op_sel_hi:[1,0,1]
	s_waitcnt vmcnt(4)
	v_pk_fma_f32 v[100:101], v[204:205], v[100:101], v[92:93]
	v_pk_mul_f32 v[52:53], v[32:33], v[52:53] op_sel_hi:[1,0]
	v_pk_fma_f32 v[30:31], v[204:205], v[66:67], v[30:31]
	v_pk_mul_f32 v[14:15], v[32:33], v[50:51] op_sel_hi:[1,0]
	v_pk_fma_f32 v[52:53], v[36:37], v[90:91], v[52:53] op_sel_hi:[1,0,1]
	v_pk_fma_f32 v[14:15], v[36:37], v[78:79], v[14:15] op_sel_hi:[1,0,1]
	ds_read_b128 v[38:41], v118 offset:5120
	global_load_dwordx4 v[192:195], v118, s[56:57]
	s_add_u32 s56, s56, s58
	s_addc_u32 s57, s57, s59
	ds_read_b128 v[22:25], v118 offset:5632
	ds_read_b128 v[26:29], v118 offset:5888
	ds_read_b128 v[2:5], v118 offset:6144
	ds_read2_b32 v[94:95], v121 offset0:128 offset1:132
	v_pk_fma_f32 v[80:81], v[206:207], v[80:81], v[52:53]
	v_pk_fma_f32 v[32:33], v[206:207], v[68:69], v[14:15]
	s_waitcnt lgkmcnt(4)
	v_pk_mul_f32 v[78:79], v[40:41], v[80:81]
	v_pk_mul_f32 v[40:41], v[40:41], v[32:33]
	v_pk_fma_f32 v[78:79], v[38:39], v[100:101], v[78:79]
	v_pk_fma_f32 v[38:39], v[38:39], v[30:31], v[40:41]
	v_add_f32_e32 v40, v78, v79
	v_add_f32_e32 v38, v38, v39
	s_waitcnt lgkmcnt(0)
	v_mov_b32_e32 v78, v95
	v_add_f32_dpp v40, v40, v40 row_ror:8 row_mask:0xf bank_mask:0xf bound_ctrl:1
	v_add_f32_dpp v38, v38, v38 row_ror:8 row_mask:0xf bank_mask:0xf bound_ctrl:1
	v_pk_mul_f32 v[14:15], v[8:9], v[80:81]
	v_add_f32_dpp v40, v40, v40 row_ror:4 row_mask:0xf bank_mask:0xf bound_ctrl:1
	v_add_f32_dpp v38, v38, v38 row_ror:4 row_mask:0xf bank_mask:0xf bound_ctrl:1
	v_pk_mul_f32 v[42:43], v[76:77], v[86:87]
	v_add_f32_dpp v40, v40, v40 row_ror:2 row_mask:0xf bank_mask:0xf bound_ctrl:1
	v_add_f32_dpp v38, v38, v38 row_ror:2 row_mask:0xf bank_mask:0xf bound_ctrl:1
	v_pk_fma_f32 v[14:15], v[6:7], v[100:101], v[14:15]
	v_add_f32_dpp v40, v40, v40 row_ror:1 row_mask:0xf bank_mask:0xf bound_ctrl:1
	v_add_f32_dpp v38, v38, v38 row_ror:1 row_mask:0xf bank_mask:0xf bound_ctrl:1
	v_pk_mul_f32 v[90:91], v[22:23], v[40:41] op_sel_hi:[1,0]
	v_pk_mul_f32 v[22:23], v[22:23], v[38:39] op_sel_hi:[1,0]
	v_pk_fma_f32 v[90:91], v[26:27], v[94:95], v[90:91] op_sel_hi:[1,0,1]
	v_pk_mul_f32 v[40:41], v[24:25], v[40:41] op_sel_hi:[1,0]
	v_pk_fma_f32 v[22:23], v[26:27], v[78:79], v[22:23] op_sel_hi:[1,0,1]
	s_waitcnt vmcnt(4)
	v_pk_fma_f32 v[100:101], v[208:209], v[100:101], v[90:91]
	v_pk_fma_f32 v[40:41], v[28:29], v[94:95], v[40:41] op_sel_hi:[1,0,1]
	v_pk_fma_f32 v[94:95], v[208:209], v[30:31], v[22:23]
	v_pk_mul_f32 v[18:19], v[24:25], v[38:39] op_sel_hi:[1,0]
	v_pk_fma_f32 v[42:43], v[74:75], v[84:85], v[42:43]
	v_pk_fma_f32 v[44:45], v[74:75], v[88:89], v[44:45]
	v_pk_mul_f32 v[12:13], v[12:13], v[68:69]
	v_pk_fma_f32 v[18:19], v[28:29], v[78:79], v[18:19] op_sel_hi:[1,0,1]
	v_add_f32_e32 v42, v42, v43
	v_add_f32_e32 v43, v44, v45
	v_pk_fma_f32 v[10:11], v[10:11], v[66:67], v[12:13]
	v_pk_mul_f32 v[8:9], v[8:9], v[32:33]
	v_pk_fma_f32 v[80:81], v[210:211], v[80:81], v[40:41]
	v_pk_fma_f32 v[78:79], v[210:211], v[32:33], v[18:19]
	ds_write2st64_b32 v111, v42, v43 offset0:184 offset1:185
	v_add_f32_e32 v12, v46, v47
	v_add_f32_e32 v10, v10, v11
	v_pk_fma_f32 v[6:7], v[6:7], v[30:31], v[8:9]
	v_pk_mul_f32 v[18:19], v[4:5], v[80:81]
	v_pk_mul_f32 v[4:5], v[4:5], v[78:79]
	ds_read_b128 v[74:77], v118 offset:6400
	global_load_dwordx4 v[196:199], v118, s[56:57]
	s_add_u32 s56, s56, s58
	s_addc_u32 s57, s57, s59
	ds_read_b128 v[62:65], v118 offset:6912
	ds_read_b128 v[70:73], v118 offset:7168
	ds_read_b128 v[42:45], v118 offset:7424
	ds_read2_b32 v[96:97], v121 offset0:160 offset1:164
	ds_write2st64_b32 v111, v12, v10 offset0:192 offset1:193
	v_add_f32_e32 v8, v14, v15
	v_add_f32_e32 v6, v6, v7
	v_pk_fma_f32 v[18:19], v[2:3], v[100:101], v[18:19]
	v_pk_fma_f32 v[2:3], v[2:3], v[94:95], v[4:5]
	ds_read_b128 v[86:89], v118 offset:7680
	global_load_dwordx4 v[200:203], v118, s[56:57]
	s_add_u32 s56, s56, s58
	s_addc_u32 s57, s57, s59
	ds_read_b128 v[58:61], v118 offset:8192
	ds_read_b128 v[82:85], v118 offset:8448
	ds_read_b128 v[10:13], v118 offset:8704
	ds_read2_b32 v[98:99], v121 offset0:192 offset1:196
	ds_write2st64_b32 v111, v8, v6 offset0:200 offset1:201
	v_add_f32_e32 v4, v18, v19
	v_add_f32_e32 v2, v2, v3
	ds_read_b128 v[66:69], v118 offset:8960
	global_load_dwordx4 v[204:207], v118, s[56:57]
	s_add_u32 s56, s56, s58
	s_addc_u32 s57, s57, s59
	ds_read_b128 v[34:37], v118 offset:9472
	ds_read_b128 v[50:53], v118 offset:9728
	ds_read_b128 v[6:9], v118 offset:9984
	ds_read2_b32 v[92:93], v121 offset0:224 offset1:228
	ds_write2st64_b32 v111, v4, v2 offset0:208 offset1:209
	s_waitcnt lgkmcnt(12)
	v_pk_mul_f32 v[2:3], v[76:77], v[80:81]
	v_pk_mul_f32 v[4:5], v[76:77], v[78:79]
	v_pk_fma_f32 v[2:3], v[74:75], v[100:101], v[2:3]
	v_pk_fma_f32 v[4:5], v[74:75], v[94:95], v[4:5]
	v_add_f32_e32 v2, v2, v3
	v_add_f32_e32 v3, v4, v5
	v_mov_b32_e32 v74, v97
	v_add_f32_dpp v2, v2, v2 row_ror:8 row_mask:0xf bank_mask:0xf bound_ctrl:1
	v_add_f32_dpp v3, v3, v3 row_ror:8 row_mask:0xf bank_mask:0xf bound_ctrl:1
	s_waitcnt lgkmcnt(1)
	v_mov_b32_e32 v104, v93
	v_add_f32_dpp v2, v2, v2 row_ror:4 row_mask:0xf bank_mask:0xf bound_ctrl:1
	v_add_f32_dpp v3, v3, v3 row_ror:4 row_mask:0xf bank_mask:0xf bound_ctrl:1
	ds_read_b128 v[38:41], v118 offset:10240
	global_load_dwordx4 v[208:211], v118, s[56:57]
	s_add_u32 s56, s56, s58
	s_addc_u32 s57, s57, s59
	ds_read_b128 v[26:29], v118 offset:10752
	ds_read_b128 v[30:33], v118 offset:11008
	ds_read_b128 v[18:21], v118 offset:11264
	ds_read2_b32 v[90:91], v117 offset1:4
	v_add_f32_dpp v2, v2, v2 row_ror:2 row_mask:0xf bank_mask:0xf bound_ctrl:1
	v_add_f32_dpp v3, v3, v3 row_ror:2 row_mask:0xf bank_mask:0xf bound_ctrl:1
	s_nop 0
	v_add_f32_dpp v2, v2, v2 row_ror:1 row_mask:0xf bank_mask:0xf bound_ctrl:1
	v_add_f32_dpp v4, v3, v3 row_ror:1 row_mask:0xf bank_mask:0xf bound_ctrl:1
	v_pk_mul_f32 v[76:77], v[62:63], v[2:3] op_sel_hi:[1,0]
	v_pk_mul_f32 v[2:3], v[64:65], v[2:3] op_sel_hi:[1,0]
	v_pk_mul_f32 v[62:63], v[62:63], v[4:5] op_sel_hi:[1,0]
	v_pk_fma_f32 v[2:3], v[72:73], v[96:97], v[2:3] op_sel_hi:[1,0,1]
	v_pk_mul_f32 v[4:5], v[64:65], v[4:5] op_sel_hi:[1,0]
	v_pk_fma_f32 v[76:77], v[70:71], v[96:97], v[76:77] op_sel_hi:[1,0,1]
	s_waitcnt vmcnt(7)
	v_pk_fma_f32 v[2:3], v[214:215], v[80:81], v[2:3]
	v_pk_fma_f32 v[4:5], v[72:73], v[74:75], v[4:5] op_sel_hi:[1,0,1]
	v_pk_fma_f32 v[100:101], v[212:213], v[100:101], v[76:77]
	v_pk_fma_f32 v[62:63], v[70:71], v[74:75], v[62:63] op_sel_hi:[1,0,1]
	v_pk_fma_f32 v[4:5], v[214:215], v[78:79], v[4:5]
	v_pk_mul_f32 v[56:57], v[44:45], v[2:3]
	v_pk_fma_f32 v[54:55], v[212:213], v[94:95], v[62:63]
	v_pk_fma_f32 v[56:57], v[42:43], v[100:101], v[56:57]
	v_pk_mul_f32 v[44:45], v[44:45], v[4:5]
	s_nop 0
	v_pk_fma_f32 v[42:43], v[42:43], v[54:55], v[44:45]
	v_add_f32_e32 v44, v56, v57
	v_pk_mul_f32 v[56:57], v[88:89], v[2:3]
	v_pk_mul_f32 v[88:89], v[88:89], v[4:5]
	v_pk_fma_f32 v[56:57], v[86:87], v[100:101], v[56:57]
	v_pk_fma_f32 v[86:87], v[86:87], v[54:55], v[88:89]
	v_add_f32_e32 v56, v56, v57
	v_add_f32_e32 v57, v86, v87
	v_mov_b32_e32 v88, v99
	v_add_f32_dpp v56, v56, v56 row_ror:8 row_mask:0xf bank_mask:0xf bound_ctrl:1
	v_add_f32_dpp v57, v57, v57 row_ror:8 row_mask:0xf bank_mask:0xf bound_ctrl:1
	v_add_f32_e32 v42, v42, v43
	v_add_f32_dpp v56, v56, v56 row_ror:4 row_mask:0xf bank_mask:0xf bound_ctrl:1
	v_add_f32_dpp v57, v57, v57 row_ror:4 row_mask:0xf bank_mask:0xf bound_ctrl:1
	ds_write2st64_b32 v111, v44, v42 offset0:216 offset1:217
	v_add_f32_dpp v56, v56, v56 row_ror:2 row_mask:0xf bank_mask:0xf bound_ctrl:1
	v_add_f32_dpp v57, v57, v57 row_ror:2 row_mask:0xf bank_mask:0xf bound_ctrl:1
	ds_read_b128 v[78:81], v118 offset:11520
	global_load_dwordx4 v[212:215], v118, s[56:57]
	s_add_u32 s56, s56, s58
	s_addc_u32 s57, s57, s59
	ds_read_b128 v[70:73], v118 offset:12032
	ds_read_b128 v[74:77], v118 offset:12288
	ds_read_b128 v[42:45], v118 offset:12544
	ds_read2_b32 v[94:95], v117 offset0:32 offset1:36
	v_add_f32_dpp v56, v56, v56 row_ror:1 row_mask:0xf bank_mask:0xf bound_ctrl:1
	v_add_f32_dpp v86, v57, v57 row_ror:1 row_mask:0xf bank_mask:0xf bound_ctrl:1
	v_pk_mul_f32 v[96:97], v[58:59], v[56:57] op_sel_hi:[1,0]
	v_pk_mul_f32 v[56:57], v[60:61], v[56:57] op_sel_hi:[1,0]
	v_pk_fma_f32 v[96:97], v[82:83], v[98:99], v[96:97] op_sel_hi:[1,0,1]
	v_pk_fma_f32 v[56:57], v[84:85], v[98:99], v[56:57] op_sel_hi:[1,0,1]
	s_waitcnt vmcnt(7)
	v_pk_fma_f32 v[96:97], v[216:217], v[100:101], v[96:97]
	v_pk_fma_f32 v[98:99], v[218:219], v[2:3], v[56:57]
	v_pk_mul_f32 v[2:3], v[58:59], v[86:87] op_sel_hi:[1,0]
	s_nop 0
	v_pk_fma_f32 v[2:3], v[82:83], v[88:89], v[2:3] op_sel_hi:[1,0,1]
	s_nop 0
	v_pk_fma_f32 v[100:101], v[216:217], v[54:55], v[2:3]
	v_pk_mul_f32 v[2:3], v[60:61], v[86:87] op_sel_hi:[1,0]
	s_nop 0
	v_pk_fma_f32 v[2:3], v[84:85], v[88:89], v[2:3] op_sel_hi:[1,0,1]
	v_pk_mul_f32 v[84:85], v[68:69], v[98:99]
	v_pk_fma_f32 v[102:103], v[218:219], v[4:5], v[2:3]
	v_pk_fma_f32 v[84:85], v[66:67], v[96:97], v[84:85]
	v_pk_mul_f32 v[68:69], v[68:69], v[102:103]
	v_pk_mul_f32 v[2:3], v[12:13], v[98:99]
	v_pk_fma_f32 v[66:67], v[66:67], v[100:101], v[68:69]
	v_add_f32_e32 v68, v84, v85
	v_add_f32_e32 v66, v66, v67
	v_pk_fma_f32 v[2:3], v[10:11], v[96:97], v[2:3]
	v_add_f32_dpp v68, v68, v68 row_ror:8 row_mask:0xf bank_mask:0xf bound_ctrl:1
	v_add_f32_dpp v66, v66, v66 row_ror:8 row_mask:0xf bank_mask:0xf bound_ctrl:1
	v_pk_mul_f32 v[4:5], v[12:13], v[102:103]
	v_add_f32_dpp v68, v68, v68 row_ror:4 row_mask:0xf bank_mask:0xf bound_ctrl:1
	v_add_f32_dpp v66, v66, v66 row_ror:4 row_mask:0xf bank_mask:0xf bound_ctrl:1
	v_pk_fma_f32 v[4:5], v[10:11], v[100:101], v[4:5]
	v_add_f32_dpp v68, v68, v68 row_ror:2 row_mask:0xf bank_mask:0xf bound_ctrl:1
	v_add_f32_dpp v66, v66, v66 row_ror:2 row_mask:0xf bank_mask:0xf bound_ctrl:1
	v_add_f32_e32 v2, v2, v3
	v_add_f32_dpp v68, v68, v68 row_ror:1 row_mask:0xf bank_mask:0xf bound_ctrl:1
	v_add_f32_dpp v66, v66, v66 row_ror:1 row_mask:0xf bank_mask:0xf bound_ctrl:1
	v_pk_mul_f32 v[84:85], v[34:35], v[68:69] op_sel_hi:[1,0]
	v_pk_mul_f32 v[34:35], v[34:35], v[66:67] op_sel_hi:[1,0]
	v_pk_fma_f32 v[84:85], v[50:51], v[92:93], v[84:85] op_sel_hi:[1,0,1]
	v_pk_fma_f32 v[34:35], v[50:51], v[104:105], v[34:35] op_sel_hi:[1,0,1]
	s_waitcnt vmcnt(6)
	v_pk_fma_f32 v[84:85], v[220:221], v[96:97], v[84:85]
	v_pk_mul_f32 v[68:69], v[36:37], v[68:69] op_sel_hi:[1,0]
	v_pk_fma_f32 v[88:89], v[220:221], v[100:101], v[34:35]
	v_pk_mul_f32 v[14:15], v[36:37], v[66:67] op_sel_hi:[1,0]
	v_pk_fma_f32 v[68:69], v[52:53], v[92:93], v[68:69] op_sel_hi:[1,0,1]
	v_pk_fma_f32 v[14:15], v[52:53], v[104:105], v[14:15] op_sel_hi:[1,0,1]
	v_pk_fma_f32 v[86:87], v[222:223], v[98:99], v[68:69]
	v_pk_fma_f32 v[96:97], v[222:223], v[102:103], v[14:15]
	s_waitcnt lgkmcnt(10)
	v_pk_mul_f32 v[98:99], v[40:41], v[86:87]
	v_pk_mul_f32 v[40:41], v[40:41], v[96:97]
	v_pk_fma_f32 v[98:99], v[38:39], v[84:85], v[98:99]
	v_pk_fma_f32 v[38:39], v[38:39], v[88:89], v[40:41]
	v_add_f32_e32 v40, v98, v99
	v_add_f32_e32 v38, v38, v39
	s_waitcnt lgkmcnt(6)
	v_mov_b32_e32 v98, v91
	v_add_f32_dpp v40, v40, v40 row_ror:8 row_mask:0xf bank_mask:0xf bound_ctrl:1
	v_add_f32_dpp v38, v38, v38 row_ror:8 row_mask:0xf bank_mask:0xf bound_ctrl:1
	v_pk_mul_f32 v[14:15], v[8:9], v[86:87]
	v_add_f32_dpp v40, v40, v40 row_ror:4 row_mask:0xf bank_mask:0xf bound_ctrl:1
	v_add_f32_dpp v38, v38, v38 row_ror:4 row_mask:0xf bank_mask:0xf bound_ctrl:1
	v_pk_mul_f32 v[8:9], v[8:9], v[96:97]
	v_add_f32_dpp v40, v40, v40 row_ror:2 row_mask:0xf bank_mask:0xf bound_ctrl:1
	v_add_f32_dpp v38, v38, v38 row_ror:2 row_mask:0xf bank_mask:0xf bound_ctrl:1
	v_pk_fma_f32 v[14:15], v[6:7], v[84:85], v[14:15]
	v_add_f32_dpp v40, v40, v40 row_ror:1 row_mask:0xf bank_mask:0xf bound_ctrl:1
	v_add_f32_dpp v38, v38, v38 row_ror:1 row_mask:0xf bank_mask:0xf bound_ctrl:1
	v_pk_mul_f32 v[100:101], v[26:27], v[40:41] op_sel_hi:[1,0]
	v_pk_mul_f32 v[26:27], v[26:27], v[38:39] op_sel_hi:[1,0]
	v_pk_fma_f32 v[100:101], v[30:31], v[90:91], v[100:101] op_sel_hi:[1,0,1]
	v_pk_fma_f32 v[26:27], v[30:31], v[98:99], v[26:27] op_sel_hi:[1,0,1]
	v_pk_fma_f32 v[6:7], v[6:7], v[88:89], v[8:9]
	s_waitcnt vmcnt(5)
	v_pk_fma_f32 v[84:85], v[192:193], v[84:85], v[100:101]
	v_pk_mul_f32 v[40:41], v[28:29], v[40:41] op_sel_hi:[1,0]
	v_pk_fma_f32 v[88:89], v[192:193], v[88:89], v[26:27]
	v_pk_mul_f32 v[22:23], v[28:29], v[38:39] op_sel_hi:[1,0]
	v_pk_fma_f32 v[40:41], v[32:33], v[90:91], v[40:41] op_sel_hi:[1,0,1]
	v_pk_fma_f32 v[22:23], v[32:33], v[98:99], v[22:23] op_sel_hi:[1,0,1]
	v_pk_fma_f32 v[86:87], v[194:195], v[86:87], v[40:41]
	v_pk_fma_f32 v[96:97], v[194:195], v[96:97], v[22:23]
	s_waitcnt lgkmcnt(4)
	v_pk_mul_f32 v[98:99], v[80:81], v[86:87]
	v_pk_mul_f32 v[80:81], v[80:81], v[96:97]
	v_pk_fma_f32 v[98:99], v[78:79], v[84:85], v[98:99]
	v_pk_fma_f32 v[78:79], v[78:79], v[88:89], v[80:81]
	v_add_f32_e32 v80, v98, v99
	v_add_f32_e32 v78, v78, v79
	s_waitcnt lgkmcnt(0)
	v_mov_b32_e32 v98, v95
	v_add_f32_dpp v80, v80, v80 row_ror:8 row_mask:0xf bank_mask:0xf bound_ctrl:1
	v_add_f32_dpp v78, v78, v78 row_ror:8 row_mask:0xf bank_mask:0xf bound_ctrl:1
	v_pk_mul_f32 v[22:23], v[20:21], v[86:87]
	v_add_f32_dpp v80, v80, v80 row_ror:4 row_mask:0xf bank_mask:0xf bound_ctrl:1
	v_add_f32_dpp v78, v78, v78 row_ror:4 row_mask:0xf bank_mask:0xf bound_ctrl:1
	v_pk_mul_f32 v[20:21], v[20:21], v[96:97]
	v_add_f32_dpp v80, v80, v80 row_ror:2 row_mask:0xf bank_mask:0xf bound_ctrl:1
	v_add_f32_dpp v78, v78, v78 row_ror:2 row_mask:0xf bank_mask:0xf bound_ctrl:1
	v_add_f32_e32 v3, v4, v5
	v_add_f32_dpp v80, v80, v80 row_ror:1 row_mask:0xf bank_mask:0xf bound_ctrl:1
	v_add_f32_dpp v78, v78, v78 row_ror:1 row_mask:0xf bank_mask:0xf bound_ctrl:1
	v_pk_mul_f32 v[100:101], v[70:71], v[80:81] op_sel_hi:[1,0]
	v_pk_mul_f32 v[70:71], v[70:71], v[78:79] op_sel_hi:[1,0]
	v_pk_fma_f32 v[100:101], v[74:75], v[94:95], v[100:101] op_sel_hi:[1,0,1]
	v_pk_fma_f32 v[70:71], v[74:75], v[98:99], v[70:71] op_sel_hi:[1,0,1]
	v_pk_fma_f32 v[22:23], v[18:19], v[84:85], v[22:23]
	v_pk_fma_f32 v[18:19], v[18:19], v[88:89], v[20:21]
	s_waitcnt vmcnt(4)
	v_pk_fma_f32 v[84:85], v[196:197], v[84:85], v[100:101]
	v_pk_mul_f32 v[80:81], v[72:73], v[80:81] op_sel_hi:[1,0]
	v_pk_fma_f32 v[88:89], v[196:197], v[88:89], v[70:71]
	v_pk_mul_f32 v[62:63], v[72:73], v[78:79] op_sel_hi:[1,0]
	ds_write2st64_b32 v111, v2, v3 offset0:224 offset1:225
	v_pk_fma_f32 v[80:81], v[76:77], v[94:95], v[80:81] op_sel_hi:[1,0,1]
	v_pk_fma_f32 v[62:63], v[76:77], v[98:99], v[62:63] op_sel_hi:[1,0,1]
	ds_read_b128 v[10:13], v118 offset:12800
	global_load_dwordx4 v[216:219], v118, s[56:57]
	s_add_u32 s56, s56, s58
	s_addc_u32 s57, s57, s59
	ds_read_b128 v[46:49], v118 offset:13312
	ds_read_b128 v[58:61], v118 offset:13568
	ds_read_b128 v[54:57], v118 offset:13824
	ds_read2_b32 v[82:83], v117 offset0:64 offset1:68
	v_pk_fma_f32 v[86:87], v[198:199], v[86:87], v[80:81]
	v_pk_fma_f32 v[96:97], v[198:199], v[96:97], v[62:63]
	s_waitcnt lgkmcnt(4)
	v_pk_mul_f32 v[98:99], v[12:13], v[86:87]
	v_pk_mul_f32 v[12:13], v[12:13], v[96:97]
	v_pk_fma_f32 v[98:99], v[10:11], v[84:85], v[98:99]
	v_pk_fma_f32 v[10:11], v[10:11], v[88:89], v[12:13]
	v_add_f32_e32 v12, v98, v99
	v_add_f32_e32 v10, v10, v11
	s_waitcnt lgkmcnt(0)
	v_mov_b32_e32 v100, v83
	v_add_f32_dpp v12, v12, v12 row_ror:8 row_mask:0xf bank_mask:0xf bound_ctrl:1
	v_add_f32_dpp v10, v10, v10 row_ror:8 row_mask:0xf bank_mask:0xf bound_ctrl:1
	v_add_f32_e32 v8, v14, v15
	v_add_f32_dpp v12, v12, v12 row_ror:4 row_mask:0xf bank_mask:0xf bound_ctrl:1
	v_add_f32_dpp v10, v10, v10 row_ror:4 row_mask:0xf bank_mask:0xf bound_ctrl:1
	v_add_f32_e32 v6, v6, v7
	v_add_f32_dpp v12, v12, v12 row_ror:2 row_mask:0xf bank_mask:0xf bound_ctrl:1
	v_add_f32_dpp v10, v10, v10 row_ror:2 row_mask:0xf bank_mask:0xf bound_ctrl:1
	ds_write2st64_b32 v111, v8, v6 offset0:232 offset1:233
	v_add_f32_dpp v12, v12, v12 row_ror:1 row_mask:0xf bank_mask:0xf bound_ctrl:1
	v_add_f32_dpp v98, v10, v10 row_ror:1 row_mask:0xf bank_mask:0xf bound_ctrl:1
	v_pk_mul_f32 v[10:11], v[46:47], v[12:13] op_sel_hi:[1,0]
	v_pk_mul_f32 v[46:47], v[46:47], v[98:99] op_sel_hi:[1,0]
	v_pk_fma_f32 v[10:11], v[58:59], v[82:83], v[10:11] op_sel_hi:[1,0,1]
	v_pk_mul_f32 v[12:13], v[48:49], v[12:13] op_sel_hi:[1,0]
	v_pk_fma_f32 v[46:47], v[58:59], v[100:101], v[46:47] op_sel_hi:[1,0,1]
	s_waitcnt vmcnt(4)
	v_pk_fma_f32 v[10:11], v[200:201], v[84:85], v[10:11]
	v_pk_fma_f32 v[12:13], v[60:61], v[82:83], v[12:13] op_sel_hi:[1,0,1]
	v_pk_fma_f32 v[2:3], v[200:201], v[88:89], v[46:47]
	v_pk_mul_f32 v[46:47], v[48:49], v[98:99] op_sel_hi:[1,0]
	v_pk_fma_f32 v[12:13], v[202:203], v[86:87], v[12:13]
	v_pk_fma_f32 v[46:47], v[60:61], v[100:101], v[46:47] op_sel_hi:[1,0,1]
	ds_read_b128 v[6:9], v118 offset:14080
	global_load_dwordx4 v[220:223], v118, s[56:57]
	s_add_u32 s56, s56, s58
	s_addc_u32 s57, s57, s59
	ds_read_b128 v[34:37], v118 offset:14592
	ds_read_b128 v[50:53], v118 offset:14848
	ds_read_b128 v[66:69], v118 offset:15104
	ds_read2_b32 v[92:93], v117 offset0:96 offset1:100
	v_pk_fma_f32 v[4:5], v[202:203], v[96:97], v[46:47]
	s_waitcnt lgkmcnt(4)
	v_pk_mul_f32 v[98:99], v[8:9], v[12:13]
	v_pk_mul_f32 v[8:9], v[8:9], v[4:5]
	v_pk_fma_f32 v[98:99], v[6:7], v[10:11], v[98:99]
	v_pk_fma_f32 v[6:7], v[6:7], v[2:3], v[8:9]
	v_add_f32_e32 v8, v98, v99
	v_add_f32_e32 v6, v6, v7
	s_waitcnt lgkmcnt(0)
	v_mov_b32_e32 v102, v93
	v_add_f32_dpp v8, v8, v8 row_ror:8 row_mask:0xf bank_mask:0xf bound_ctrl:1
	v_add_f32_dpp v6, v6, v6 row_ror:8 row_mask:0xf bank_mask:0xf bound_ctrl:1
	v_pk_mul_f32 v[48:49], v[56:57], v[4:5]
	v_add_f32_dpp v8, v8, v8 row_ror:4 row_mask:0xf bank_mask:0xf bound_ctrl:1
	v_add_f32_dpp v6, v6, v6 row_ror:4 row_mask:0xf bank_mask:0xf bound_ctrl:1
	v_pk_fma_f32 v[48:49], v[54:55], v[2:3], v[48:49]
	v_add_f32_dpp v8, v8, v8 row_ror:2 row_mask:0xf bank_mask:0xf bound_ctrl:1
	v_add_f32_dpp v6, v6, v6 row_ror:2 row_mask:0xf bank_mask:0xf bound_ctrl:1
	v_add_f32_e32 v20, v22, v23
	v_add_f32_dpp v8, v8, v8 row_ror:1 row_mask:0xf bank_mask:0xf bound_ctrl:1
	v_pk_mul_f32 v[98:99], v[34:35], v[8:9] op_sel_hi:[1,0]
	v_pk_mul_f32 v[8:9], v[36:37], v[8:9] op_sel_hi:[1,0]
	v_add_f32_dpp v6, v6, v6 row_ror:1 row_mask:0xf bank_mask:0xf bound_ctrl:1
	v_pk_fma_f32 v[8:9], v[52:53], v[92:93], v[8:9] op_sel_hi:[1,0,1]
	v_pk_fma_f32 v[98:99], v[50:51], v[92:93], v[98:99] op_sel_hi:[1,0,1]
	s_waitcnt vmcnt(4)
	v_pk_fma_f32 v[92:93], v[206:207], v[12:13], v[8:9]
	v_pk_mul_f32 v[8:9], v[34:35], v[6:7] op_sel_hi:[1,0]
	v_add_f32_e32 v18, v18, v19
	v_pk_fma_f32 v[8:9], v[50:51], v[102:103], v[8:9] op_sel_hi:[1,0,1]
	ds_write2st64_b32 v111, v20, v18 offset0:240 offset1:241
	v_pk_fma_f32 v[100:101], v[204:205], v[2:3], v[8:9]
	v_pk_mul_f32 v[2:3], v[36:37], v[6:7] op_sel_hi:[1,0]
	ds_read_b128 v[38:41], v118 offset:15360
	global_load_dwordx4 v[192:195], v118, s[56:57]
	s_add_u32 s56, s56, s58
	s_addc_u32 s57, s57, s59
	ds_read_b128 v[22:25], v118 offset:15872
	ds_read_b128 v[26:29], v118 offset:16128
	ds_read_b128 v[30:33], v118 offset:16384
	ds_read2_b32 v[90:91], v117 offset0:128 offset1:132
	v_pk_fma_f32 v[2:3], v[52:53], v[102:103], v[2:3] op_sel_hi:[1,0,1]
	v_pk_fma_f32 v[98:99], v[204:205], v[10:11], v[98:99]
	v_pk_fma_f32 v[52:53], v[206:207], v[4:5], v[2:3]
	v_pk_mul_f32 v[2:3], v[68:69], v[92:93]
	v_pk_mul_f32 v[4:5], v[68:69], v[52:53]
	v_pk_fma_f32 v[2:3], v[66:67], v[98:99], v[2:3]
	v_pk_fma_f32 v[4:5], v[66:67], v[100:101], v[4:5]
	s_waitcnt lgkmcnt(4)
	v_pk_mul_f32 v[66:67], v[40:41], v[92:93]
	v_pk_mul_f32 v[40:41], v[40:41], v[52:53]
	v_pk_fma_f32 v[66:67], v[38:39], v[98:99], v[66:67]
	v_pk_fma_f32 v[38:39], v[38:39], v[100:101], v[40:41]
	v_add_f32_e32 v40, v66, v67
	v_add_f32_e32 v38, v38, v39
	s_waitcnt lgkmcnt(0)
	v_mov_b32_e32 v66, v91
	v_add_f32_dpp v40, v40, v40 row_ror:8 row_mask:0xf bank_mask:0xf bound_ctrl:1
	v_add_f32_dpp v38, v38, v38 row_ror:8 row_mask:0xf bank_mask:0xf bound_ctrl:1
	v_pk_mul_f32 v[62:63], v[44:45], v[86:87]
	v_add_f32_dpp v40, v40, v40 row_ror:4 row_mask:0xf bank_mask:0xf bound_ctrl:1
	v_add_f32_dpp v38, v38, v38 row_ror:4 row_mask:0xf bank_mask:0xf bound_ctrl:1
	v_pk_mul_f32 v[44:45], v[44:45], v[96:97]
	v_add_f32_dpp v40, v40, v40 row_ror:2 row_mask:0xf bank_mask:0xf bound_ctrl:1
	v_add_f32_dpp v38, v38, v38 row_ror:2 row_mask:0xf bank_mask:0xf bound_ctrl:1
	v_pk_fma_f32 v[62:63], v[42:43], v[84:85], v[62:63]
	v_add_f32_dpp v40, v40, v40 row_ror:1 row_mask:0xf bank_mask:0xf bound_ctrl:1
	v_add_f32_dpp v38, v38, v38 row_ror:1 row_mask:0xf bank_mask:0xf bound_ctrl:1
	v_pk_mul_f32 v[68:69], v[22:23], v[40:41] op_sel_hi:[1,0]
	v_pk_mul_f32 v[22:23], v[22:23], v[38:39] op_sel_hi:[1,0]
	v_pk_fma_f32 v[68:69], v[26:27], v[90:91], v[68:69] op_sel_hi:[1,0,1]
	v_pk_fma_f32 v[22:23], v[26:27], v[66:67], v[22:23] op_sel_hi:[1,0,1]
	s_waitcnt vmcnt(4)
	v_pk_fma_f32 v[68:69], v[208:209], v[98:99], v[68:69]
	v_pk_mul_f32 v[40:41], v[24:25], v[40:41] op_sel_hi:[1,0]
	v_pk_fma_f32 v[18:19], v[208:209], v[100:101], v[22:23]
	v_pk_mul_f32 v[22:23], v[24:25], v[38:39] op_sel_hi:[1,0]
	v_pk_fma_f32 v[42:43], v[42:43], v[88:89], v[44:45]
	v_pk_mul_f32 v[46:47], v[56:57], v[12:13]
	v_pk_fma_f32 v[40:41], v[28:29], v[90:91], v[40:41] op_sel_hi:[1,0,1]
	v_pk_fma_f32 v[22:23], v[28:29], v[66:67], v[22:23] op_sel_hi:[1,0,1]
	v_add_f32_e32 v44, v62, v63
	v_add_f32_e32 v42, v42, v43
	v_pk_fma_f32 v[46:47], v[54:55], v[10:11], v[46:47]
	v_pk_fma_f32 v[40:41], v[210:211], v[92:93], v[40:41]
	v_pk_fma_f32 v[20:21], v[210:211], v[52:53], v[22:23]
	ds_write2st64_b32 v111, v44, v42 offset0:248 offset1:249
	v_add_f32_e32 v46, v46, v47
	v_add_f32_e32 v47, v48, v49
	v_pk_mul_f32 v[22:23], v[32:33], v[40:41]
	v_pk_mul_f32 v[24:25], v[32:33], v[20:21]
	ds_read_b128 v[78:81], v118 offset:16640
	global_load_dwordx4 v[196:199], v118, s[56:57]
	s_add_u32 s56, s56, s58
	s_addc_u32 s57, s57, s59
	ds_read_b128 v[62:65], v118 offset:17152
	ds_read_b128 v[70:73], v118 offset:17408
	ds_read_b128 v[74:77], v118 offset:17664
	ds_read2_b32 v[94:95], v117 offset0:160 offset1:164
	ds_write2st64_b32 v112, v46, v47 offset0:80 offset1:81
	v_add_f32_e32 v2, v2, v3
	v_add_f32_e32 v3, v4, v5
	v_pk_fma_f32 v[22:23], v[30:31], v[68:69], v[22:23]
	v_pk_fma_f32 v[24:25], v[30:31], v[18:19], v[24:25]
	ds_read_b128 v[86:89], v118 offset:17920
	global_load_dwordx4 v[200:203], v118, s[56:57]
	s_add_u32 s56, s56, s58
	s_addc_u32 s57, s57, s59
	ds_read_b128 v[54:57], v118 offset:18432
	ds_read_b128 v[58:61], v118 offset:18688
	ds_read_b128 v[82:85], v118 offset:18944
	ds_read2_b32 v[96:97], v117 offset0:192 offset1:196
	ds_write2st64_b32 v112, v2, v3 offset0:88 offset1:89
	v_add_f32_e32 v22, v22, v23
	v_add_f32_e32 v23, v24, v25
	ds_read_b128 v[34:37], v118 offset:19200
	global_load_dwordx4 v[204:207], v118, s[56:57]
	s_add_u32 s56, s56, s58
	s_addc_u32 s57, s57, s59
	ds_read_b128 v[6:9], v118 offset:19712
	ds_read_b128 v[14:17], v118 offset:19968
	ds_read_b128 v[10:13], v118 offset:20224
	ds_read2_b32 v[50:51], v117 offset0:224 offset1:228
	ds_write2st64_b32 v112, v22, v23 offset0:96 offset1:97
	s_waitcnt lgkmcnt(12)
	v_pk_mul_f32 v[22:23], v[80:81], v[40:41]
	v_pk_mul_f32 v[24:25], v[80:81], v[20:21]
	v_pk_fma_f32 v[22:23], v[78:79], v[68:69], v[22:23]
	v_pk_fma_f32 v[24:25], v[78:79], v[18:19], v[24:25]
	v_add_f32_e32 v22, v22, v23
	v_add_f32_e32 v23, v24, v25
	v_mov_b32_e32 v26, v95
	v_add_f32_dpp v22, v22, v22 row_ror:8 row_mask:0xf bank_mask:0xf bound_ctrl:1
	v_add_f32_dpp v23, v23, v23 row_ror:8 row_mask:0xf bank_mask:0xf bound_ctrl:1
	s_waitcnt lgkmcnt(7)
	v_mov_b32_e32 v32, v97
	v_add_f32_dpp v22, v22, v22 row_ror:4 row_mask:0xf bank_mask:0xf bound_ctrl:1
	v_add_f32_dpp v23, v23, v23 row_ror:4 row_mask:0xf bank_mask:0xf bound_ctrl:1
	s_nop 0
	v_add_f32_dpp v22, v22, v22 row_ror:2 row_mask:0xf bank_mask:0xf bound_ctrl:1
	v_add_f32_dpp v23, v23, v23 row_ror:2 row_mask:0xf bank_mask:0xf bound_ctrl:1
	s_nop 0
	v_add_f32_dpp v22, v22, v22 row_ror:1 row_mask:0xf bank_mask:0xf bound_ctrl:1
	v_add_f32_dpp v24, v23, v23 row_ror:1 row_mask:0xf bank_mask:0xf bound_ctrl:1
	v_pk_mul_f32 v[28:29], v[62:63], v[22:23] op_sel_hi:[1,0]
	v_pk_mul_f32 v[22:23], v[64:65], v[22:23] op_sel_hi:[1,0]
	v_pk_mul_f32 v[30:31], v[62:63], v[24:25] op_sel_hi:[1,0]
	v_pk_mul_f32 v[24:25], v[64:65], v[24:25] op_sel_hi:[1,0]
	v_pk_fma_f32 v[22:23], v[72:73], v[94:95], v[22:23] op_sel_hi:[1,0,1]
	v_pk_fma_f32 v[24:25], v[72:73], v[26:27], v[24:25] op_sel_hi:[1,0,1]
	v_pk_fma_f32 v[28:29], v[70:71], v[94:95], v[28:29] op_sel_hi:[1,0,1]
	s_waitcnt vmcnt(6)
	v_pk_fma_f32 v[22:23], v[214:215], v[40:41], v[22:23]
	v_pk_fma_f32 v[30:31], v[70:71], v[26:27], v[30:31] op_sel_hi:[1,0,1]
	v_pk_fma_f32 v[26:27], v[214:215], v[20:21], v[24:25]
	v_pk_fma_f32 v[28:29], v[212:213], v[68:69], v[28:29]
	v_pk_fma_f32 v[18:19], v[212:213], v[18:19], v[30:31]
	v_pk_mul_f32 v[20:21], v[76:77], v[22:23]
	v_pk_mul_f32 v[24:25], v[76:77], v[26:27]
	v_pk_fma_f32 v[20:21], v[74:75], v[28:29], v[20:21]
	v_pk_fma_f32 v[24:25], v[74:75], v[18:19], v[24:25]
	v_add_f32_e32 v20, v20, v21
	v_add_f32_e32 v21, v24, v25
	ds_write2st64_b32 v112, v20, v21 offset0:104 offset1:105
	ds_read_b32 v249, v246
	v_pk_mul_f32 v[20:21], v[88:89], v[22:23]
	v_pk_mul_f32 v[24:25], v[88:89], v[26:27]
	v_pk_fma_f32 v[20:21], v[86:87], v[28:29], v[20:21]
	v_pk_fma_f32 v[24:25], v[86:87], v[18:19], v[24:25]
	v_add_f32_e32 v20, v20, v21
	v_add_f32_e32 v21, v24, v25
	s_nop 0
	v_add_f32_dpp v20, v20, v20 row_ror:8 row_mask:0xf bank_mask:0xf bound_ctrl:1
	v_add_f32_dpp v21, v21, v21 row_ror:8 row_mask:0xf bank_mask:0xf bound_ctrl:1
	s_nop 0
	v_add_f32_dpp v20, v20, v20 row_ror:4 row_mask:0xf bank_mask:0xf bound_ctrl:1
	v_add_f32_dpp v21, v21, v21 row_ror:4 row_mask:0xf bank_mask:0xf bound_ctrl:1
	s_nop 0
	v_add_f32_dpp v20, v20, v20 row_ror:2 row_mask:0xf bank_mask:0xf bound_ctrl:1
	v_add_f32_dpp v21, v21, v21 row_ror:2 row_mask:0xf bank_mask:0xf bound_ctrl:1
	s_nop 0
	v_add_f32_dpp v20, v20, v20 row_ror:1 row_mask:0xf bank_mask:0xf bound_ctrl:1
	v_add_f32_dpp v30, v21, v21 row_ror:1 row_mask:0xf bank_mask:0xf bound_ctrl:1
	v_pk_mul_f32 v[24:25], v[54:55], v[20:21] op_sel_hi:[1,0]
	v_pk_mul_f32 v[20:21], v[56:57], v[20:21] op_sel_hi:[1,0]
	v_pk_fma_f32 v[24:25], v[58:59], v[96:97], v[24:25] op_sel_hi:[1,0,1]
	v_pk_fma_f32 v[20:21], v[60:61], v[96:97], v[20:21] op_sel_hi:[1,0,1]
	s_waitcnt vmcnt(5)
	v_pk_fma_f32 v[24:25], v[216:217], v[28:29], v[24:25]
	v_pk_fma_f32 v[22:23], v[218:219], v[22:23], v[20:21]
	v_pk_mul_f32 v[20:21], v[54:55], v[30:31] op_sel_hi:[1,0]
	s_nop 0
	v_pk_fma_f32 v[20:21], v[58:59], v[32:33], v[20:21] op_sel_hi:[1,0,1]
	s_nop 0
	v_pk_fma_f32 v[20:21], v[216:217], v[18:19], v[20:21]
	v_pk_mul_f32 v[18:19], v[56:57], v[30:31] op_sel_hi:[1,0]
	s_nop 0
	v_pk_fma_f32 v[18:19], v[60:61], v[32:33], v[18:19] op_sel_hi:[1,0,1]
	s_nop 0
	v_pk_fma_f32 v[18:19], v[218:219], v[26:27], v[18:19]
	v_pk_mul_f32 v[26:27], v[84:85], v[22:23]
	v_pk_mul_f32 v[28:29], v[84:85], v[18:19]
	v_pk_fma_f32 v[26:27], v[82:83], v[24:25], v[26:27]
	v_pk_fma_f32 v[28:29], v[82:83], v[20:21], v[28:29]
	v_add_f32_e32 v26, v26, v27
	v_add_f32_e32 v27, v28, v29
	ds_write2st64_b32 v112, v26, v27 offset0:112 offset1:113
	s_waitcnt lgkmcnt(7)
	v_pk_mul_f32 v[26:27], v[36:37], v[22:23]
	v_pk_mul_f32 v[28:29], v[36:37], v[18:19]
	v_pk_fma_f32 v[26:27], v[34:35], v[24:25], v[26:27]
	v_pk_fma_f32 v[30:31], v[34:35], v[20:21], v[28:29]
	v_add_f32_e32 v26, v26, v27
	s_nop 1
	v_add_f32_dpp v26, v26, v26 row_ror:8 row_mask:0xf bank_mask:0xf bound_ctrl:1
	s_nop 1
	v_add_f32_dpp v26, v26, v26 row_ror:4 row_mask:0xf bank_mask:0xf bound_ctrl:1
	s_nop 1
	v_add_f32_dpp v26, v26, v26 row_ror:2 row_mask:0xf bank_mask:0xf bound_ctrl:1
	s_nop 1
	v_add_f32_dpp v28, v26, v26 row_ror:1 row_mask:0xf bank_mask:0xf bound_ctrl:1
	v_add_f32_e32 v26, v30, v31
	s_waitcnt lgkmcnt(3)
	v_mov_b32_e32 v30, v51
	v_pk_mul_f32 v[32:33], v[6:7], v[28:29] op_sel_hi:[1,0]
	v_add_f32_dpp v26, v26, v26 row_ror:8 row_mask:0xf bank_mask:0xf bound_ctrl:1
	v_pk_fma_f32 v[32:33], v[14:15], v[50:51], v[32:33] op_sel_hi:[1,0,1]
	s_nop 0
	v_add_f32_dpp v26, v26, v26 row_ror:4 row_mask:0xf bank_mask:0xf bound_ctrl:1
	s_waitcnt vmcnt(4)
	v_pk_fma_f32 v[76:77], v[220:221], v[24:25], v[32:33]
	v_pk_mul_f32 v[24:25], v[8:9], v[28:29] op_sel_hi:[1,0]
	v_add_f32_dpp v26, v26, v26 row_ror:2 row_mask:0xf bank_mask:0xf bound_ctrl:1
	v_pk_fma_f32 v[24:25], v[16:17], v[50:51], v[24:25] op_sel_hi:[1,0,1]
	s_nop 0
	v_add_f32_dpp v26, v26, v26 row_ror:1 row_mask:0xf bank_mask:0xf bound_ctrl:1
	v_pk_mul_f32 v[6:7], v[6:7], v[26:27] op_sel_hi:[1,0]
	v_pk_fma_f32 v[78:79], v[222:223], v[22:23], v[24:25]
	v_pk_fma_f32 v[6:7], v[14:15], v[30:31], v[6:7] op_sel_hi:[1,0,1]
	s_nop 0
	v_pk_fma_f32 v[80:81], v[220:221], v[20:21], v[6:7]
	v_pk_mul_f32 v[2:3], v[8:9], v[26:27] op_sel_hi:[1,0]
	s_nop 0
	v_pk_fma_f32 v[2:3], v[16:17], v[30:31], v[2:3] op_sel_hi:[1,0,1]
	s_nop 0
	v_pk_fma_f32 v[92:93], v[222:223], v[18:19], v[2:3]
	v_pk_mul_f32 v[2:3], v[12:13], v[78:79]
	v_pk_mul_f32 v[4:5], v[12:13], v[92:93]
	v_pk_fma_f32 v[2:3], v[10:11], v[76:77], v[2:3]
	v_pk_fma_f32 v[4:5], v[10:11], v[80:81], v[4:5]
	v_add_f32_e32 v2, v2, v3
	v_add_f32_e32 v3, v4, v5
	ds_write2st64_b32 v112, v2, v3 offset0:120 offset1:121
	s_add_i32 s64, s4, 3
	v_mov_b32_e32 v248, s64
	ds_write_b32 v247, v248
	s_waitcnt lgkmcnt(3)
	v_cmp_gt_u32_e32 vcc, s64, v249
	s_nop 0
	s_cbranch_vccnz .Lsflag_slow_3
.Lsflag_go_3:
	ds_read_b128 v[10:13], v118 offset:20480
	global_load_dwordx4 v[208:211], v118, s[56:57]
	s_add_u32 s56, s56, s58
	s_addc_u32 s57, s57, s59
	ds_read_b128 v[22:25], v118 offset:20992
	ds_read_b128 v[26:29], v118 offset:21248
	ds_read_b128 v[46:49], v118 offset:21504
	ds_read2_b32 v[94:95], v120 offset1:4
	ds_read_b128 v[50:53], v118 offset:21760
	global_load_dwordx4 v[212:215], v118, s[56:57]
	s_add_u32 s56, s56, s58
	s_addc_u32 s57, s57, s59
	ds_read_b128 v[72:75], v118 offset:22272
	ds_read_b128 v[82:85], v118 offset:22528
	ds_read_b128 v[86:89], v118 offset:22784
	ds_read2_b32 v[96:97], v120 offset0:32 offset1:36
	ds_read_b128 v[62:65], v118 offset:23040
	global_load_dwordx4 v[216:219], v118, s[56:57]
	s_add_u32 s56, s56, s58
	s_addc_u32 s57, s57, s59
	ds_read_b128 v[54:57], v118 offset:23552
	ds_read_b128 v[58:61], v118 offset:23808
	ds_read_b128 v[14:17], v118 offset:24064
	ds_read2_b32 v[66:67], v120 offset0:64 offset1:68
	ds_read_b128 v[42:45], v118 offset:24320
	global_load_dwordx4 v[220:223], v118, s[56:57]
	s_add_u32 s56, s56, s58
	s_addc_u32 s57, s57, s59
	ds_read_b128 v[30:33], v118 offset:24832
	ds_read_b128 v[34:37], v118 offset:25088
	ds_read_b128 v[2:5], v118 offset:25344
	ds_read2_b32 v[90:91], v120 offset0:96 offset1:100
	s_waitcnt lgkmcnt(12)
	v_pk_mul_f32 v[98:99], v[12:13], v[78:79]
	v_pk_mul_f32 v[12:13], v[12:13], v[92:93]
	v_pk_fma_f32 v[98:99], v[10:11], v[76:77], v[98:99]
	v_pk_fma_f32 v[10:11], v[10:11], v[80:81], v[12:13]
	v_add_f32_e32 v12, v98, v99
	v_add_f32_e32 v10, v10, v11
	v_mov_b32_e32 v98, v95
	v_add_f32_dpp v12, v12, v12 row_ror:8 row_mask:0xf bank_mask:0xf bound_ctrl:1
	v_add_f32_dpp v10, v10, v10 row_ror:8 row_mask:0xf bank_mask:0xf bound_ctrl:1
	s_nop 0
	v_add_f32_dpp v12, v12, v12 row_ror:4 row_mask:0xf bank_mask:0xf bound_ctrl:1
	v_add_f32_dpp v10, v10, v10 row_ror:4 row_mask:0xf bank_mask:0xf bound_ctrl:1
	s_nop 0
	v_add_f32_dpp v12, v12, v12 row_ror:2 row_mask:0xf bank_mask:0xf bound_ctrl:1
	v_add_f32_dpp v10, v10, v10 row_ror:2 row_mask:0xf bank_mask:0xf bound_ctrl:1
	s_nop 0
	v_add_f32_dpp v12, v12, v12 row_ror:1 row_mask:0xf bank_mask:0xf bound_ctrl:1
	v_pk_mul_f32 v[100:101], v[22:23], v[12:13] op_sel_hi:[1,0]
	v_pk_mul_f32 v[12:13], v[24:25], v[12:13] op_sel_hi:[1,0]
	v_add_f32_dpp v10, v10, v10 row_ror:1 row_mask:0xf bank_mask:0xf bound_ctrl:1
	v_pk_fma_f32 v[100:101], v[26:27], v[94:95], v[100:101] op_sel_hi:[1,0,1]
	v_pk_fma_f32 v[12:13], v[28:29], v[94:95], v[12:13] op_sel_hi:[1,0,1]
	s_waitcnt vmcnt(7)
	v_pk_fma_f32 v[76:77], v[192:193], v[76:77], v[100:101]
	v_pk_fma_f32 v[100:101], v[194:195], v[78:79], v[12:13]
	v_pk_mul_f32 v[12:13], v[22:23], v[10:11] op_sel_hi:[1,0]
	v_pk_mul_f32 v[10:11], v[24:25], v[10:11] op_sel_hi:[1,0]
	v_pk_fma_f32 v[12:13], v[26:27], v[98:99], v[12:13] op_sel_hi:[1,0,1]
	v_pk_fma_f32 v[10:11], v[28:29], v[98:99], v[10:11] op_sel_hi:[1,0,1]
	v_pk_fma_f32 v[102:103], v[192:193], v[80:81], v[12:13]
	v_pk_fma_f32 v[92:93], v[194:195], v[92:93], v[10:11]
	v_pk_mul_f32 v[10:11], v[48:49], v[100:101]
	v_pk_mul_f32 v[12:13], v[48:49], v[92:93]
	v_pk_fma_f32 v[10:11], v[46:47], v[76:77], v[10:11]
	v_pk_fma_f32 v[12:13], v[46:47], v[102:103], v[12:13]
	v_pk_mul_f32 v[46:47], v[52:53], v[100:101]
	v_pk_mul_f32 v[48:49], v[52:53], v[92:93]
	v_pk_fma_f32 v[46:47], v[50:51], v[76:77], v[46:47]
	v_pk_fma_f32 v[48:49], v[50:51], v[102:103], v[48:49]
	v_add_f32_e32 v46, v46, v47
	v_add_f32_e32 v47, v48, v49
	s_waitcnt lgkmcnt(10)
	v_mov_b32_e32 v50, v97
	v_add_f32_dpp v46, v46, v46 row_ror:8 row_mask:0xf bank_mask:0xf bound_ctrl:1
	v_add_f32_dpp v47, v47, v47 row_ror:8 row_mask:0xf bank_mask:0xf bound_ctrl:1
	v_add_f32_e32 v10, v10, v11
	v_add_f32_dpp v46, v46, v46 row_ror:4 row_mask:0xf bank_mask:0xf bound_ctrl:1
	v_add_f32_dpp v47, v47, v47 row_ror:4 row_mask:0xf bank_mask:0xf bound_ctrl:1
	v_add_f32_e32 v11, v12, v13
	v_add_f32_dpp v46, v46, v46 row_ror:2 row_mask:0xf bank_mask:0xf bound_ctrl:1
	v_add_f32_dpp v47, v47, v47 row_ror:2 row_mask:0xf bank_mask:0xf bound_ctrl:1
	ds_write2st64_b32 v113, v10, v11 offset1:1
	v_add_f32_dpp v46, v46, v46 row_ror:1 row_mask:0xf bank_mask:0xf bound_ctrl:1
	v_add_f32_dpp v48, v47, v47 row_ror:1 row_mask:0xf bank_mask:0xf bound_ctrl:1
	v_pk_mul_f32 v[52:53], v[72:73], v[46:47] op_sel_hi:[1,0]
	v_pk_mul_f32 v[46:47], v[74:75], v[46:47] op_sel_hi:[1,0]
	v_pk_fma_f32 v[52:53], v[82:83], v[96:97], v[52:53] op_sel_hi:[1,0,1]
	v_pk_fma_f32 v[46:47], v[84:85], v[96:97], v[46:47] op_sel_hi:[1,0,1]
	s_waitcnt vmcnt(6)
	v_pk_fma_f32 v[98:99], v[196:197], v[76:77], v[52:53]
	v_pk_fma_f32 v[100:101], v[198:199], v[100:101], v[46:47]
	v_pk_mul_f32 v[46:47], v[72:73], v[48:49] op_sel_hi:[1,0]
	ds_read_b128 v[78:81], v118 offset:25600
	global_load_dwordx4 v[192:195], v118, s[56:57]
	s_add_u32 s56, s56, s58
	s_addc_u32 s57, s57, s59
	ds_read_b128 v[22:25], v118 offset:26112
	ds_read_b128 v[26:29], v118 offset:26368
	ds_read_b128 v[10:13], v118 offset:26624
	ds_read2_b32 v[94:95], v120 offset0:128 offset1:132
	v_pk_fma_f32 v[46:47], v[82:83], v[50:51], v[46:47] op_sel_hi:[1,0,1]
	s_nop 0
	v_pk_fma_f32 v[68:69], v[196:197], v[102:103], v[46:47]
	v_pk_mul_f32 v[46:47], v[74:75], v[48:49] op_sel_hi:[1,0]
	s_nop 0
	v_pk_fma_f32 v[46:47], v[84:85], v[50:51], v[46:47] op_sel_hi:[1,0,1]
	s_waitcnt lgkmcnt(12)
	v_pk_mul_f32 v[84:85], v[64:65], v[100:101]
	v_pk_fma_f32 v[82:83], v[198:199], v[92:93], v[46:47]
	v_pk_fma_f32 v[84:85], v[62:63], v[98:99], v[84:85]
	v_pk_mul_f32 v[64:65], v[64:65], v[82:83]
	v_pk_mul_f32 v[46:47], v[88:89], v[100:101]
	v_pk_fma_f32 v[62:63], v[62:63], v[68:69], v[64:65]
	v_add_f32_e32 v64, v84, v85
	v_add_f32_e32 v62, v62, v63
	s_waitcnt lgkmcnt(11)
	v_mov_b32_e32 v84, v67
	v_add_f32_dpp v64, v64, v64 row_ror:8 row_mask:0xf bank_mask:0xf bound_ctrl:1
	v_add_f32_dpp v62, v62, v62 row_ror:8 row_mask:0xf bank_mask:0xf bound_ctrl:1
	v_pk_mul_f32 v[48:49], v[88:89], v[82:83]
	v_add_f32_dpp v64, v64, v64 row_ror:4 row_mask:0xf bank_mask:0xf bound_ctrl:1
	v_add_f32_dpp v62, v62, v62 row_ror:4 row_mask:0xf bank_mask:0xf bound_ctrl:1
	v_pk_fma_f32 v[46:47], v[86:87], v[98:99], v[46:47]
	v_add_f32_dpp v64, v64, v64 row_ror:2 row_mask:0xf bank_mask:0xf bound_ctrl:1
	v_add_f32_dpp v62, v62, v62 row_ror:2 row_mask:0xf bank_mask:0xf bound_ctrl:1
	v_pk_fma_f32 v[48:49], v[86:87], v[68:69], v[48:49]
	v_add_f32_dpp v64, v64, v64 row_ror:1 row_mask:0xf bank_mask:0xf bound_ctrl:1
	v_add_f32_dpp v62, v62, v62 row_ror:1 row_mask:0xf bank_mask:0xf bound_ctrl:1
	v_pk_mul_f32 v[92:93], v[54:55], v[64:65] op_sel_hi:[1,0]
	v_pk_mul_f32 v[54:55], v[54:55], v[62:63] op_sel_hi:[1,0]
	v_pk_fma_f32 v[92:93], v[58:59], v[66:67], v[92:93] op_sel_hi:[1,0,1]
	v_pk_fma_f32 v[54:55], v[58:59], v[84:85], v[54:55] op_sel_hi:[1,0,1]
	s_waitcnt vmcnt(6)
	v_pk_fma_f32 v[92:93], v[200:201], v[98:99], v[92:93]
	v_pk_mul_f32 v[64:65], v[56:57], v[64:65] op_sel_hi:[1,0]
	v_pk_fma_f32 v[58:59], v[200:201], v[68:69], v[54:55]
	v_pk_mul_f32 v[38:39], v[56:57], v[62:63] op_sel_hi:[1,0]
	v_pk_fma_f32 v[64:65], v[60:61], v[66:67], v[64:65] op_sel_hi:[1,0,1]
	v_pk_fma_f32 v[38:39], v[60:61], v[84:85], v[38:39] op_sel_hi:[1,0,1]
	v_pk_fma_f32 v[64:65], v[202:203], v[100:101], v[64:65]
	v_pk_fma_f32 v[60:61], v[202:203], v[82:83], v[38:39]
	s_waitcnt lgkmcnt(10)
	v_pk_mul_f32 v[62:63], v[44:45], v[64:65]
	v_pk_mul_f32 v[44:45], v[44:45], v[60:61]
	v_pk_fma_f32 v[62:63], v[42:43], v[92:93], v[62:63]
	v_pk_fma_f32 v[42:43], v[42:43], v[58:59], v[44:45]
	v_add_f32_e32 v44, v62, v63
	v_add_f32_e32 v42, v42, v43
	s_waitcnt lgkmcnt(6)
	v_mov_b32_e32 v62, v91
	v_add_f32_dpp v44, v44, v44 row_ror:8 row_mask:0xf bank_mask:0xf bound_ctrl:1
	v_add_f32_dpp v42, v42, v42 row_ror:8 row_mask:0xf bank_mask:0xf bound_ctrl:1
	v_pk_mul_f32 v[38:39], v[16:17], v[64:65]
	v_add_f32_dpp v44, v44, v44 row_ror:4 row_mask:0xf bank_mask:0xf bound_ctrl:1
	v_add_f32_dpp v42, v42, v42 row_ror:4 row_mask:0xf bank_mask:0xf bound_ctrl:1
	v_pk_mul_f32 v[16:17], v[16:17], v[60:61]
	v_add_f32_dpp v44, v44, v44 row_ror:2 row_mask:0xf bank_mask:0xf bound_ctrl:1
	v_add_f32_dpp v42, v42, v42 row_ror:2 row_mask:0xf bank_mask:0xf bound_ctrl:1
	v_add_f32_e32 v46, v46, v47
	v_add_f32_dpp v44, v44, v44 row_ror:1 row_mask:0xf bank_mask:0xf bound_ctrl:1
	v_add_f32_dpp v42, v42, v42 row_ror:1 row_mask:0xf bank_mask:0xf bound_ctrl:1
	v_pk_mul_f32 v[100:101], v[30:31], v[44:45] op_sel_hi:[1,0]
	v_pk_mul_f32 v[30:31], v[30:31], v[42:43] op_sel_hi:[1,0]
	v_pk_fma_f32 v[100:101], v[34:35], v[90:91], v[100:101] op_sel_hi:[1,0,1]
	v_pk_fma_f32 v[30:31], v[34:35], v[62:63], v[30:31] op_sel_hi:[1,0,1]
	s_waitcnt vmcnt(5)
	v_pk_fma_f32 v[100:101], v[204:205], v[92:93], v[100:101]
	v_pk_mul_f32 v[44:45], v[32:33], v[44:45] op_sel_hi:[1,0]
	v_pk_fma_f32 v[30:31], v[204:205], v[58:59], v[30:31]
	v_pk_mul_f32 v[6:7], v[32:33], v[42:43] op_sel_hi:[1,0]
	v_pk_fma_f32 v[44:45], v[36:37], v[90:91], v[44:45] op_sel_hi:[1,0,1]
	v_pk_fma_f32 v[6:7], v[36:37], v[62:63], v[6:7] op_sel_hi:[1,0,1]
	v_pk_fma_f32 v[90:91], v[206:207], v[64:65], v[44:45]
	v_pk_fma_f32 v[32:33], v[206:207], v[60:61], v[6:7]
	s_waitcnt lgkmcnt(4)
	v_pk_mul_f32 v[34:35], v[80:81], v[90:91]
	v_pk_mul_f32 v[36:37], v[80:81], v[32:33]
	v_pk_fma_f32 v[34:35], v[78:79], v[100:101], v[34:35]
	v_pk_fma_f32 v[36:37], v[78:79], v[30:31], v[36:37]
	v_add_f32_e32 v34, v34, v35
	v_add_f32_e32 v35, v36, v37
	s_waitcnt lgkmcnt(0)
	v_mov_b32_e32 v78, v95
	v_add_f32_dpp v34, v34, v34 row_ror:8 row_mask:0xf bank_mask:0xf bound_ctrl:1
	v_add_f32_dpp v35, v35, v35 row_ror:8 row_mask:0xf bank_mask:0xf bound_ctrl:1
	v_pk_mul_f32 v[6:7], v[4:5], v[90:91]
	v_add_f32_dpp v34, v34, v34 row_ror:4 row_mask:0xf bank_mask:0xf bound_ctrl:1
	v_add_f32_dpp v35, v35, v35 row_ror:4 row_mask:0xf bank_mask:0xf bound_ctrl:1
	v_pk_fma_f32 v[6:7], v[2:3], v[100:101], v[6:7]
	v_add_f32_dpp v34, v34, v34 row_ror:2 row_mask:0xf bank_mask:0xf bound_ctrl:1
	v_add_f32_dpp v35, v35, v35 row_ror:2 row_mask:0xf bank_mask:0xf bound_ctrl:1
	v_add_f32_e32 v47, v48, v49
	v_add_f32_dpp v34, v34, v34 row_ror:1 row_mask:0xf bank_mask:0xf bound_ctrl:1
	v_add_f32_dpp v36, v35, v35 row_ror:1 row_mask:0xf bank_mask:0xf bound_ctrl:1
	v_pk_mul_f32 v[80:81], v[22:23], v[34:35] op_sel_hi:[1,0]
	v_pk_mul_f32 v[22:23], v[22:23], v[36:37] op_sel_hi:[1,0]
	v_pk_fma_f32 v[80:81], v[26:27], v[94:95], v[80:81] op_sel_hi:[1,0,1]
	v_pk_fma_f32 v[22:23], v[26:27], v[78:79], v[22:23] op_sel_hi:[1,0,1]
	s_waitcnt vmcnt(4)
	v_pk_fma_f32 v[80:81], v[208:209], v[100:101], v[80:81]
	v_pk_mul_f32 v[34:35], v[24:25], v[34:35] op_sel_hi:[1,0]
	v_pk_fma_f32 v[100:101], v[208:209], v[30:31], v[22:23]
	v_pk_mul_f32 v[18:19], v[24:25], v[36:37] op_sel_hi:[1,0]
	v_pk_fma_f32 v[34:35], v[28:29], v[94:95], v[34:35] op_sel_hi:[1,0,1]
	v_pk_fma_f32 v[18:19], v[28:29], v[78:79], v[18:19] op_sel_hi:[1,0,1]
	v_pk_fma_f32 v[38:39], v[14:15], v[92:93], v[38:39]
	v_pk_fma_f32 v[14:15], v[14:15], v[58:59], v[16:17]
	v_pk_mul_f32 v[4:5], v[4:5], v[32:33]
	v_pk_fma_f32 v[94:95], v[210:211], v[90:91], v[34:35]
	v_pk_fma_f32 v[78:79], v[210:211], v[32:33], v[18:19]
	ds_write2st64_b32 v113, v46, v47 offset0:8 offset1:9
	v_add_f32_e32 v16, v38, v39
	v_add_f32_e32 v14, v14, v15
	v_pk_fma_f32 v[2:3], v[2:3], v[30:31], v[4:5]
	v_pk_mul_f32 v[18:19], v[12:13], v[94:95]
	v_pk_mul_f32 v[12:13], v[12:13], v[78:79]
	ds_read_b128 v[86:89], v118 offset:26880
	global_load_dwordx4 v[196:199], v118, s[56:57]
	s_add_u32 s56, s56, s58
	s_addc_u32 s57, s57, s59
	ds_read_b128 v[70:73], v118 offset:27392
	ds_read_b128 v[74:77], v118 offset:27648
	ds_read_b128 v[46:49], v118 offset:27904
	ds_read2_b32 v[96:97], v120 offset0:160 offset1:164
	ds_write2st64_b32 v113, v16, v14 offset0:16 offset1:17
	v_add_f32_e32 v4, v6, v7
	v_add_f32_e32 v2, v2, v3
	v_pk_fma_f32 v[18:19], v[10:11], v[80:81], v[18:19]
	v_pk_fma_f32 v[10:11], v[10:11], v[100:101], v[12:13]
	ds_read_b128 v[82:85], v118 offset:28160
	global_load_dwordx4 v[200:203], v118, s[56:57]
	s_add_u32 s56, s56, s58
	s_addc_u32 s57, s57, s59
	ds_read_b128 v[54:57], v118 offset:28672
	ds_read_b128 v[66:69], v118 offset:28928
	ds_read_b128 v[14:17], v118 offset:29184
	ds_read2_b32 v[98:99], v120 offset0:192 offset1:196
	ds_write2st64_b32 v113, v4, v2 offset0:24 offset1:25
	v_add_f32_e32 v12, v18, v19
	v_add_f32_e32 v10, v10, v11
	ds_read_b128 v[62:65], v118 offset:29440
	global_load_dwordx4 v[204:207], v118, s[56:57]
	s_add_u32 s56, s56, s58
	s_addc_u32 s57, s57, s59
	ds_read_b128 v[42:45], v118 offset:29952
	ds_read_b128 v[58:61], v118 offset:30208
	ds_read_b128 v[2:5], v118 offset:30464
	ds_read2_b32 v[92:93], v120 offset0:224 offset1:228
	ds_write2st64_b32 v113, v12, v10 offset0:32 offset1:33
	s_waitcnt lgkmcnt(12)
	v_pk_mul_f32 v[10:11], v[88:89], v[94:95]
	v_pk_mul_f32 v[12:13], v[88:89], v[78:79]
	v_pk_fma_f32 v[10:11], v[86:87], v[80:81], v[10:11]
	v_pk_fma_f32 v[12:13], v[86:87], v[100:101], v[12:13]
	v_add_f32_e32 v10, v10, v11
	v_add_f32_e32 v11, v12, v13
	v_mov_b32_e32 v86, v97
	v_add_f32_dpp v10, v10, v10 row_ror:8 row_mask:0xf bank_mask:0xf bound_ctrl:1
	v_add_f32_dpp v11, v11, v11 row_ror:8 row_mask:0xf bank_mask:0xf bound_ctrl:1
	ds_read_b128 v[34:37], v118 offset:30720
	global_load_dwordx4 v[208:211], v118, s[56:57]
	s_add_u32 s56, s56, s58
	s_addc_u32 s57, s57, s59
	ds_read_b128 v[26:29], v118 offset:31232
	ds_read_b128 v[30:33], v118 offset:31488
	ds_read_b128 v[18:21], v118 offset:31744
	ds_read2_b32 v[90:91], v114 offset1:4
	v_add_f32_dpp v10, v10, v10 row_ror:4 row_mask:0xf bank_mask:0xf bound_ctrl:1
	v_add_f32_dpp v11, v11, v11 row_ror:4 row_mask:0xf bank_mask:0xf bound_ctrl:1
	s_nop 0
	v_add_f32_dpp v10, v10, v10 row_ror:2 row_mask:0xf bank_mask:0xf bound_ctrl:1
	v_add_f32_dpp v11, v11, v11 row_ror:2 row_mask:0xf bank_mask:0xf bound_ctrl:1
	s_nop 0
	v_add_f32_dpp v10, v10, v10 row_ror:1 row_mask:0xf bank_mask:0xf bound_ctrl:1
	v_add_f32_dpp v12, v11, v11 row_ror:1 row_mask:0xf bank_mask:0xf bound_ctrl:1
	v_pk_mul_f32 v[88:89], v[70:71], v[10:11] op_sel_hi:[1,0]
	v_pk_mul_f32 v[10:11], v[72:73], v[10:11] op_sel_hi:[1,0]
	v_pk_mul_f32 v[70:71], v[70:71], v[12:13] op_sel_hi:[1,0]
	v_pk_fma_f32 v[10:11], v[76:77], v[96:97], v[10:11] op_sel_hi:[1,0,1]
	v_pk_mul_f32 v[12:13], v[72:73], v[12:13] op_sel_hi:[1,0]
	v_pk_fma_f32 v[88:89], v[74:75], v[96:97], v[88:89] op_sel_hi:[1,0,1]
	s_waitcnt vmcnt(7)
	v_pk_fma_f32 v[10:11], v[214:215], v[94:95], v[10:11]
	v_pk_fma_f32 v[12:13], v[76:77], v[86:87], v[12:13] op_sel_hi:[1,0,1]
	v_pk_fma_f32 v[88:89], v[212:213], v[80:81], v[88:89]
	v_pk_fma_f32 v[70:71], v[74:75], v[86:87], v[70:71] op_sel_hi:[1,0,1]
	v_pk_fma_f32 v[12:13], v[214:215], v[78:79], v[12:13]
	s_waitcnt lgkmcnt(12)
	v_pk_mul_f32 v[96:97], v[84:85], v[10:11]
	v_pk_fma_f32 v[94:95], v[212:213], v[100:101], v[70:71]
	v_pk_fma_f32 v[96:97], v[82:83], v[88:89], v[96:97]
	v_pk_mul_f32 v[84:85], v[84:85], v[12:13]
	v_pk_mul_f32 v[50:51], v[48:49], v[10:11]
	v_pk_fma_f32 v[82:83], v[82:83], v[94:95], v[84:85]
	v_add_f32_e32 v84, v96, v97
	v_add_f32_e32 v82, v82, v83
	v_mov_b32_e32 v96, v99
	v_add_f32_dpp v84, v84, v84 row_ror:8 row_mask:0xf bank_mask:0xf bound_ctrl:1
	v_add_f32_dpp v82, v82, v82 row_ror:8 row_mask:0xf bank_mask:0xf bound_ctrl:1
	v_pk_mul_f32 v[48:49], v[48:49], v[12:13]
	v_add_f32_dpp v84, v84, v84 row_ror:4 row_mask:0xf bank_mask:0xf bound_ctrl:1
	v_add_f32_dpp v82, v82, v82 row_ror:4 row_mask:0xf bank_mask:0xf bound_ctrl:1
	v_pk_fma_f32 v[50:51], v[46:47], v[88:89], v[50:51]
	v_add_f32_dpp v84, v84, v84 row_ror:2 row_mask:0xf bank_mask:0xf bound_ctrl:1
	v_add_f32_dpp v82, v82, v82 row_ror:2 row_mask:0xf bank_mask:0xf bound_ctrl:1
	v_pk_fma_f32 v[46:47], v[46:47], v[94:95], v[48:49]
	v_add_f32_dpp v84, v84, v84 row_ror:1 row_mask:0xf bank_mask:0xf bound_ctrl:1
	v_pk_mul_f32 v[100:101], v[54:55], v[84:85] op_sel_hi:[1,0]
	v_pk_mul_f32 v[84:85], v[56:57], v[84:85] op_sel_hi:[1,0]
	v_add_f32_dpp v82, v82, v82 row_ror:1 row_mask:0xf bank_mask:0xf bound_ctrl:1
	v_pk_fma_f32 v[84:85], v[68:69], v[98:99], v[84:85] op_sel_hi:[1,0,1]
	v_pk_fma_f32 v[100:101], v[66:67], v[98:99], v[100:101] op_sel_hi:[1,0,1]
	s_waitcnt vmcnt(6)
	v_pk_fma_f32 v[98:99], v[218:219], v[10:11], v[84:85]
	v_pk_mul_f32 v[10:11], v[54:55], v[82:83] op_sel_hi:[1,0]
	v_pk_fma_f32 v[88:89], v[216:217], v[88:89], v[100:101]
	v_pk_fma_f32 v[10:11], v[66:67], v[96:97], v[10:11] op_sel_hi:[1,0,1]
	s_waitcnt lgkmcnt(10)
	v_pk_mul_f32 v[84:85], v[64:65], v[98:99]
	v_pk_fma_f32 v[94:95], v[216:217], v[94:95], v[10:11]
	v_pk_mul_f32 v[10:11], v[56:57], v[82:83] op_sel_hi:[1,0]
	v_pk_fma_f32 v[84:85], v[62:63], v[88:89], v[84:85]
	v_pk_fma_f32 v[10:11], v[68:69], v[96:97], v[10:11] op_sel_hi:[1,0,1]
	s_waitcnt lgkmcnt(6)
	v_mov_b32_e32 v100, v93
	v_pk_fma_f32 v[96:97], v[218:219], v[12:13], v[10:11]
	v_pk_mul_f32 v[10:11], v[16:17], v[98:99]
	v_pk_mul_f32 v[64:65], v[64:65], v[96:97]
	v_pk_mul_f32 v[12:13], v[16:17], v[96:97]
	v_pk_fma_f32 v[62:63], v[62:63], v[94:95], v[64:65]
	v_add_f32_e32 v64, v84, v85
	v_add_f32_e32 v62, v62, v63
	v_pk_fma_f32 v[12:13], v[14:15], v[94:95], v[12:13]
	v_add_f32_dpp v64, v64, v64 row_ror:8 row_mask:0xf bank_mask:0xf bound_ctrl:1
	v_add_f32_dpp v62, v62, v62 row_ror:8 row_mask:0xf bank_mask:0xf bound_ctrl:1
	v_pk_fma_f32 v[10:11], v[14:15], v[88:89], v[10:11]
	v_add_f32_dpp v64, v64, v64 row_ror:4 row_mask:0xf bank_mask:0xf bound_ctrl:1
	v_add_f32_dpp v62, v62, v62 row_ror:4 row_mask:0xf bank_mask:0xf bound_ctrl:1
	v_add_f32_e32 v48, v50, v51
	v_add_f32_dpp v64, v64, v64 row_ror:2 row_mask:0xf bank_mask:0xf bound_ctrl:1
	v_add_f32_dpp v62, v62, v62 row_ror:2 row_mask:0xf bank_mask:0xf bound_ctrl:1
	v_add_f32_e32 v46, v46, v47
	v_add_f32_dpp v64, v64, v64 row_ror:1 row_mask:0xf bank_mask:0xf bound_ctrl:1
	v_add_f32_dpp v62, v62, v62 row_ror:1 row_mask:0xf bank_mask:0xf bound_ctrl:1
	v_pk_mul_f32 v[84:85], v[42:43], v[64:65] op_sel_hi:[1,0]
	v_pk_mul_f32 v[42:43], v[42:43], v[62:63] op_sel_hi:[1,0]
	v_pk_fma_f32 v[84:85], v[58:59], v[92:93], v[84:85] op_sel_hi:[1,0,1]
	v_pk_fma_f32 v[42:43], v[58:59], v[100:101], v[42:43] op_sel_hi:[1,0,1]
	s_waitcnt vmcnt(5)
	v_pk_fma_f32 v[84:85], v[220:221], v[88:89], v[84:85]
	v_pk_mul_f32 v[64:65], v[44:45], v[64:65] op_sel_hi:[1,0]
	v_pk_fma_f32 v[94:95], v[220:221], v[94:95], v[42:43]
	v_pk_mul_f32 v[6:7], v[44:45], v[62:63] op_sel_hi:[1,0]
	v_pk_fma_f32 v[64:65], v[60:61], v[92:93], v[64:65] op_sel_hi:[1,0,1]
	v_pk_fma_f32 v[6:7], v[60:61], v[100:101], v[6:7] op_sel_hi:[1,0,1]
	v_pk_fma_f32 v[88:89], v[222:223], v[98:99], v[64:65]
	v_pk_fma_f32 v[96:97], v[222:223], v[96:97], v[6:7]
	s_waitcnt lgkmcnt(4)
	v_pk_mul_f32 v[98:99], v[36:37], v[88:89]
	v_pk_mul_f32 v[36:37], v[36:37], v[96:97]
	v_pk_fma_f32 v[98:99], v[34:35], v[84:85], v[98:99]
	v_pk_fma_f32 v[34:35], v[34:35], v[94:95], v[36:37]
	v_add_f32_e32 v36, v98, v99
	v_add_f32_e32 v34, v34, v35
	s_waitcnt lgkmcnt(0)
	v_mov_b32_e32 v98, v91
	v_add_f32_dpp v36, v36, v36 row_ror:8 row_mask:0xf bank_mask:0xf bound_ctrl:1
	v_add_f32_dpp v34, v34, v34 row_ror:8 row_mask:0xf bank_mask:0xf bound_ctrl:1
	v_pk_mul_f32 v[6:7], v[4:5], v[88:89]
	v_add_f32_dpp v36, v36, v36 row_ror:4 row_mask:0xf bank_mask:0xf bound_ctrl:1
	v_add_f32_dpp v34, v34, v34 row_ror:4 row_mask:0xf bank_mask:0xf bound_ctrl:1
	v_pk_mul_f32 v[4:5], v[4:5], v[96:97]
	v_add_f32_dpp v36, v36, v36 row_ror:2 row_mask:0xf bank_mask:0xf bound_ctrl:1
	v_add_f32_dpp v34, v34, v34 row_ror:2 row_mask:0xf bank_mask:0xf bound_ctrl:1
	v_pk_fma_f32 v[6:7], v[2:3], v[84:85], v[6:7]
	v_add_f32_dpp v36, v36, v36 row_ror:1 row_mask:0xf bank_mask:0xf bound_ctrl:1
	v_add_f32_dpp v34, v34, v34 row_ror:1 row_mask:0xf bank_mask:0xf bound_ctrl:1
	v_pk_mul_f32 v[100:101], v[26:27], v[36:37] op_sel_hi:[1,0]
	v_pk_mul_f32 v[26:27], v[26:27], v[34:35] op_sel_hi:[1,0]
	v_pk_fma_f32 v[100:101], v[30:31], v[90:91], v[100:101] op_sel_hi:[1,0,1]
	v_pk_fma_f32 v[26:27], v[30:31], v[98:99], v[26:27] op_sel_hi:[1,0,1]
	v_pk_fma_f32 v[2:3], v[2:3], v[94:95], v[4:5]
	s_waitcnt vmcnt(4)
	v_pk_fma_f32 v[84:85], v[192:193], v[84:85], v[100:101]
	v_pk_mul_f32 v[36:37], v[28:29], v[36:37] op_sel_hi:[1,0]
	v_pk_fma_f32 v[94:95], v[192:193], v[94:95], v[26:27]
	v_pk_mul_f32 v[22:23], v[28:29], v[34:35] op_sel_hi:[1,0]
	ds_write2st64_b32 v113, v48, v46 offset0:40 offset1:41
	v_pk_fma_f32 v[36:37], v[32:33], v[90:91], v[36:37] op_sel_hi:[1,0,1]
	v_pk_fma_f32 v[22:23], v[32:33], v[98:99], v[22:23] op_sel_hi:[1,0,1]
	ds_read_b128 v[78:81], v118 offset:32000
	global_load_dwordx4 v[212:215], v118, s[56:57]
	s_add_u32 s56, s56, s58
	s_addc_u32 s57, s57, s59
	ds_read_b128 v[70:73], v118 offset:32512
	ds_read_b128 v[74:77], v118 offset:32768
	ds_read_b128 v[46:49], v118 offset:33024
	ds_read2_b32 v[86:87], v114 offset0:32 offset1:36
	v_pk_fma_f32 v[88:89], v[194:195], v[88:89], v[36:37]
	v_pk_fma_f32 v[96:97], v[194:195], v[96:97], v[22:23]
	s_waitcnt lgkmcnt(4)
	v_pk_mul_f32 v[98:99], v[80:81], v[88:89]
	v_pk_mul_f32 v[80:81], v[80:81], v[96:97]
	v_pk_fma_f32 v[98:99], v[78:79], v[84:85], v[98:99]
	v_pk_fma_f32 v[78:79], v[78:79], v[94:95], v[80:81]
	v_add_f32_e32 v80, v98, v99
	v_add_f32_e32 v78, v78, v79
	s_waitcnt lgkmcnt(0)
	v_mov_b32_e32 v98, v87
	v_add_f32_dpp v80, v80, v80 row_ror:8 row_mask:0xf bank_mask:0xf bound_ctrl:1
	v_add_f32_dpp v78, v78, v78 row_ror:8 row_mask:0xf bank_mask:0xf bound_ctrl:1
	v_pk_mul_f32 v[22:23], v[20:21], v[88:89]
	v_add_f32_dpp v80, v80, v80 row_ror:4 row_mask:0xf bank_mask:0xf bound_ctrl:1
	v_add_f32_dpp v78, v78, v78 row_ror:4 row_mask:0xf bank_mask:0xf bound_ctrl:1
	v_add_f32_e32 v10, v10, v11
	v_add_f32_dpp v80, v80, v80 row_ror:2 row_mask:0xf bank_mask:0xf bound_ctrl:1
	v_add_f32_dpp v78, v78, v78 row_ror:2 row_mask:0xf bank_mask:0xf bound_ctrl:1
	v_add_f32_e32 v11, v12, v13
	v_add_f32_dpp v80, v80, v80 row_ror:1 row_mask:0xf bank_mask:0xf bound_ctrl:1
	v_add_f32_dpp v78, v78, v78 row_ror:1 row_mask:0xf bank_mask:0xf bound_ctrl:1
	v_pk_mul_f32 v[100:101], v[70:71], v[80:81] op_sel_hi:[1,0]
	v_pk_mul_f32 v[80:81], v[72:73], v[80:81] op_sel_hi:[1,0]
	v_pk_mul_f32 v[70:71], v[70:71], v[78:79] op_sel_hi:[1,0]
	v_pk_fma_f32 v[100:101], v[74:75], v[86:87], v[100:101] op_sel_hi:[1,0,1]
	v_pk_fma_f32 v[80:81], v[76:77], v[86:87], v[80:81] op_sel_hi:[1,0,1]
	v_pk_fma_f32 v[70:71], v[74:75], v[98:99], v[70:71] op_sel_hi:[1,0,1]
	v_pk_fma_f32 v[22:23], v[18:19], v[84:85], v[22:23]
	s_waitcnt vmcnt(4)
	v_pk_fma_f32 v[84:85], v[196:197], v[84:85], v[100:101]
	v_pk_fma_f32 v[86:87], v[198:199], v[88:89], v[80:81]
	v_pk_fma_f32 v[88:89], v[196:197], v[94:95], v[70:71]
	v_pk_mul_f32 v[50:51], v[72:73], v[78:79] op_sel_hi:[1,0]
	ds_write2st64_b32 v113, v10, v11 offset0:48 offset1:49
	v_pk_fma_f32 v[50:51], v[76:77], v[98:99], v[50:51] op_sel_hi:[1,0,1]
	ds_read_b128 v[14:17], v118 offset:33280
	global_load_dwordx4 v[216:219], v118, s[56:57]
	s_add_u32 s56, s56, s58
	s_addc_u32 s57, s57, s59
	ds_read_b128 v[38:41], v118 offset:33792
	ds_read_b128 v[54:57], v118 offset:34048
	ds_read_b128 v[66:69], v118 offset:34304
	ds_read2_b32 v[82:83], v114 offset0:64 offset1:68
	v_pk_mul_f32 v[20:21], v[20:21], v[96:97]
	v_pk_fma_f32 v[96:97], v[198:199], v[96:97], v[50:51]
	s_waitcnt lgkmcnt(4)
	v_pk_mul_f32 v[98:99], v[16:17], v[86:87]
	v_pk_mul_f32 v[16:17], v[16:17], v[96:97]
	v_pk_fma_f32 v[98:99], v[14:15], v[84:85], v[98:99]
	v_pk_fma_f32 v[14:15], v[14:15], v[88:89], v[16:17]
	v_add_f32_e32 v16, v98, v99
	v_add_f32_e32 v14, v14, v15
	s_waitcnt lgkmcnt(0)
	v_mov_b32_e32 v100, v83
	v_add_f32_dpp v16, v16, v16 row_ror:8 row_mask:0xf bank_mask:0xf bound_ctrl:1
	v_add_f32_dpp v14, v14, v14 row_ror:8 row_mask:0xf bank_mask:0xf bound_ctrl:1
	v_add_f32_e32 v4, v6, v7
	v_add_f32_dpp v16, v16, v16 row_ror:4 row_mask:0xf bank_mask:0xf bound_ctrl:1
	v_add_f32_dpp v14, v14, v14 row_ror:4 row_mask:0xf bank_mask:0xf bound_ctrl:1
	v_add_f32_e32 v2, v2, v3
	v_add_f32_dpp v16, v16, v16 row_ror:2 row_mask:0xf bank_mask:0xf bound_ctrl:1
	v_add_f32_dpp v14, v14, v14 row_ror:2 row_mask:0xf bank_mask:0xf bound_ctrl:1
	ds_write2st64_b32 v113, v4, v2 offset0:56 offset1:57
	v_add_f32_dpp v16, v16, v16 row_ror:1 row_mask:0xf bank_mask:0xf bound_ctrl:1
	v_add_f32_dpp v98, v14, v14 row_ror:1 row_mask:0xf bank_mask:0xf bound_ctrl:1
	v_pk_mul_f32 v[14:15], v[38:39], v[16:17] op_sel_hi:[1,0]
	v_pk_mul_f32 v[38:39], v[38:39], v[98:99] op_sel_hi:[1,0]
	v_pk_fma_f32 v[14:15], v[54:55], v[82:83], v[14:15] op_sel_hi:[1,0,1]
	v_pk_mul_f32 v[16:17], v[40:41], v[16:17] op_sel_hi:[1,0]
	v_pk_fma_f32 v[38:39], v[54:55], v[100:101], v[38:39] op_sel_hi:[1,0,1]
	s_waitcnt vmcnt(4)
	v_pk_fma_f32 v[14:15], v[200:201], v[84:85], v[14:15]
	v_pk_fma_f32 v[16:17], v[56:57], v[82:83], v[16:17] op_sel_hi:[1,0,1]
	v_pk_fma_f32 v[10:11], v[200:201], v[88:89], v[38:39]
	v_pk_mul_f32 v[38:39], v[40:41], v[98:99] op_sel_hi:[1,0]
	v_pk_fma_f32 v[16:17], v[202:203], v[86:87], v[16:17]
	v_pk_fma_f32 v[38:39], v[56:57], v[100:101], v[38:39] op_sel_hi:[1,0,1]
	ds_read_b128 v[6:9], v118 offset:34560
	global_load_dwordx4 v[220:223], v118, s[56:57]
	s_add_u32 s56, s56, s58
	s_addc_u32 s57, s57, s59
	ds_read_b128 v[42:45], v118 offset:35072
	ds_read_b128 v[58:61], v118 offset:35328
	ds_read_b128 v[62:65], v118 offset:35584
	ds_read2_b32 v[92:93], v114 offset0:96 offset1:100
	v_pk_fma_f32 v[12:13], v[202:203], v[96:97], v[38:39]
	s_waitcnt lgkmcnt(4)
	v_pk_mul_f32 v[98:99], v[8:9], v[16:17]
	v_pk_mul_f32 v[8:9], v[8:9], v[12:13]
	v_pk_fma_f32 v[98:99], v[6:7], v[14:15], v[98:99]
	v_pk_fma_f32 v[6:7], v[6:7], v[10:11], v[8:9]
	v_add_f32_e32 v8, v98, v99
	v_add_f32_e32 v6, v6, v7
	s_waitcnt lgkmcnt(0)
	v_mov_b32_e32 v102, v93
	v_add_f32_dpp v8, v8, v8 row_ror:8 row_mask:0xf bank_mask:0xf bound_ctrl:1
	v_add_f32_dpp v6, v6, v6 row_ror:8 row_mask:0xf bank_mask:0xf bound_ctrl:1
	v_pk_fma_f32 v[18:19], v[18:19], v[94:95], v[20:21]
	v_add_f32_dpp v8, v8, v8 row_ror:4 row_mask:0xf bank_mask:0xf bound_ctrl:1
	v_add_f32_dpp v6, v6, v6 row_ror:4 row_mask:0xf bank_mask:0xf bound_ctrl:1
	v_add_f32_e32 v20, v22, v23
	v_add_f32_dpp v8, v8, v8 row_ror:2 row_mask:0xf bank_mask:0xf bound_ctrl:1
	v_add_f32_dpp v6, v6, v6 row_ror:2 row_mask:0xf bank_mask:0xf bound_ctrl:1
	v_add_f32_e32 v18, v18, v19
	v_add_f32_dpp v8, v8, v8 row_ror:1 row_mask:0xf bank_mask:0xf bound_ctrl:1
	v_pk_mul_f32 v[98:99], v[42:43], v[8:9] op_sel_hi:[1,0]
	v_pk_mul_f32 v[8:9], v[44:45], v[8:9] op_sel_hi:[1,0]
	v_add_f32_dpp v6, v6, v6 row_ror:1 row_mask:0xf bank_mask:0xf bound_ctrl:1
	v_pk_fma_f32 v[8:9], v[60:61], v[92:93], v[8:9] op_sel_hi:[1,0,1]
	v_pk_fma_f32 v[98:99], v[58:59], v[92:93], v[98:99] op_sel_hi:[1,0,1]
	s_waitcnt vmcnt(4)
	v_pk_fma_f32 v[92:93], v[206:207], v[16:17], v[8:9]
	v_pk_mul_f32 v[8:9], v[42:43], v[6:7] op_sel_hi:[1,0]
	v_pk_fma_f32 v[98:99], v[204:205], v[14:15], v[98:99]
	v_pk_fma_f32 v[8:9], v[58:59], v[102:103], v[8:9] op_sel_hi:[1,0,1]
	ds_write2st64_b32 v113, v20, v18 offset0:64 offset1:65
	v_pk_fma_f32 v[100:101], v[204:205], v[10:11], v[8:9]
	v_pk_mul_f32 v[2:3], v[44:45], v[6:7] op_sel_hi:[1,0]
	ds_read_b128 v[34:37], v118 offset:35840
	global_load_dwordx4 v[192:195], v118, s[56:57]
	s_add_u32 s56, s56, s58
	s_addc_u32 s57, s57, s59
	ds_read_b128 v[22:25], v118 offset:36352
	ds_read_b128 v[26:29], v118 offset:36608
	ds_read_b128 v[30:33], v118 offset:36864
	ds_read2_b32 v[90:91], v114 offset0:128 offset1:132
	v_pk_fma_f32 v[2:3], v[60:61], v[102:103], v[2:3] op_sel_hi:[1,0,1]
	v_pk_mul_f32 v[50:51], v[48:49], v[86:87]
	v_pk_fma_f32 v[60:61], v[206:207], v[12:13], v[2:3]
	v_pk_mul_f32 v[2:3], v[64:65], v[92:93]
	v_pk_mul_f32 v[4:5], v[64:65], v[60:61]
	v_pk_fma_f32 v[2:3], v[62:63], v[98:99], v[2:3]
	v_pk_fma_f32 v[4:5], v[62:63], v[100:101], v[4:5]
	s_waitcnt lgkmcnt(4)
	v_pk_mul_f32 v[62:63], v[36:37], v[92:93]
	v_pk_mul_f32 v[36:37], v[36:37], v[60:61]
	v_pk_fma_f32 v[62:63], v[34:35], v[98:99], v[62:63]
	v_pk_fma_f32 v[34:35], v[34:35], v[100:101], v[36:37]
	v_add_f32_e32 v36, v62, v63
	v_add_f32_e32 v34, v34, v35
	s_waitcnt lgkmcnt(0)
	v_mov_b32_e32 v62, v91
	v_add_f32_dpp v36, v36, v36 row_ror:8 row_mask:0xf bank_mask:0xf bound_ctrl:1
	v_add_f32_dpp v34, v34, v34 row_ror:8 row_mask:0xf bank_mask:0xf bound_ctrl:1
	v_pk_mul_f32 v[48:49], v[48:49], v[96:97]
	v_add_f32_dpp v36, v36, v36 row_ror:4 row_mask:0xf bank_mask:0xf bound_ctrl:1
	v_add_f32_dpp v34, v34, v34 row_ror:4 row_mask:0xf bank_mask:0xf bound_ctrl:1
	v_pk_fma_f32 v[50:51], v[46:47], v[84:85], v[50:51]
	v_add_f32_dpp v36, v36, v36 row_ror:2 row_mask:0xf bank_mask:0xf bound_ctrl:1
	v_add_f32_dpp v34, v34, v34 row_ror:2 row_mask:0xf bank_mask:0xf bound_ctrl:1
	v_pk_fma_f32 v[46:47], v[46:47], v[88:89], v[48:49]
	v_add_f32_dpp v36, v36, v36 row_ror:1 row_mask:0xf bank_mask:0xf bound_ctrl:1
	v_add_f32_dpp v34, v34, v34 row_ror:1 row_mask:0xf bank_mask:0xf bound_ctrl:1
	v_pk_mul_f32 v[64:65], v[22:23], v[36:37] op_sel_hi:[1,0]
	v_pk_mul_f32 v[22:23], v[22:23], v[34:35] op_sel_hi:[1,0]
	v_pk_fma_f32 v[64:65], v[26:27], v[90:91], v[64:65] op_sel_hi:[1,0,1]
	v_pk_fma_f32 v[22:23], v[26:27], v[62:63], v[22:23] op_sel_hi:[1,0,1]
	s_waitcnt vmcnt(4)
	v_pk_fma_f32 v[64:65], v[208:209], v[98:99], v[64:65]
	v_pk_mul_f32 v[36:37], v[24:25], v[36:37] op_sel_hi:[1,0]
	v_pk_fma_f32 v[18:19], v[208:209], v[100:101], v[22:23]
	v_pk_mul_f32 v[22:23], v[24:25], v[34:35] op_sel_hi:[1,0]
	v_pk_mul_f32 v[38:39], v[68:69], v[16:17]
	v_pk_mul_f32 v[40:41], v[68:69], v[12:13]
	v_pk_fma_f32 v[36:37], v[28:29], v[90:91], v[36:37] op_sel_hi:[1,0,1]
	v_pk_fma_f32 v[22:23], v[28:29], v[62:63], v[22:23] op_sel_hi:[1,0,1]
	v_add_f32_e32 v48, v50, v51
	v_add_f32_e32 v46, v46, v47
	v_pk_fma_f32 v[38:39], v[66:67], v[14:15], v[38:39]
	v_pk_fma_f32 v[40:41], v[66:67], v[10:11], v[40:41]
	v_pk_fma_f32 v[36:37], v[210:211], v[92:93], v[36:37]
	v_pk_fma_f32 v[20:21], v[210:211], v[60:61], v[22:23]
	ds_write2st64_b32 v113, v48, v46 offset0:72 offset1:73
	v_add_f32_e32 v38, v38, v39
	v_add_f32_e32 v39, v40, v41
	v_pk_mul_f32 v[22:23], v[32:33], v[36:37]
	v_pk_mul_f32 v[24:25], v[32:33], v[20:21]
	ds_read_b128 v[78:81], v118 offset:37120
	global_load_dwordx4 v[196:199], v118, s[56:57]
	s_add_u32 s56, s56, s58
	s_addc_u32 s57, s57, s59
	ds_read_b128 v[50:53], v118 offset:37632
	ds_read_b128 v[70:73], v118 offset:37888
	ds_read_b128 v[74:77], v118 offset:38144
	ds_read2_b32 v[94:95], v114 offset0:160 offset1:164
	ds_write2st64_b32 v113, v38, v39 offset0:80 offset1:81
	v_add_f32_e32 v2, v2, v3
	v_add_f32_e32 v3, v4, v5
	v_pk_fma_f32 v[22:23], v[30:31], v[64:65], v[22:23]
	v_pk_fma_f32 v[24:25], v[30:31], v[18:19], v[24:25]
	ds_read_b128 v[86:89], v118 offset:38400
	global_load_dwordx4 v[200:203], v118, s[56:57]
	s_add_u32 s56, s56, s58
	s_addc_u32 s57, s57, s59
	ds_read_b128 v[54:57], v118 offset:38912
	ds_read_b128 v[66:69], v118 offset:39168
	ds_read_b128 v[82:85], v118 offset:39424
	ds_read2_b32 v[96:97], v114 offset0:192 offset1:196
	ds_write2st64_b32 v113, v2, v3 offset0:88 offset1:89
	v_add_f32_e32 v22, v22, v23
	v_add_f32_e32 v23, v24, v25
	ds_read_b128 v[42:45], v118 offset:39680
	global_load_dwordx4 v[204:207], v118, s[56:57]
	s_add_u32 s56, s56, s58
	s_addc_u32 s57, s57, s59
	ds_read_b128 v[10:13], v118 offset:40192
	ds_read_b128 v[6:9], v118 offset:40448
	ds_read_b128 v[14:17], v118 offset:40704
	ds_read2_b32 v[58:59], v114 offset0:224 offset1:228
	ds_write2st64_b32 v113, v22, v23 offset0:96 offset1:97
	s_waitcnt lgkmcnt(12)
	v_pk_mul_f32 v[22:23], v[80:81], v[36:37]
	v_pk_mul_f32 v[24:25], v[80:81], v[20:21]
	v_pk_fma_f32 v[22:23], v[78:79], v[64:65], v[22:23]
	v_pk_fma_f32 v[24:25], v[78:79], v[18:19], v[24:25]
	v_add_f32_e32 v22, v22, v23
	v_add_f32_e32 v23, v24, v25
	v_mov_b32_e32 v26, v95
	v_add_f32_dpp v22, v22, v22 row_ror:8 row_mask:0xf bank_mask:0xf bound_ctrl:1
	v_add_f32_dpp v23, v23, v23 row_ror:8 row_mask:0xf bank_mask:0xf bound_ctrl:1
	s_waitcnt lgkmcnt(7)
	v_mov_b32_e32 v32, v97
	v_add_f32_dpp v22, v22, v22 row_ror:4 row_mask:0xf bank_mask:0xf bound_ctrl:1
	v_add_f32_dpp v23, v23, v23 row_ror:4 row_mask:0xf bank_mask:0xf bound_ctrl:1
	s_nop 0
	v_add_f32_dpp v22, v22, v22 row_ror:2 row_mask:0xf bank_mask:0xf bound_ctrl:1
	v_add_f32_dpp v23, v23, v23 row_ror:2 row_mask:0xf bank_mask:0xf bound_ctrl:1
	s_nop 0
	v_add_f32_dpp v22, v22, v22 row_ror:1 row_mask:0xf bank_mask:0xf bound_ctrl:1
	v_add_f32_dpp v24, v23, v23 row_ror:1 row_mask:0xf bank_mask:0xf bound_ctrl:1
	v_pk_mul_f32 v[28:29], v[50:51], v[22:23] op_sel_hi:[1,0]
	v_pk_mul_f32 v[22:23], v[52:53], v[22:23] op_sel_hi:[1,0]
	v_pk_mul_f32 v[30:31], v[50:51], v[24:25] op_sel_hi:[1,0]
	v_pk_mul_f32 v[24:25], v[52:53], v[24:25] op_sel_hi:[1,0]
	v_pk_fma_f32 v[22:23], v[72:73], v[94:95], v[22:23] op_sel_hi:[1,0,1]
	v_pk_fma_f32 v[24:25], v[72:73], v[26:27], v[24:25] op_sel_hi:[1,0,1]
	v_pk_fma_f32 v[28:29], v[70:71], v[94:95], v[28:29] op_sel_hi:[1,0,1]
	s_waitcnt vmcnt(6)
	v_pk_fma_f32 v[22:23], v[214:215], v[36:37], v[22:23]
	v_pk_fma_f32 v[30:31], v[70:71], v[26:27], v[30:31] op_sel_hi:[1,0,1]
	v_pk_fma_f32 v[26:27], v[214:215], v[20:21], v[24:25]
	v_pk_fma_f32 v[28:29], v[212:213], v[64:65], v[28:29]
	v_pk_fma_f32 v[18:19], v[212:213], v[18:19], v[30:31]
	v_pk_mul_f32 v[20:21], v[76:77], v[22:23]
	v_pk_mul_f32 v[24:25], v[76:77], v[26:27]
	v_pk_fma_f32 v[20:21], v[74:75], v[28:29], v[20:21]
	v_pk_fma_f32 v[24:25], v[74:75], v[18:19], v[24:25]
	v_add_f32_e32 v20, v20, v21
	v_add_f32_e32 v21, v24, v25
	ds_write2st64_b32 v113, v20, v21 offset0:104 offset1:105
	ds_read_b32 v249, v246
	v_pk_mul_f32 v[20:21], v[88:89], v[22:23]
	v_pk_mul_f32 v[24:25], v[88:89], v[26:27]
	v_pk_fma_f32 v[20:21], v[86:87], v[28:29], v[20:21]
	v_pk_fma_f32 v[24:25], v[86:87], v[18:19], v[24:25]
	v_add_f32_e32 v20, v20, v21
	v_add_f32_e32 v21, v24, v25
	s_nop 0
	v_add_f32_dpp v20, v20, v20 row_ror:8 row_mask:0xf bank_mask:0xf bound_ctrl:1
	v_add_f32_dpp v21, v21, v21 row_ror:8 row_mask:0xf bank_mask:0xf bound_ctrl:1
	s_nop 0
	v_add_f32_dpp v20, v20, v20 row_ror:4 row_mask:0xf bank_mask:0xf bound_ctrl:1
	v_add_f32_dpp v21, v21, v21 row_ror:4 row_mask:0xf bank_mask:0xf bound_ctrl:1
	s_nop 0
	v_add_f32_dpp v20, v20, v20 row_ror:2 row_mask:0xf bank_mask:0xf bound_ctrl:1
	v_add_f32_dpp v21, v21, v21 row_ror:2 row_mask:0xf bank_mask:0xf bound_ctrl:1
	s_nop 0
	v_add_f32_dpp v20, v20, v20 row_ror:1 row_mask:0xf bank_mask:0xf bound_ctrl:1
	v_add_f32_dpp v30, v21, v21 row_ror:1 row_mask:0xf bank_mask:0xf bound_ctrl:1
	v_pk_mul_f32 v[24:25], v[54:55], v[20:21] op_sel_hi:[1,0]
	v_pk_mul_f32 v[20:21], v[56:57], v[20:21] op_sel_hi:[1,0]
	v_pk_fma_f32 v[24:25], v[66:67], v[96:97], v[24:25] op_sel_hi:[1,0,1]
	v_pk_fma_f32 v[20:21], v[68:69], v[96:97], v[20:21] op_sel_hi:[1,0,1]
	s_waitcnt vmcnt(5)
	v_pk_fma_f32 v[24:25], v[216:217], v[28:29], v[24:25]
	v_pk_fma_f32 v[22:23], v[218:219], v[22:23], v[20:21]
	v_pk_mul_f32 v[20:21], v[54:55], v[30:31] op_sel_hi:[1,0]
	s_nop 0
	v_pk_fma_f32 v[20:21], v[66:67], v[32:33], v[20:21] op_sel_hi:[1,0,1]
	s_nop 0
	v_pk_fma_f32 v[20:21], v[216:217], v[18:19], v[20:21]
	v_pk_mul_f32 v[18:19], v[56:57], v[30:31] op_sel_hi:[1,0]
	s_nop 0
	v_pk_fma_f32 v[18:19], v[68:69], v[32:33], v[18:19] op_sel_hi:[1,0,1]
	s_nop 0
	v_pk_fma_f32 v[18:19], v[218:219], v[26:27], v[18:19]
	v_pk_mul_f32 v[26:27], v[84:85], v[22:23]
	v_pk_mul_f32 v[28:29], v[84:85], v[18:19]
	v_pk_fma_f32 v[26:27], v[82:83], v[24:25], v[26:27]
	v_pk_fma_f32 v[28:29], v[82:83], v[20:21], v[28:29]
	v_add_f32_e32 v26, v26, v27
	v_add_f32_e32 v27, v28, v29
	ds_write2st64_b32 v113, v26, v27 offset0:112 offset1:113
	s_waitcnt lgkmcnt(7)
	v_pk_mul_f32 v[26:27], v[44:45], v[22:23]
	v_pk_mul_f32 v[28:29], v[44:45], v[18:19]
	v_pk_fma_f32 v[26:27], v[42:43], v[24:25], v[26:27]
	v_pk_fma_f32 v[30:31], v[42:43], v[20:21], v[28:29]
	v_add_f32_e32 v26, v26, v27
	s_nop 1
	v_add_f32_dpp v26, v26, v26 row_ror:8 row_mask:0xf bank_mask:0xf bound_ctrl:1
	s_nop 1
	v_add_f32_dpp v26, v26, v26 row_ror:4 row_mask:0xf bank_mask:0xf bound_ctrl:1
	s_nop 1
	v_add_f32_dpp v26, v26, v26 row_ror:2 row_mask:0xf bank_mask:0xf bound_ctrl:1
	s_nop 1
	v_add_f32_dpp v28, v26, v26 row_ror:1 row_mask:0xf bank_mask:0xf bound_ctrl:1
	v_add_f32_e32 v26, v30, v31
	s_waitcnt lgkmcnt(3)
	v_mov_b32_e32 v30, v59
	v_pk_mul_f32 v[32:33], v[10:11], v[28:29] op_sel_hi:[1,0]
	v_add_f32_dpp v26, v26, v26 row_ror:8 row_mask:0xf bank_mask:0xf bound_ctrl:1
	v_pk_fma_f32 v[32:33], v[6:7], v[58:59], v[32:33] op_sel_hi:[1,0,1]
	v_pk_mul_f32 v[28:29], v[12:13], v[28:29] op_sel_hi:[1,0]
	v_add_f32_dpp v26, v26, v26 row_ror:4 row_mask:0xf bank_mask:0xf bound_ctrl:1
	s_waitcnt vmcnt(4)
	v_pk_fma_f32 v[24:25], v[220:221], v[24:25], v[32:33]
	v_pk_fma_f32 v[28:29], v[8:9], v[58:59], v[28:29] op_sel_hi:[1,0,1]
	v_add_f32_dpp v26, v26, v26 row_ror:2 row_mask:0xf bank_mask:0xf bound_ctrl:1
	v_pk_fma_f32 v[22:23], v[222:223], v[22:23], v[28:29]
	s_nop 0
	v_add_f32_dpp v26, v26, v26 row_ror:1 row_mask:0xf bank_mask:0xf bound_ctrl:1
	v_pk_mul_f32 v[10:11], v[10:11], v[26:27] op_sel_hi:[1,0]
	s_nop 0
	v_pk_fma_f32 v[6:7], v[6:7], v[30:31], v[10:11] op_sel_hi:[1,0,1]
	s_nop 0
	v_pk_fma_f32 v[6:7], v[220:221], v[20:21], v[6:7]
	v_pk_mul_f32 v[2:3], v[12:13], v[26:27] op_sel_hi:[1,0]
	s_nop 0
	v_pk_fma_f32 v[2:3], v[8:9], v[30:31], v[2:3] op_sel_hi:[1,0,1]
	s_nop 0
	v_pk_fma_f32 v[8:9], v[222:223], v[18:19], v[2:3]
	v_pk_mul_f32 v[2:3], v[16:17], v[22:23]
	v_pk_mul_f32 v[4:5], v[16:17], v[8:9]
	v_pk_fma_f32 v[2:3], v[14:15], v[24:25], v[2:3]
	v_pk_fma_f32 v[4:5], v[14:15], v[6:7], v[4:5]
	v_add_f32_e32 v2, v2, v3
	v_add_f32_e32 v3, v4, v5
	ds_write2st64_b32 v113, v2, v3 offset0:120 offset1:121
	s_add_i32 s64, s4, 4
	v_mov_b32_e32 v248, s64
	ds_write_b32 v247, v248
	s_waitcnt lgkmcnt(3)
	v_cmp_gt_u32_e32 vcc, s64, v249
	s_nop 0
	s_cbranch_vccnz .Lsflag_slow_4
.Lsflag_go_4:
	s_cmpk_gt_u32 s4, 0x1fb
	s_cbranch_scc0 .LBB0_833
	s_branch .LBB0_834
.Lsflag_slow_1:
	s_sleep 1
	ds_read_b32 v249, v246
	s_waitcnt lgkmcnt(0)
	v_cmp_gt_u32_e32 vcc, s64, v249
	s_nop 0
	s_cbranch_vccnz .Lsflag_slow_1
	s_branch .Lsflag_go_1
